# EpiResNorm residual-stream loads requested 4 row groups ahead into dead A-fragment registers, counted vmcnt waits (plus tile-transition barrier change)
# speedup vs baseline: 1.0090x; 1.0026x over previous
.LBB0_389:
	v_lshl_add_u32 v150, s48, 8, v131
	v_ashrrev_i32_e32 v151, 31, v150
	v_lshl_or_b32 v148, s0, 8, v153
	v_lshlrev_b64 v[160:161], 11, v[150:151]
	v_ashrrev_i32_e32 v149, 31, v148
	v_lshl_add_u64 v[160:161], s[14:15], 0, v[160:161]
	v_lshl_add_u64 v[164:165], v[148:149], 1, v[160:161]
	v_mov_b32_e32 v232, v164
	v_mov_b32_e32 v233, v165
	global_load_dwordx4 v[188:191], v[232:233], off
	global_load_dwordx4 v[192:195], v[232:233], off offset:256
	s_mov_b64 s[100:101], 0x8000
	v_lshl_add_u64 v[230:231], v[232:233], 0, s[100:101]
	global_load_dwordx4 v[196:199], v[230:231], off
	global_load_dwordx4 v[200:203], v[230:231], off offset:256
	s_mov_b64 s[100:101], 0x10000
	v_lshl_add_u64 v[230:231], v[232:233], 0, s[100:101]
	global_load_dwordx4 v[204:207], v[230:231], off
	global_load_dwordx4 v[208:211], v[230:231], off offset:256
	s_mov_b64 s[100:101], 0x18000
	v_lshl_add_u64 v[230:231], v[232:233], 0, s[100:101]
	global_load_dwordx4 v[212:215], v[230:231], off
	global_load_dwordx4 v[216:219], v[230:231], off offset:256
	v_and_b32_e32 v170, 64, v158
	v_add_u32_e32 v170, 64, v170
	v_xor_b32_e32 v171, 32, v158
	s_lshl_b32 s48, s0, 2
	s_ashr_i32 s49, s48, 31
	s_waitcnt vmcnt(7)
	v_lshlrev_b32_e32 v159, 16, v188
	v_and_b32_e32 v160, 0xffff0000, v188
	v_lshlrev_b32_e32 v166, 16, v189
	v_and_b32_e32 v161, 0xffff0000, v189
	v_lshlrev_b32_e32 v167, 16, v190
	v_and_b32_e32 v162, 0xffff0000, v190
	v_lshlrev_b32_e32 v168, 16, v191
	v_and_b32_e32 v163, 0xffff0000, v191
	v_add_f32_e32 v159, v124, v159
	v_add_f32_e32 v169, v125, v160
	v_add_f32_e32 v126, v126, v166
	v_add_f32_e32 v127, v127, v161
	v_add_f32_e32 v166, v120, v167
	v_add_f32_e32 v121, v121, v162
	v_add_f32_e32 v167, v122, v168
	v_add_f32_e32 v168, v123, v163
	v_cvt_pk_bf16_f32 v122, v159, v169
	v_cvt_pk_bf16_f32 v123, v126, v127
	v_cvt_pk_bf16_f32 v124, v166, v121
	v_cvt_pk_bf16_f32 v125, v167, v168
	v_mul_f32_e32 v169, v169, v169
	v_mul_f32_e32 v127, v127, v127
	v_mul_f32_e32 v121, v121, v121
	v_mul_f32_e32 v168, v168, v168
	v_fmac_f32_e32 v169, v159, v159
	v_fmac_f32_e32 v127, v126, v126
	v_fmac_f32_e32 v121, v166, v166
	v_fmac_f32_e32 v168, v167, v167
	v_add_f32_e32 v126, v169, v127
	v_add_f32_e32 v121, v121, v168
	v_add_f32_e32 v121, v126, v121
	v_xor_b32_e32 v120, 16, v158
	v_cmp_lt_i32_e32 vcc, v120, v170
	global_store_dwordx4 v[164:165], v[122:125], off
	s_waitcnt vmcnt(7)
	v_lshlrev_b32_e32 v126, 16, v192
	v_and_b32_e32 v127, 0xffff0000, v192
	v_lshlrev_b32_e32 v159, 16, v193
	v_and_b32_e32 v160, 0xffff0000, v193
	v_lshlrev_b32_e32 v161, 16, v194
	v_and_b32_e32 v162, 0xffff0000, v194
	v_lshlrev_b32_e32 v166, 16, v195
	v_and_b32_e32 v163, 0xffff0000, v195
	v_add_f32_e32 v117, v117, v127
	v_add_f32_e32 v119, v119, v160
	v_add_f32_e32 v127, v113, v162
	v_add_f32_e32 v115, v115, v163
	v_add_f32_e32 v116, v116, v126
	v_add_f32_e32 v118, v118, v159
	v_add_f32_e32 v126, v112, v161
	v_add_f32_e32 v159, v114, v166
	v_mul_f32_e32 v112, v117, v117
	v_mul_f32_e32 v113, v119, v119
	v_mul_f32_e32 v114, v127, v127
	v_mul_f32_e32 v160, v115, v115
	v_fmac_f32_e32 v112, v116, v116
	v_fmac_f32_e32 v113, v118, v118
	v_fmac_f32_e32 v114, v126, v126
	v_fmac_f32_e32 v160, v159, v159
	v_add_f32_e32 v112, v112, v113
	v_add_f32_e32 v113, v114, v160
	v_cndmask_b32_e32 v120, v158, v120, vcc
	v_add_f32_e32 v112, v112, v113
	v_lshlrev_b32_e32 v120, 2, v120
	v_add_f32_e32 v112, v121, v112
	ds_bpermute_b32 v113, v120, v112
	v_cmp_lt_i32_e32 vcc, v171, v170
	v_cvt_pk_bf16_f32 v116, v116, v117
	v_cvt_pk_bf16_f32 v117, v118, v119
	v_cvt_pk_bf16_f32 v118, v126, v127
	s_waitcnt lgkmcnt(0)
	v_add_f32_e32 v112, v112, v113
	v_cvt_pk_bf16_f32 v119, v159, v115
	v_cndmask_b32_e32 v114, v158, v171, vcc
	v_lshlrev_b32_e32 v114, 2, v114
	ds_bpermute_b32 v113, v114, v112
	global_store_dwordx4 v[164:165], v[116:119], off offset:256
	s_and_saveexec_b64 s[50:51], s[4:5]
	s_cbranch_execz .LBB0_391
	v_lshlrev_b64 v[116:117], 6, v[150:151]
	v_lshl_add_u64 v[116:117], s[18:19], 0, v[116:117]
	v_lshl_add_u64 v[116:117], s[48:49], 2, v[116:117]
	s_lshl_b32 s0, s64, 2
	v_lshl_add_u64 v[116:117], v[116:117], 0, s[0:1]
	s_waitcnt lgkmcnt(0)
	v_add_f32_e32 v112, v112, v113
	global_store_dword v[116:117], v112, off
.LBB0_391:
	s_or_b64 exec, exec, s[50:51]
	v_or_b32_e32 v112, 16, v150
	s_waitcnt lgkmcnt(0)
	v_ashrrev_i32_e32 v113, 31, v112
	v_lshlrev_b64 v[116:117], 11, v[112:113]
	v_lshl_add_u64 v[116:117], s[14:15], 0, v[116:117]
	v_lshl_add_u64 v[122:123], v[148:149], 1, v[116:117]
	s_mov_b64 s[100:101], 0x40000
	v_lshl_add_u64 v[230:231], v[232:233], 0, s[100:101]
	global_load_dwordx4 v[188:191], v[230:231], off
	global_load_dwordx4 v[192:195], v[230:231], off offset:256
	s_waitcnt vmcnt(9)
	v_lshlrev_b32_e32 v115, 16, v196
	v_and_b32_e32 v116, 0xffff0000, v196
	v_lshlrev_b32_e32 v121, 16, v197
	v_and_b32_e32 v117, 0xffff0000, v197
	v_lshlrev_b32_e32 v124, 16, v198
	v_and_b32_e32 v118, 0xffff0000, v198
	v_lshlrev_b32_e32 v125, 16, v199
	v_and_b32_e32 v119, 0xffff0000, v199
	v_add_f32_e32 v115, v108, v115
	v_add_f32_e32 v116, v109, v116
	v_add_f32_e32 v121, v110, v121
	v_add_f32_e32 v117, v111, v117
	v_add_f32_e32 v124, v104, v124
	v_add_f32_e32 v118, v105, v118
	v_add_f32_e32 v125, v106, v125
	v_add_f32_e32 v119, v107, v119
	v_cvt_pk_bf16_f32 v104, v115, v116
	v_cvt_pk_bf16_f32 v105, v121, v117
	v_cvt_pk_bf16_f32 v106, v124, v118
	v_cvt_pk_bf16_f32 v107, v125, v119
	v_mul_f32_e32 v116, v116, v116
	v_mul_f32_e32 v117, v117, v117
	v_mul_f32_e32 v118, v118, v118
	v_mul_f32_e32 v119, v119, v119
	v_fmac_f32_e32 v116, v115, v115
	v_fmac_f32_e32 v117, v121, v121
	v_fmac_f32_e32 v118, v124, v124
	v_fmac_f32_e32 v119, v125, v125
	v_add_f32_e32 v115, v116, v117
	v_add_f32_e32 v116, v118, v119
	v_add_f32_e32 v115, v115, v116
	global_store_dwordx4 v[122:123], v[104:107], off
	s_waitcnt vmcnt(9)
	v_lshlrev_b32_e32 v116, 16, v200
	v_and_b32_e32 v108, 0xffff0000, v200
	v_lshlrev_b32_e32 v117, 16, v201
	v_and_b32_e32 v109, 0xffff0000, v201
	v_lshlrev_b32_e32 v118, 16, v202
	v_and_b32_e32 v110, 0xffff0000, v202
	v_lshlrev_b32_e32 v119, 16, v203
	v_and_b32_e32 v111, 0xffff0000, v203
	v_add_f32_e32 v101, v101, v108
	v_add_f32_e32 v103, v103, v109
	v_add_f32_e32 v109, v97, v110
	v_add_f32_e32 v111, v99, v111
	v_add_f32_e32 v100, v100, v116
	v_add_f32_e32 v102, v102, v117
	v_add_f32_e32 v108, v96, v118
	v_add_f32_e32 v110, v98, v119
	v_mul_f32_e32 v96, v101, v101
	v_mul_f32_e32 v97, v103, v103
	v_mul_f32_e32 v98, v109, v109
	v_mul_f32_e32 v99, v111, v111
	v_fmac_f32_e32 v96, v100, v100
	v_fmac_f32_e32 v97, v102, v102
	v_fmac_f32_e32 v98, v108, v108
	v_fmac_f32_e32 v99, v110, v110
	v_add_f32_e32 v96, v96, v97
	v_add_f32_e32 v97, v98, v99
	v_add_f32_e32 v96, v96, v97
	v_add_f32_e32 v96, v115, v96
	ds_bpermute_b32 v97, v120, v96
	v_cvt_pk_bf16_f32 v98, v100, v101
	v_cvt_pk_bf16_f32 v99, v102, v103
	v_cvt_pk_bf16_f32 v100, v108, v109
	v_cvt_pk_bf16_f32 v101, v110, v111
	s_waitcnt lgkmcnt(0)
	v_add_f32_e32 v96, v96, v97
	ds_bpermute_b32 v97, v114, v96
	global_store_dwordx4 v[122:123], v[98:101], off offset:256
	s_and_saveexec_b64 s[50:51], s[4:5]
	s_cbranch_execz .LBB0_393
	v_lshlrev_b64 v[98:99], 6, v[112:113]
	v_lshl_add_u64 v[98:99], s[18:19], 0, v[98:99]
	v_lshl_add_u64 v[98:99], s[48:49], 2, v[98:99]
	s_lshl_b32 s0, s64, 2
	v_lshl_add_u64 v[98:99], v[98:99], 0, s[0:1]
	s_waitcnt lgkmcnt(0)
	v_add_f32_e32 v96, v96, v97
	global_store_dword v[98:99], v96, off
.LBB0_393:
	s_or_b64 exec, exec, s[50:51]
	v_or_b32_e32 v96, 32, v150
	s_waitcnt lgkmcnt(0)
	v_ashrrev_i32_e32 v97, 31, v96
	v_lshlrev_b64 v[98:99], 11, v[96:97]
	v_lshl_add_u64 v[98:99], s[14:15], 0, v[98:99]
	v_lshl_add_u64 v[102:103], v[148:149], 1, v[98:99]
	s_mov_b64 s[100:101], 0x48000
	v_lshl_add_u64 v[230:231], v[232:233], 0, s[100:101]
	global_load_dwordx4 v[196:199], v[230:231], off
	global_load_dwordx4 v[200:203], v[230:231], off offset:256
	s_waitcnt vmcnt(11)
	v_lshlrev_b32_e32 v104, 16, v204
	v_and_b32_e32 v98, 0xffff0000, v204
	v_lshlrev_b32_e32 v105, 16, v205
	v_and_b32_e32 v99, 0xffff0000, v205
	v_lshlrev_b32_e32 v106, 16, v206
	v_and_b32_e32 v100, 0xffff0000, v206
	v_lshlrev_b32_e32 v107, 16, v207
	v_and_b32_e32 v101, 0xffff0000, v207
	v_add_f32_e32 v104, v92, v104
	v_add_f32_e32 v98, v93, v98
	v_add_f32_e32 v105, v94, v105
	v_add_f32_e32 v99, v95, v99
	v_add_f32_e32 v106, v88, v106
	v_add_f32_e32 v100, v89, v100
	v_add_f32_e32 v107, v90, v107
	v_add_f32_e32 v101, v91, v101
	v_cvt_pk_bf16_f32 v88, v104, v98
	v_cvt_pk_bf16_f32 v89, v105, v99
	v_cvt_pk_bf16_f32 v90, v106, v100
	v_cvt_pk_bf16_f32 v91, v107, v101
	v_mul_f32_e32 v98, v98, v98
	v_mul_f32_e32 v99, v99, v99
	v_mul_f32_e32 v100, v100, v100
	v_mul_f32_e32 v101, v101, v101
	v_fmac_f32_e32 v98, v104, v104
	v_fmac_f32_e32 v99, v105, v105
	v_fmac_f32_e32 v100, v106, v106
	v_fmac_f32_e32 v101, v107, v107
	v_add_f32_e32 v98, v98, v99
	v_add_f32_e32 v99, v100, v101
	v_add_f32_e32 v98, v98, v99
	global_store_dwordx4 v[102:103], v[88:91], off
	s_waitcnt vmcnt(11)
	v_lshlrev_b32_e32 v99, 16, v208
	v_and_b32_e32 v92, 0xffff0000, v208
	v_lshlrev_b32_e32 v100, 16, v209
	v_and_b32_e32 v93, 0xffff0000, v209
	v_lshlrev_b32_e32 v101, 16, v210
	v_and_b32_e32 v94, 0xffff0000, v210
	v_lshlrev_b32_e32 v104, 16, v211
	v_and_b32_e32 v95, 0xffff0000, v211
	v_add_f32_e32 v85, v85, v92
	v_add_f32_e32 v87, v87, v93
	v_add_f32_e32 v93, v81, v94
	v_add_f32_e32 v95, v83, v95
	v_add_f32_e32 v84, v84, v99
	v_add_f32_e32 v86, v86, v100
	v_add_f32_e32 v92, v80, v101
	v_add_f32_e32 v94, v82, v104
	v_mul_f32_e32 v80, v85, v85
	v_mul_f32_e32 v81, v87, v87
	v_mul_f32_e32 v82, v93, v93
	v_mul_f32_e32 v83, v95, v95
	v_fmac_f32_e32 v80, v84, v84
	v_fmac_f32_e32 v81, v86, v86
	v_fmac_f32_e32 v82, v92, v92
	v_fmac_f32_e32 v83, v94, v94
	v_add_f32_e32 v80, v80, v81
	v_add_f32_e32 v81, v82, v83
	v_add_f32_e32 v80, v80, v81
	v_add_f32_e32 v80, v98, v80
	ds_bpermute_b32 v81, v120, v80
	v_cvt_pk_bf16_f32 v82, v84, v85
	v_cvt_pk_bf16_f32 v83, v86, v87
	v_cvt_pk_bf16_f32 v84, v92, v93
	v_cvt_pk_bf16_f32 v85, v94, v95
	s_waitcnt lgkmcnt(0)
	v_add_f32_e32 v80, v80, v81
	ds_bpermute_b32 v81, v114, v80
	global_store_dwordx4 v[102:103], v[82:85], off offset:256
	s_and_saveexec_b64 s[50:51], s[4:5]
	s_cbranch_execz .LBB0_395
	v_lshlrev_b64 v[82:83], 6, v[96:97]
	v_lshl_add_u64 v[82:83], s[18:19], 0, v[82:83]
	v_lshl_add_u64 v[82:83], s[48:49], 2, v[82:83]
	s_lshl_b32 s0, s64, 2
	v_lshl_add_u64 v[82:83], v[82:83], 0, s[0:1]
	s_waitcnt lgkmcnt(0)
	v_add_f32_e32 v80, v80, v81
	global_store_dword v[82:83], v80, off
.LBB0_395:
	s_or_b64 exec, exec, s[50:51]
	v_or_b32_e32 v80, 48, v150
	s_waitcnt lgkmcnt(0)
	v_ashrrev_i32_e32 v81, 31, v80
	v_lshlrev_b64 v[82:83], 11, v[80:81]
	v_lshl_add_u64 v[82:83], s[14:15], 0, v[82:83]
	v_lshl_add_u64 v[86:87], v[148:149], 1, v[82:83]
	s_mov_b64 s[100:101], 0x50000
	v_lshl_add_u64 v[230:231], v[232:233], 0, s[100:101]
	global_load_dwordx4 v[204:207], v[230:231], off
	global_load_dwordx4 v[208:211], v[230:231], off offset:256
	s_waitcnt vmcnt(13)
	v_lshlrev_b32_e32 v88, 16, v212
	v_and_b32_e32 v82, 0xffff0000, v212
	v_lshlrev_b32_e32 v89, 16, v213
	v_and_b32_e32 v83, 0xffff0000, v213
	v_lshlrev_b32_e32 v90, 16, v214
	v_and_b32_e32 v84, 0xffff0000, v214
	v_lshlrev_b32_e32 v91, 16, v215
	v_and_b32_e32 v85, 0xffff0000, v215
	v_add_f32_e32 v88, v76, v88
	v_add_f32_e32 v82, v77, v82
	v_add_f32_e32 v89, v78, v89
	v_add_f32_e32 v83, v79, v83
	v_add_f32_e32 v90, v72, v90
	v_add_f32_e32 v84, v73, v84
	v_add_f32_e32 v91, v74, v91
	v_add_f32_e32 v85, v75, v85
	v_cvt_pk_bf16_f32 v72, v88, v82
	v_cvt_pk_bf16_f32 v73, v89, v83
	v_cvt_pk_bf16_f32 v74, v90, v84
	v_cvt_pk_bf16_f32 v75, v91, v85
	v_mul_f32_e32 v82, v82, v82
	v_mul_f32_e32 v83, v83, v83
	v_mul_f32_e32 v84, v84, v84
	v_mul_f32_e32 v85, v85, v85
	v_fmac_f32_e32 v82, v88, v88
	v_fmac_f32_e32 v83, v89, v89
	v_fmac_f32_e32 v84, v90, v90
	v_fmac_f32_e32 v85, v91, v91
	v_add_f32_e32 v82, v82, v83
	v_add_f32_e32 v83, v84, v85
	v_add_f32_e32 v82, v82, v83
	global_store_dwordx4 v[86:87], v[72:75], off
	s_waitcnt vmcnt(13)
	v_lshlrev_b32_e32 v83, 16, v216
	v_and_b32_e32 v76, 0xffff0000, v216
	v_lshlrev_b32_e32 v84, 16, v217
	v_and_b32_e32 v77, 0xffff0000, v217
	v_lshlrev_b32_e32 v85, 16, v218
	v_and_b32_e32 v78, 0xffff0000, v218
	v_lshlrev_b32_e32 v88, 16, v219
	v_and_b32_e32 v79, 0xffff0000, v219
	v_add_f32_e32 v69, v69, v76
	v_add_f32_e32 v71, v71, v77
	v_add_f32_e32 v77, v65, v78
	v_add_f32_e32 v79, v67, v79
	v_add_f32_e32 v68, v68, v83
	v_add_f32_e32 v70, v70, v84
	v_add_f32_e32 v76, v64, v85
	v_add_f32_e32 v78, v66, v88
	v_mul_f32_e32 v64, v69, v69
	v_mul_f32_e32 v65, v71, v71
	v_mul_f32_e32 v66, v77, v77
	v_mul_f32_e32 v67, v79, v79
	v_fmac_f32_e32 v64, v68, v68
	v_fmac_f32_e32 v65, v70, v70
	v_fmac_f32_e32 v66, v76, v76
	v_fmac_f32_e32 v67, v78, v78
	v_add_f32_e32 v64, v64, v65
	v_add_f32_e32 v65, v66, v67
	v_add_f32_e32 v64, v64, v65
	v_add_f32_e32 v64, v82, v64
	ds_bpermute_b32 v65, v120, v64
	v_cvt_pk_bf16_f32 v66, v68, v69
	v_cvt_pk_bf16_f32 v67, v70, v71
	v_cvt_pk_bf16_f32 v68, v76, v77
	v_cvt_pk_bf16_f32 v69, v78, v79
	s_waitcnt lgkmcnt(0)
	v_add_f32_e32 v64, v64, v65
	ds_bpermute_b32 v65, v114, v64
	global_store_dwordx4 v[86:87], v[66:69], off offset:256
	s_and_saveexec_b64 s[50:51], s[4:5]
	s_cbranch_execz .LBB0_397
	v_lshlrev_b64 v[66:67], 6, v[80:81]
	v_lshl_add_u64 v[66:67], s[18:19], 0, v[66:67]
	v_lshl_add_u64 v[66:67], s[48:49], 2, v[66:67]
	s_lshl_b32 s0, s64, 2
	v_lshl_add_u64 v[66:67], v[66:67], 0, s[0:1]
	s_waitcnt lgkmcnt(0)
	v_add_f32_e32 v64, v64, v65
	global_store_dword v[66:67], v64, off
.LBB0_397:
	s_or_b64 exec, exec, s[50:51]
	v_add_u32_e32 v64, 0x80, v150
	s_waitcnt lgkmcnt(0)
	v_ashrrev_i32_e32 v65, 31, v64
	v_lshlrev_b64 v[66:67], 11, v[64:65]
	v_lshl_add_u64 v[66:67], s[14:15], 0, v[66:67]
	v_lshl_add_u64 v[70:71], v[148:149], 1, v[66:67]
	s_mov_b64 s[100:101], 0x58000
	v_lshl_add_u64 v[230:231], v[232:233], 0, s[100:101]
	global_load_dwordx4 v[212:215], v[230:231], off
	global_load_dwordx4 v[216:219], v[230:231], off offset:256
	s_waitcnt vmcnt(13)
	v_lshlrev_b32_e32 v72, 16, v188
	v_and_b32_e32 v66, 0xffff0000, v188
	v_lshlrev_b32_e32 v73, 16, v189
	v_and_b32_e32 v67, 0xffff0000, v189
	v_lshlrev_b32_e32 v74, 16, v190
	v_and_b32_e32 v68, 0xffff0000, v190
	v_lshlrev_b32_e32 v75, 16, v191
	v_and_b32_e32 v69, 0xffff0000, v191
	v_add_f32_e32 v72, v60, v72
	v_add_f32_e32 v66, v61, v66
	v_add_f32_e32 v73, v62, v73
	v_add_f32_e32 v67, v63, v67
	v_add_f32_e32 v74, v56, v74
	v_add_f32_e32 v68, v57, v68
	v_add_f32_e32 v75, v58, v75
	v_add_f32_e32 v69, v59, v69
	v_cvt_pk_bf16_f32 v56, v72, v66
	v_cvt_pk_bf16_f32 v57, v73, v67
	v_cvt_pk_bf16_f32 v58, v74, v68
	v_cvt_pk_bf16_f32 v59, v75, v69
	v_mul_f32_e32 v66, v66, v66
	v_mul_f32_e32 v67, v67, v67
	v_mul_f32_e32 v68, v68, v68
	v_mul_f32_e32 v69, v69, v69
	v_fmac_f32_e32 v66, v72, v72
	v_fmac_f32_e32 v67, v73, v73
	v_fmac_f32_e32 v68, v74, v74
	v_fmac_f32_e32 v69, v75, v75
	v_add_f32_e32 v66, v66, v67
	v_add_f32_e32 v67, v68, v69
	v_add_f32_e32 v66, v66, v67
	global_store_dwordx4 v[70:71], v[56:59], off
	s_waitcnt vmcnt(13)
	v_lshlrev_b32_e32 v67, 16, v192
	v_and_b32_e32 v60, 0xffff0000, v192
	v_lshlrev_b32_e32 v68, 16, v193
	v_and_b32_e32 v61, 0xffff0000, v193
	v_lshlrev_b32_e32 v69, 16, v194
	v_and_b32_e32 v62, 0xffff0000, v194
	v_lshlrev_b32_e32 v72, 16, v195
	v_and_b32_e32 v63, 0xffff0000, v195
	v_add_f32_e32 v53, v53, v60
	v_add_f32_e32 v55, v55, v61
	v_add_f32_e32 v61, v49, v62
	v_add_f32_e32 v63, v51, v63
	v_add_f32_e32 v52, v52, v67
	v_add_f32_e32 v54, v54, v68
	v_add_f32_e32 v60, v48, v69
	v_add_f32_e32 v62, v50, v72
	v_mul_f32_e32 v48, v53, v53
	v_mul_f32_e32 v49, v55, v55
	v_mul_f32_e32 v50, v61, v61
	v_mul_f32_e32 v51, v63, v63
	v_fmac_f32_e32 v48, v52, v52
	v_fmac_f32_e32 v49, v54, v54
	v_fmac_f32_e32 v50, v60, v60
	v_fmac_f32_e32 v51, v62, v62
	v_add_f32_e32 v48, v48, v49
	v_add_f32_e32 v49, v50, v51
	v_add_f32_e32 v48, v48, v49
	v_add_f32_e32 v48, v66, v48
	ds_bpermute_b32 v49, v120, v48
	v_cvt_pk_bf16_f32 v50, v52, v53
	v_cvt_pk_bf16_f32 v51, v54, v55
	v_cvt_pk_bf16_f32 v52, v60, v61
	v_cvt_pk_bf16_f32 v53, v62, v63
	s_waitcnt lgkmcnt(0)
	v_add_f32_e32 v48, v48, v49
	ds_bpermute_b32 v49, v114, v48
	global_store_dwordx4 v[70:71], v[50:53], off offset:256
	s_and_saveexec_b64 s[50:51], s[4:5]
	s_cbranch_execz .LBB0_399
	v_lshlrev_b64 v[50:51], 6, v[64:65]
	v_lshl_add_u64 v[50:51], s[18:19], 0, v[50:51]
	v_lshl_add_u64 v[50:51], s[48:49], 2, v[50:51]
	s_lshl_b32 s0, s64, 2
	v_lshl_add_u64 v[50:51], v[50:51], 0, s[0:1]
	s_waitcnt lgkmcnt(0)
	v_add_f32_e32 v48, v48, v49
	global_store_dword v[50:51], v48, off
.LBB0_399:
	s_or_b64 exec, exec, s[50:51]
	v_add_u32_e32 v48, 0x90, v150
	s_waitcnt lgkmcnt(0)
	v_ashrrev_i32_e32 v49, 31, v48
	v_lshlrev_b64 v[50:51], 11, v[48:49]
	v_lshl_add_u64 v[50:51], s[14:15], 0, v[50:51]
	v_lshl_add_u64 v[54:55], v[148:149], 1, v[50:51]
	s_waitcnt vmcnt(11)
	v_lshlrev_b32_e32 v56, 16, v196
	v_and_b32_e32 v50, 0xffff0000, v196
	v_lshlrev_b32_e32 v57, 16, v197
	v_and_b32_e32 v51, 0xffff0000, v197
	v_lshlrev_b32_e32 v58, 16, v198
	v_and_b32_e32 v52, 0xffff0000, v198
	v_lshlrev_b32_e32 v59, 16, v199
	v_and_b32_e32 v53, 0xffff0000, v199
	v_add_f32_e32 v56, v44, v56
	v_add_f32_e32 v50, v45, v50
	v_add_f32_e32 v57, v46, v57
	v_add_f32_e32 v51, v47, v51
	v_add_f32_e32 v58, v40, v58
	v_add_f32_e32 v52, v41, v52
	v_add_f32_e32 v59, v42, v59
	v_add_f32_e32 v53, v43, v53
	v_cvt_pk_bf16_f32 v40, v56, v50
	v_cvt_pk_bf16_f32 v41, v57, v51
	v_cvt_pk_bf16_f32 v42, v58, v52
	v_cvt_pk_bf16_f32 v43, v59, v53
	v_mul_f32_e32 v50, v50, v50
	v_mul_f32_e32 v51, v51, v51
	v_mul_f32_e32 v52, v52, v52
	v_mul_f32_e32 v53, v53, v53
	v_fmac_f32_e32 v50, v56, v56
	v_fmac_f32_e32 v51, v57, v57
	v_fmac_f32_e32 v52, v58, v58
	v_fmac_f32_e32 v53, v59, v59
	v_add_f32_e32 v50, v50, v51
	v_add_f32_e32 v51, v52, v53
	v_add_f32_e32 v50, v50, v51
	global_store_dwordx4 v[54:55], v[40:43], off
	s_waitcnt vmcnt(11)
	v_lshlrev_b32_e32 v51, 16, v200
	v_and_b32_e32 v44, 0xffff0000, v200
	v_lshlrev_b32_e32 v52, 16, v201
	v_and_b32_e32 v45, 0xffff0000, v201
	v_lshlrev_b32_e32 v53, 16, v202
	v_and_b32_e32 v46, 0xffff0000, v202
	v_lshlrev_b32_e32 v56, 16, v203
	v_and_b32_e32 v47, 0xffff0000, v203
	v_add_f32_e32 v37, v37, v44
	v_add_f32_e32 v39, v39, v45
	v_add_f32_e32 v45, v33, v46
	v_add_f32_e32 v47, v35, v47
	v_add_f32_e32 v36, v36, v51
	v_add_f32_e32 v38, v38, v52
	v_add_f32_e32 v44, v32, v53
	v_add_f32_e32 v46, v34, v56
	v_mul_f32_e32 v32, v37, v37
	v_mul_f32_e32 v33, v39, v39
	v_mul_f32_e32 v34, v45, v45
	v_mul_f32_e32 v35, v47, v47
	v_fmac_f32_e32 v32, v36, v36
	v_fmac_f32_e32 v33, v38, v38
	v_fmac_f32_e32 v34, v44, v44
	v_fmac_f32_e32 v35, v46, v46
	v_add_f32_e32 v32, v32, v33
	v_add_f32_e32 v33, v34, v35
	v_add_f32_e32 v32, v32, v33
	v_add_f32_e32 v32, v50, v32
	ds_bpermute_b32 v33, v120, v32
	v_cvt_pk_bf16_f32 v34, v36, v37
	v_cvt_pk_bf16_f32 v35, v38, v39
	v_cvt_pk_bf16_f32 v36, v44, v45
	v_cvt_pk_bf16_f32 v37, v46, v47
	s_waitcnt lgkmcnt(0)
	v_add_f32_e32 v32, v32, v33
	ds_bpermute_b32 v33, v114, v32
	global_store_dwordx4 v[54:55], v[34:37], off offset:256
	s_and_saveexec_b64 s[50:51], s[4:5]
	s_cbranch_execz .LBB0_401
	v_lshlrev_b64 v[34:35], 6, v[48:49]
	v_lshl_add_u64 v[34:35], s[18:19], 0, v[34:35]
	v_lshl_add_u64 v[34:35], s[48:49], 2, v[34:35]
	s_lshl_b32 s0, s64, 2
	v_lshl_add_u64 v[34:35], v[34:35], 0, s[0:1]
	s_waitcnt lgkmcnt(0)
	v_add_f32_e32 v32, v32, v33
	global_store_dword v[34:35], v32, off
.LBB0_401:
	s_or_b64 exec, exec, s[50:51]
	v_add_u32_e32 v32, 0xa0, v150
	s_waitcnt lgkmcnt(0)
	v_ashrrev_i32_e32 v33, 31, v32
	v_lshlrev_b64 v[34:35], 11, v[32:33]
	v_lshl_add_u64 v[34:35], s[14:15], 0, v[34:35]
	v_lshl_add_u64 v[38:39], v[148:149], 1, v[34:35]
	s_waitcnt vmcnt(9)
	v_lshlrev_b32_e32 v40, 16, v204
	v_and_b32_e32 v34, 0xffff0000, v204
	v_lshlrev_b32_e32 v41, 16, v205
	v_and_b32_e32 v35, 0xffff0000, v205
	v_lshlrev_b32_e32 v42, 16, v206
	v_and_b32_e32 v36, 0xffff0000, v206
	v_lshlrev_b32_e32 v43, 16, v207
	v_and_b32_e32 v37, 0xffff0000, v207
	v_add_f32_e32 v40, v28, v40
	v_add_f32_e32 v34, v29, v34
	v_add_f32_e32 v41, v30, v41
	v_add_f32_e32 v35, v31, v35
	v_add_f32_e32 v42, v24, v42
	v_add_f32_e32 v36, v25, v36
	v_add_f32_e32 v43, v26, v43
	v_add_f32_e32 v37, v27, v37
	v_cvt_pk_bf16_f32 v24, v40, v34
	v_cvt_pk_bf16_f32 v25, v41, v35
	v_cvt_pk_bf16_f32 v26, v42, v36
	v_cvt_pk_bf16_f32 v27, v43, v37
	v_mul_f32_e32 v34, v34, v34
	v_mul_f32_e32 v35, v35, v35
	v_mul_f32_e32 v36, v36, v36
	v_mul_f32_e32 v37, v37, v37
	v_fmac_f32_e32 v34, v40, v40
	v_fmac_f32_e32 v35, v41, v41
	v_fmac_f32_e32 v36, v42, v42
	v_fmac_f32_e32 v37, v43, v43
	v_add_f32_e32 v34, v34, v35
	v_add_f32_e32 v35, v36, v37
	v_add_f32_e32 v34, v34, v35
	global_store_dwordx4 v[38:39], v[24:27], off
	s_waitcnt vmcnt(9)
	v_lshlrev_b32_e32 v35, 16, v208
	v_and_b32_e32 v28, 0xffff0000, v208
	v_lshlrev_b32_e32 v36, 16, v209
	v_and_b32_e32 v29, 0xffff0000, v209
	v_lshlrev_b32_e32 v37, 16, v210
	v_and_b32_e32 v30, 0xffff0000, v210
	v_lshlrev_b32_e32 v40, 16, v211
	v_and_b32_e32 v31, 0xffff0000, v211
	v_add_f32_e32 v21, v21, v28
	v_add_f32_e32 v23, v23, v29
	v_add_f32_e32 v29, v17, v30
	v_add_f32_e32 v31, v19, v31
	v_add_f32_e32 v20, v20, v35
	v_add_f32_e32 v22, v22, v36
	v_add_f32_e32 v28, v16, v37
	v_add_f32_e32 v30, v18, v40
	v_mul_f32_e32 v16, v21, v21
	v_mul_f32_e32 v17, v23, v23
	v_mul_f32_e32 v18, v29, v29
	v_mul_f32_e32 v19, v31, v31
	v_fmac_f32_e32 v16, v20, v20
	v_fmac_f32_e32 v17, v22, v22
	v_fmac_f32_e32 v18, v28, v28
	v_fmac_f32_e32 v19, v30, v30
	v_add_f32_e32 v16, v16, v17
	v_add_f32_e32 v17, v18, v19
	v_add_f32_e32 v16, v16, v17
	v_add_f32_e32 v16, v34, v16
	ds_bpermute_b32 v17, v120, v16
	v_cvt_pk_bf16_f32 v18, v20, v21
	v_cvt_pk_bf16_f32 v19, v22, v23
	v_cvt_pk_bf16_f32 v20, v28, v29
	v_cvt_pk_bf16_f32 v21, v30, v31
	s_waitcnt lgkmcnt(0)
	v_add_f32_e32 v16, v16, v17
	ds_bpermute_b32 v17, v114, v16
	global_store_dwordx4 v[38:39], v[18:21], off offset:256
	s_and_saveexec_b64 s[50:51], s[4:5]
	s_cbranch_execz .LBB0_403
	v_lshlrev_b64 v[18:19], 6, v[32:33]
	v_lshl_add_u64 v[18:19], s[18:19], 0, v[18:19]
	v_lshl_add_u64 v[18:19], s[48:49], 2, v[18:19]
	s_lshl_b32 s0, s64, 2
	v_lshl_add_u64 v[18:19], v[18:19], 0, s[0:1]
	s_waitcnt lgkmcnt(0)
	v_add_f32_e32 v16, v16, v17
	global_store_dword v[18:19], v16, off
.LBB0_403:
	s_or_b64 exec, exec, s[50:51]
	v_add_u32_e32 v16, 0xb0, v150
	s_waitcnt lgkmcnt(0)
	v_ashrrev_i32_e32 v17, 31, v16
	v_lshlrev_b64 v[18:19], 11, v[16:17]
	v_lshl_add_u64 v[18:19], s[14:15], 0, v[18:19]
	v_lshl_add_u64 v[22:23], v[148:149], 1, v[18:19]
	s_waitcnt vmcnt(7)
	v_lshlrev_b32_e32 v24, 16, v212
	v_and_b32_e32 v18, 0xffff0000, v212
	v_lshlrev_b32_e32 v25, 16, v213
	v_and_b32_e32 v19, 0xffff0000, v213
	v_lshlrev_b32_e32 v26, 16, v214
	v_and_b32_e32 v20, 0xffff0000, v214
	v_lshlrev_b32_e32 v27, 16, v215
	v_and_b32_e32 v21, 0xffff0000, v215
	v_add_f32_e32 v24, v12, v24
	v_add_f32_e32 v18, v13, v18
	v_add_f32_e32 v25, v14, v25
	v_add_f32_e32 v19, v15, v19
	v_add_f32_e32 v26, v8, v26
	v_add_f32_e32 v20, v9, v20
	v_add_f32_e32 v27, v10, v27
	v_add_f32_e32 v21, v11, v21
	v_cvt_pk_bf16_f32 v8, v24, v18
	v_cvt_pk_bf16_f32 v9, v25, v19
	v_cvt_pk_bf16_f32 v10, v26, v20
	v_cvt_pk_bf16_f32 v11, v27, v21
	v_mul_f32_e32 v18, v18, v18
	v_mul_f32_e32 v19, v19, v19
	v_mul_f32_e32 v20, v20, v20
	v_mul_f32_e32 v21, v21, v21
	v_fmac_f32_e32 v18, v24, v24
	v_fmac_f32_e32 v19, v25, v25
	v_fmac_f32_e32 v20, v26, v26
	v_fmac_f32_e32 v21, v27, v27
	v_add_f32_e32 v18, v18, v19
	v_add_f32_e32 v19, v20, v21
	v_add_f32_e32 v18, v18, v19
	global_store_dwordx4 v[22:23], v[8:11], off
	s_waitcnt vmcnt(7)
	v_lshlrev_b32_e32 v19, 16, v216
	v_and_b32_e32 v12, 0xffff0000, v216
	v_lshlrev_b32_e32 v20, 16, v217
	v_and_b32_e32 v13, 0xffff0000, v217
	v_lshlrev_b32_e32 v21, 16, v218
	v_and_b32_e32 v14, 0xffff0000, v218
	v_lshlrev_b32_e32 v24, 16, v219
	v_and_b32_e32 v15, 0xffff0000, v219
	v_add_f32_e32 v5, v5, v12
	v_add_f32_e32 v7, v7, v13
	v_add_f32_e32 v13, v1, v14
	v_add_f32_e32 v15, v3, v15
	v_add_f32_e32 v4, v4, v19
	v_add_f32_e32 v6, v6, v20
	v_add_f32_e32 v12, v0, v21
	v_add_f32_e32 v14, v2, v24
	v_mul_f32_e32 v0, v5, v5
	v_mul_f32_e32 v1, v7, v7
	v_mul_f32_e32 v2, v13, v13
	v_mul_f32_e32 v3, v15, v15
	v_fmac_f32_e32 v0, v4, v4
	v_fmac_f32_e32 v1, v6, v6
	v_fmac_f32_e32 v2, v12, v12
	v_fmac_f32_e32 v3, v14, v14
	v_add_f32_e32 v0, v0, v1
	v_add_f32_e32 v1, v2, v3
	v_add_f32_e32 v0, v0, v1
	v_add_f32_e32 v0, v18, v0
	ds_bpermute_b32 v1, v120, v0
	v_cvt_pk_bf16_f32 v2, v4, v5
	v_cvt_pk_bf16_f32 v3, v6, v7
	v_cvt_pk_bf16_f32 v4, v12, v13
	v_cvt_pk_bf16_f32 v5, v14, v15
	s_waitcnt lgkmcnt(0)
	v_add_f32_e32 v0, v0, v1
	ds_bpermute_b32 v1, v114, v0
	global_store_dwordx4 v[22:23], v[2:5], off offset:256
	s_and_saveexec_b64 s[50:51], s[4:5]
	s_cbranch_execz .LBB0_405
	v_lshlrev_b64 v[2:3], 6, v[16:17]
	v_lshl_add_u64 v[2:3], s[18:19], 0, v[2:3]
	v_lshl_add_u64 v[2:3], s[48:49], 2, v[2:3]
	s_lshl_b32 s0, s64, 2
	v_lshl_add_u64 v[2:3], v[2:3], 0, s[0:1]
	s_waitcnt lgkmcnt(0)
	v_add_f32_e32 v0, v0, v1
	global_store_dword v[2:3], v0, off

.LBB0_565:
	v_lshl_add_u32 v150, s12, 8, v131
	v_ashrrev_i32_e32 v151, 31, v150
	v_lshl_or_b32 v148, s8, 8, v153
	v_lshlrev_b64 v[160:161], 11, v[150:151]
	v_ashrrev_i32_e32 v149, 31, v148
	v_lshl_add_u64 v[160:161], s[14:15], 0, v[160:161]
	v_lshl_add_u64 v[164:165], v[148:149], 1, v[160:161]
	v_mov_b32_e32 v232, v164
	v_mov_b32_e32 v233, v165
	global_load_dwordx4 v[188:191], v[232:233], off
	global_load_dwordx4 v[192:195], v[232:233], off offset:256
	s_mov_b64 s[100:101], 0x8000
	v_lshl_add_u64 v[230:231], v[232:233], 0, s[100:101]
	global_load_dwordx4 v[196:199], v[230:231], off
	global_load_dwordx4 v[200:203], v[230:231], off offset:256
	s_mov_b64 s[100:101], 0x10000
	v_lshl_add_u64 v[230:231], v[232:233], 0, s[100:101]
	global_load_dwordx4 v[204:207], v[230:231], off
	global_load_dwordx4 v[208:211], v[230:231], off offset:256
	s_mov_b64 s[100:101], 0x18000
	v_lshl_add_u64 v[230:231], v[232:233], 0, s[100:101]
	global_load_dwordx4 v[212:215], v[230:231], off
	global_load_dwordx4 v[216:219], v[230:231], off offset:256
	v_and_b32_e32 v170, 64, v158
	v_add_u32_e32 v170, 64, v170
	v_xor_b32_e32 v171, 32, v158
	s_lshl_b32 s40, s8, 2
	s_ashr_i32 s41, s40, 31
	s_waitcnt vmcnt(7)
	v_lshlrev_b32_e32 v159, 16, v188
	v_and_b32_e32 v160, 0xffff0000, v188
	v_lshlrev_b32_e32 v166, 16, v189
	v_and_b32_e32 v161, 0xffff0000, v189
	v_lshlrev_b32_e32 v167, 16, v190
	v_and_b32_e32 v162, 0xffff0000, v190
	v_lshlrev_b32_e32 v168, 16, v191
	v_and_b32_e32 v163, 0xffff0000, v191
	v_add_f32_e32 v159, v124, v159
	v_add_f32_e32 v169, v125, v160
	v_add_f32_e32 v126, v126, v166
	v_add_f32_e32 v127, v127, v161
	v_add_f32_e32 v166, v120, v167
	v_add_f32_e32 v121, v121, v162
	v_add_f32_e32 v167, v122, v168
	v_add_f32_e32 v168, v123, v163
	v_cvt_pk_bf16_f32 v122, v159, v169
	v_cvt_pk_bf16_f32 v123, v126, v127
	v_cvt_pk_bf16_f32 v124, v166, v121
	v_cvt_pk_bf16_f32 v125, v167, v168
	v_mul_f32_e32 v169, v169, v169
	v_mul_f32_e32 v127, v127, v127
	v_mul_f32_e32 v121, v121, v121
	v_mul_f32_e32 v168, v168, v168
	v_fmac_f32_e32 v169, v159, v159
	v_fmac_f32_e32 v127, v126, v126
	v_fmac_f32_e32 v121, v166, v166
	v_fmac_f32_e32 v168, v167, v167
	v_add_f32_e32 v126, v169, v127
	v_add_f32_e32 v121, v121, v168
	v_add_f32_e32 v121, v126, v121
	v_xor_b32_e32 v120, 16, v158
	v_cmp_lt_i32_e32 vcc, v120, v170
	global_store_dwordx4 v[164:165], v[122:125], off
	s_waitcnt vmcnt(7)
	v_lshlrev_b32_e32 v126, 16, v192
	v_and_b32_e32 v127, 0xffff0000, v192
	v_lshlrev_b32_e32 v159, 16, v193
	v_and_b32_e32 v160, 0xffff0000, v193
	v_lshlrev_b32_e32 v161, 16, v194
	v_and_b32_e32 v162, 0xffff0000, v194
	v_lshlrev_b32_e32 v166, 16, v195
	v_and_b32_e32 v163, 0xffff0000, v195
	v_add_f32_e32 v117, v117, v127
	v_add_f32_e32 v119, v119, v160
	v_add_f32_e32 v127, v113, v162
	v_add_f32_e32 v115, v115, v163
	v_add_f32_e32 v116, v116, v126
	v_add_f32_e32 v118, v118, v159
	v_add_f32_e32 v126, v112, v161
	v_add_f32_e32 v159, v114, v166
	v_mul_f32_e32 v112, v117, v117
	v_mul_f32_e32 v113, v119, v119
	v_mul_f32_e32 v114, v127, v127
	v_mul_f32_e32 v160, v115, v115
	v_fmac_f32_e32 v112, v116, v116
	v_fmac_f32_e32 v113, v118, v118
	v_fmac_f32_e32 v114, v126, v126
	v_fmac_f32_e32 v160, v159, v159
	v_add_f32_e32 v112, v112, v113
	v_add_f32_e32 v113, v114, v160
	v_cndmask_b32_e32 v120, v158, v120, vcc
	v_add_f32_e32 v112, v112, v113
	v_lshlrev_b32_e32 v120, 2, v120
	v_add_f32_e32 v112, v121, v112
	ds_bpermute_b32 v113, v120, v112
	v_cmp_lt_i32_e32 vcc, v171, v170
	v_cvt_pk_bf16_f32 v116, v116, v117
	v_cvt_pk_bf16_f32 v117, v118, v119
	v_cvt_pk_bf16_f32 v118, v126, v127
	s_waitcnt lgkmcnt(0)
	v_add_f32_e32 v112, v112, v113
	v_cvt_pk_bf16_f32 v119, v159, v115
	v_cndmask_b32_e32 v114, v158, v171, vcc
	v_lshlrev_b32_e32 v114, 2, v114
	ds_bpermute_b32 v113, v114, v112
	global_store_dwordx4 v[164:165], v[116:119], off offset:256
	s_and_saveexec_b64 s[42:43], s[4:5]
	s_cbranch_execz .LBB0_567
	v_lshlrev_b64 v[116:117], 6, v[150:151]
	v_lshl_add_u64 v[116:117], s[18:19], 0, v[116:117]
	v_lshl_add_u64 v[116:117], s[40:41], 2, v[116:117]
	s_lshl_b32 s8, s56, 2
	v_lshl_add_u64 v[116:117], v[116:117], 0, s[8:9]
	s_waitcnt lgkmcnt(0)
	v_add_f32_e32 v112, v112, v113
	global_store_dword v[116:117], v112, off
.LBB0_567:
	s_or_b64 exec, exec, s[42:43]
	v_or_b32_e32 v112, 16, v150
	s_waitcnt lgkmcnt(0)
	v_ashrrev_i32_e32 v113, 31, v112
	v_lshlrev_b64 v[116:117], 11, v[112:113]
	v_lshl_add_u64 v[116:117], s[14:15], 0, v[116:117]
	v_lshl_add_u64 v[122:123], v[148:149], 1, v[116:117]
	s_mov_b64 s[100:101], 0x40000
	v_lshl_add_u64 v[230:231], v[232:233], 0, s[100:101]
	global_load_dwordx4 v[188:191], v[230:231], off
	global_load_dwordx4 v[192:195], v[230:231], off offset:256
	s_waitcnt vmcnt(9)
	v_lshlrev_b32_e32 v115, 16, v196
	v_and_b32_e32 v116, 0xffff0000, v196
	v_lshlrev_b32_e32 v121, 16, v197
	v_and_b32_e32 v117, 0xffff0000, v197
	v_lshlrev_b32_e32 v124, 16, v198
	v_and_b32_e32 v118, 0xffff0000, v198
	v_lshlrev_b32_e32 v125, 16, v199
	v_and_b32_e32 v119, 0xffff0000, v199
	v_add_f32_e32 v115, v108, v115
	v_add_f32_e32 v116, v109, v116
	v_add_f32_e32 v121, v110, v121
	v_add_f32_e32 v117, v111, v117
	v_add_f32_e32 v124, v104, v124
	v_add_f32_e32 v118, v105, v118
	v_add_f32_e32 v125, v106, v125
	v_add_f32_e32 v119, v107, v119
	v_cvt_pk_bf16_f32 v104, v115, v116
	v_cvt_pk_bf16_f32 v105, v121, v117
	v_cvt_pk_bf16_f32 v106, v124, v118
	v_cvt_pk_bf16_f32 v107, v125, v119
	v_mul_f32_e32 v116, v116, v116
	v_mul_f32_e32 v117, v117, v117
	v_mul_f32_e32 v118, v118, v118
	v_mul_f32_e32 v119, v119, v119
	v_fmac_f32_e32 v116, v115, v115
	v_fmac_f32_e32 v117, v121, v121
	v_fmac_f32_e32 v118, v124, v124
	v_fmac_f32_e32 v119, v125, v125
	v_add_f32_e32 v115, v116, v117
	v_add_f32_e32 v116, v118, v119
	v_add_f32_e32 v115, v115, v116
	global_store_dwordx4 v[122:123], v[104:107], off
	s_waitcnt vmcnt(9)
	v_lshlrev_b32_e32 v116, 16, v200
	v_and_b32_e32 v108, 0xffff0000, v200
	v_lshlrev_b32_e32 v117, 16, v201
	v_and_b32_e32 v109, 0xffff0000, v201
	v_lshlrev_b32_e32 v118, 16, v202
	v_and_b32_e32 v110, 0xffff0000, v202
	v_lshlrev_b32_e32 v119, 16, v203
	v_and_b32_e32 v111, 0xffff0000, v203
	v_add_f32_e32 v101, v101, v108
	v_add_f32_e32 v103, v103, v109
	v_add_f32_e32 v109, v97, v110
	v_add_f32_e32 v111, v99, v111
	v_add_f32_e32 v100, v100, v116
	v_add_f32_e32 v102, v102, v117
	v_add_f32_e32 v108, v96, v118
	v_add_f32_e32 v110, v98, v119
	v_mul_f32_e32 v96, v101, v101
	v_mul_f32_e32 v97, v103, v103
	v_mul_f32_e32 v98, v109, v109
	v_mul_f32_e32 v99, v111, v111
	v_fmac_f32_e32 v96, v100, v100
	v_fmac_f32_e32 v97, v102, v102
	v_fmac_f32_e32 v98, v108, v108
	v_fmac_f32_e32 v99, v110, v110
	v_add_f32_e32 v96, v96, v97
	v_add_f32_e32 v97, v98, v99
	v_add_f32_e32 v96, v96, v97
	v_add_f32_e32 v96, v115, v96
	ds_bpermute_b32 v97, v120, v96
	v_cvt_pk_bf16_f32 v98, v100, v101
	v_cvt_pk_bf16_f32 v99, v102, v103
	v_cvt_pk_bf16_f32 v100, v108, v109
	v_cvt_pk_bf16_f32 v101, v110, v111
	s_waitcnt lgkmcnt(0)
	v_add_f32_e32 v96, v96, v97
	ds_bpermute_b32 v97, v114, v96
	global_store_dwordx4 v[122:123], v[98:101], off offset:256
	s_and_saveexec_b64 s[42:43], s[4:5]
	s_cbranch_execz .LBB0_569
	v_lshlrev_b64 v[98:99], 6, v[112:113]
	v_lshl_add_u64 v[98:99], s[18:19], 0, v[98:99]
	v_lshl_add_u64 v[98:99], s[40:41], 2, v[98:99]
	s_lshl_b32 s8, s56, 2
	v_lshl_add_u64 v[98:99], v[98:99], 0, s[8:9]
	s_waitcnt lgkmcnt(0)
	v_add_f32_e32 v96, v96, v97
	global_store_dword v[98:99], v96, off
.LBB0_569:
	s_or_b64 exec, exec, s[42:43]
	v_or_b32_e32 v96, 32, v150
	s_waitcnt lgkmcnt(0)
	v_ashrrev_i32_e32 v97, 31, v96
	v_lshlrev_b64 v[98:99], 11, v[96:97]
	v_lshl_add_u64 v[98:99], s[14:15], 0, v[98:99]
	v_lshl_add_u64 v[102:103], v[148:149], 1, v[98:99]
	s_mov_b64 s[100:101], 0x48000
	v_lshl_add_u64 v[230:231], v[232:233], 0, s[100:101]
	global_load_dwordx4 v[196:199], v[230:231], off
	global_load_dwordx4 v[200:203], v[230:231], off offset:256
	s_waitcnt vmcnt(11)
	v_lshlrev_b32_e32 v104, 16, v204
	v_and_b32_e32 v98, 0xffff0000, v204
	v_lshlrev_b32_e32 v105, 16, v205
	v_and_b32_e32 v99, 0xffff0000, v205
	v_lshlrev_b32_e32 v106, 16, v206
	v_and_b32_e32 v100, 0xffff0000, v206
	v_lshlrev_b32_e32 v107, 16, v207
	v_and_b32_e32 v101, 0xffff0000, v207
	v_add_f32_e32 v104, v92, v104
	v_add_f32_e32 v98, v93, v98
	v_add_f32_e32 v105, v94, v105
	v_add_f32_e32 v99, v95, v99
	v_add_f32_e32 v106, v88, v106
	v_add_f32_e32 v100, v89, v100
	v_add_f32_e32 v107, v90, v107
	v_add_f32_e32 v101, v91, v101
	v_cvt_pk_bf16_f32 v88, v104, v98
	v_cvt_pk_bf16_f32 v89, v105, v99
	v_cvt_pk_bf16_f32 v90, v106, v100
	v_cvt_pk_bf16_f32 v91, v107, v101
	v_mul_f32_e32 v98, v98, v98
	v_mul_f32_e32 v99, v99, v99
	v_mul_f32_e32 v100, v100, v100
	v_mul_f32_e32 v101, v101, v101
	v_fmac_f32_e32 v98, v104, v104
	v_fmac_f32_e32 v99, v105, v105
	v_fmac_f32_e32 v100, v106, v106
	v_fmac_f32_e32 v101, v107, v107
	v_add_f32_e32 v98, v98, v99
	v_add_f32_e32 v99, v100, v101
	v_add_f32_e32 v98, v98, v99
	global_store_dwordx4 v[102:103], v[88:91], off
	s_waitcnt vmcnt(11)
	v_lshlrev_b32_e32 v99, 16, v208
	v_and_b32_e32 v92, 0xffff0000, v208
	v_lshlrev_b32_e32 v100, 16, v209
	v_and_b32_e32 v93, 0xffff0000, v209
	v_lshlrev_b32_e32 v101, 16, v210
	v_and_b32_e32 v94, 0xffff0000, v210
	v_lshlrev_b32_e32 v104, 16, v211
	v_and_b32_e32 v95, 0xffff0000, v211
	v_add_f32_e32 v85, v85, v92
	v_add_f32_e32 v87, v87, v93
	v_add_f32_e32 v93, v81, v94
	v_add_f32_e32 v95, v83, v95
	v_add_f32_e32 v84, v84, v99
	v_add_f32_e32 v86, v86, v100
	v_add_f32_e32 v92, v80, v101
	v_add_f32_e32 v94, v82, v104
	v_mul_f32_e32 v80, v85, v85
	v_mul_f32_e32 v81, v87, v87
	v_mul_f32_e32 v82, v93, v93
	v_mul_f32_e32 v83, v95, v95
	v_fmac_f32_e32 v80, v84, v84
	v_fmac_f32_e32 v81, v86, v86
	v_fmac_f32_e32 v82, v92, v92
	v_fmac_f32_e32 v83, v94, v94
	v_add_f32_e32 v80, v80, v81
	v_add_f32_e32 v81, v82, v83
	v_add_f32_e32 v80, v80, v81
	v_add_f32_e32 v80, v98, v80
	ds_bpermute_b32 v81, v120, v80
	v_cvt_pk_bf16_f32 v82, v84, v85
	v_cvt_pk_bf16_f32 v83, v86, v87
	v_cvt_pk_bf16_f32 v84, v92, v93
	v_cvt_pk_bf16_f32 v85, v94, v95
	s_waitcnt lgkmcnt(0)
	v_add_f32_e32 v80, v80, v81
	ds_bpermute_b32 v81, v114, v80
	global_store_dwordx4 v[102:103], v[82:85], off offset:256
	s_and_saveexec_b64 s[42:43], s[4:5]
	s_cbranch_execz .LBB0_571
	v_lshlrev_b64 v[82:83], 6, v[96:97]
	v_lshl_add_u64 v[82:83], s[18:19], 0, v[82:83]
	v_lshl_add_u64 v[82:83], s[40:41], 2, v[82:83]
	s_lshl_b32 s8, s56, 2
	v_lshl_add_u64 v[82:83], v[82:83], 0, s[8:9]
	s_waitcnt lgkmcnt(0)
	v_add_f32_e32 v80, v80, v81
	global_store_dword v[82:83], v80, off
.LBB0_571:
	s_or_b64 exec, exec, s[42:43]
	v_or_b32_e32 v80, 48, v150
	s_waitcnt lgkmcnt(0)
	v_ashrrev_i32_e32 v81, 31, v80
	v_lshlrev_b64 v[82:83], 11, v[80:81]
	v_lshl_add_u64 v[82:83], s[14:15], 0, v[82:83]
	v_lshl_add_u64 v[86:87], v[148:149], 1, v[82:83]
	s_mov_b64 s[100:101], 0x50000
	v_lshl_add_u64 v[230:231], v[232:233], 0, s[100:101]
	global_load_dwordx4 v[204:207], v[230:231], off
	global_load_dwordx4 v[208:211], v[230:231], off offset:256
	s_waitcnt vmcnt(13)
	v_lshlrev_b32_e32 v88, 16, v212
	v_and_b32_e32 v82, 0xffff0000, v212
	v_lshlrev_b32_e32 v89, 16, v213
	v_and_b32_e32 v83, 0xffff0000, v213
	v_lshlrev_b32_e32 v90, 16, v214
	v_and_b32_e32 v84, 0xffff0000, v214
	v_lshlrev_b32_e32 v91, 16, v215
	v_and_b32_e32 v85, 0xffff0000, v215
	v_add_f32_e32 v88, v76, v88
	v_add_f32_e32 v82, v77, v82
	v_add_f32_e32 v89, v78, v89
	v_add_f32_e32 v83, v79, v83
	v_add_f32_e32 v90, v72, v90
	v_add_f32_e32 v84, v73, v84
	v_add_f32_e32 v91, v74, v91
	v_add_f32_e32 v85, v75, v85
	v_cvt_pk_bf16_f32 v72, v88, v82
	v_cvt_pk_bf16_f32 v73, v89, v83
	v_cvt_pk_bf16_f32 v74, v90, v84
	v_cvt_pk_bf16_f32 v75, v91, v85
	v_mul_f32_e32 v82, v82, v82
	v_mul_f32_e32 v83, v83, v83
	v_mul_f32_e32 v84, v84, v84
	v_mul_f32_e32 v85, v85, v85
	v_fmac_f32_e32 v82, v88, v88
	v_fmac_f32_e32 v83, v89, v89
	v_fmac_f32_e32 v84, v90, v90
	v_fmac_f32_e32 v85, v91, v91
	v_add_f32_e32 v82, v82, v83
	v_add_f32_e32 v83, v84, v85
	v_add_f32_e32 v82, v82, v83
	global_store_dwordx4 v[86:87], v[72:75], off
	s_waitcnt vmcnt(13)
	v_lshlrev_b32_e32 v83, 16, v216
	v_and_b32_e32 v76, 0xffff0000, v216
	v_lshlrev_b32_e32 v84, 16, v217
	v_and_b32_e32 v77, 0xffff0000, v217
	v_lshlrev_b32_e32 v85, 16, v218
	v_and_b32_e32 v78, 0xffff0000, v218
	v_lshlrev_b32_e32 v88, 16, v219
	v_and_b32_e32 v79, 0xffff0000, v219
	v_add_f32_e32 v69, v69, v76
	v_add_f32_e32 v71, v71, v77
	v_add_f32_e32 v77, v65, v78
	v_add_f32_e32 v79, v67, v79
	v_add_f32_e32 v68, v68, v83
	v_add_f32_e32 v70, v70, v84
	v_add_f32_e32 v76, v64, v85
	v_add_f32_e32 v78, v66, v88
	v_mul_f32_e32 v64, v69, v69
	v_mul_f32_e32 v65, v71, v71
	v_mul_f32_e32 v66, v77, v77
	v_mul_f32_e32 v67, v79, v79
	v_fmac_f32_e32 v64, v68, v68
	v_fmac_f32_e32 v65, v70, v70
	v_fmac_f32_e32 v66, v76, v76
	v_fmac_f32_e32 v67, v78, v78
	v_add_f32_e32 v64, v64, v65
	v_add_f32_e32 v65, v66, v67
	v_add_f32_e32 v64, v64, v65
	v_add_f32_e32 v64, v82, v64
	ds_bpermute_b32 v65, v120, v64
	v_cvt_pk_bf16_f32 v66, v68, v69
	v_cvt_pk_bf16_f32 v67, v70, v71
	v_cvt_pk_bf16_f32 v68, v76, v77
	v_cvt_pk_bf16_f32 v69, v78, v79
	s_waitcnt lgkmcnt(0)
	v_add_f32_e32 v64, v64, v65
	ds_bpermute_b32 v65, v114, v64
	global_store_dwordx4 v[86:87], v[66:69], off offset:256
	s_and_saveexec_b64 s[42:43], s[4:5]
	s_cbranch_execz .LBB0_573
	v_lshlrev_b64 v[66:67], 6, v[80:81]
	v_lshl_add_u64 v[66:67], s[18:19], 0, v[66:67]
	v_lshl_add_u64 v[66:67], s[40:41], 2, v[66:67]
	s_lshl_b32 s8, s56, 2
	v_lshl_add_u64 v[66:67], v[66:67], 0, s[8:9]
	s_waitcnt lgkmcnt(0)
	v_add_f32_e32 v64, v64, v65
	global_store_dword v[66:67], v64, off
.LBB0_573:
	s_or_b64 exec, exec, s[42:43]
	v_add_u32_e32 v64, 0x80, v150
	s_waitcnt lgkmcnt(0)
	v_ashrrev_i32_e32 v65, 31, v64
	v_lshlrev_b64 v[66:67], 11, v[64:65]
	v_lshl_add_u64 v[66:67], s[14:15], 0, v[66:67]
	v_lshl_add_u64 v[70:71], v[148:149], 1, v[66:67]
	s_mov_b64 s[100:101], 0x58000
	v_lshl_add_u64 v[230:231], v[232:233], 0, s[100:101]
	global_load_dwordx4 v[212:215], v[230:231], off
	global_load_dwordx4 v[216:219], v[230:231], off offset:256
	s_waitcnt vmcnt(13)
	v_lshlrev_b32_e32 v72, 16, v188
	v_and_b32_e32 v66, 0xffff0000, v188
	v_lshlrev_b32_e32 v73, 16, v189
	v_and_b32_e32 v67, 0xffff0000, v189
	v_lshlrev_b32_e32 v74, 16, v190
	v_and_b32_e32 v68, 0xffff0000, v190
	v_lshlrev_b32_e32 v75, 16, v191
	v_and_b32_e32 v69, 0xffff0000, v191
	v_add_f32_e32 v72, v60, v72
	v_add_f32_e32 v66, v61, v66
	v_add_f32_e32 v73, v62, v73
	v_add_f32_e32 v67, v63, v67
	v_add_f32_e32 v74, v56, v74
	v_add_f32_e32 v68, v57, v68
	v_add_f32_e32 v75, v58, v75
	v_add_f32_e32 v69, v59, v69
	v_cvt_pk_bf16_f32 v56, v72, v66
	v_cvt_pk_bf16_f32 v57, v73, v67
	v_cvt_pk_bf16_f32 v58, v74, v68
	v_cvt_pk_bf16_f32 v59, v75, v69
	v_mul_f32_e32 v66, v66, v66
	v_mul_f32_e32 v67, v67, v67
	v_mul_f32_e32 v68, v68, v68
	v_mul_f32_e32 v69, v69, v69
	v_fmac_f32_e32 v66, v72, v72
	v_fmac_f32_e32 v67, v73, v73
	v_fmac_f32_e32 v68, v74, v74
	v_fmac_f32_e32 v69, v75, v75
	v_add_f32_e32 v66, v66, v67
	v_add_f32_e32 v67, v68, v69
	v_add_f32_e32 v66, v66, v67
	global_store_dwordx4 v[70:71], v[56:59], off
	s_waitcnt vmcnt(13)
	v_lshlrev_b32_e32 v67, 16, v192
	v_and_b32_e32 v60, 0xffff0000, v192
	v_lshlrev_b32_e32 v68, 16, v193
	v_and_b32_e32 v61, 0xffff0000, v193
	v_lshlrev_b32_e32 v69, 16, v194
	v_and_b32_e32 v62, 0xffff0000, v194
	v_lshlrev_b32_e32 v72, 16, v195
	v_and_b32_e32 v63, 0xffff0000, v195
	v_add_f32_e32 v53, v53, v60
	v_add_f32_e32 v55, v55, v61
	v_add_f32_e32 v61, v49, v62
	v_add_f32_e32 v63, v51, v63
	v_add_f32_e32 v52, v52, v67
	v_add_f32_e32 v54, v54, v68
	v_add_f32_e32 v60, v48, v69
	v_add_f32_e32 v62, v50, v72
	v_mul_f32_e32 v48, v53, v53
	v_mul_f32_e32 v49, v55, v55
	v_mul_f32_e32 v50, v61, v61
	v_mul_f32_e32 v51, v63, v63
	v_fmac_f32_e32 v48, v52, v52
	v_fmac_f32_e32 v49, v54, v54
	v_fmac_f32_e32 v50, v60, v60
	v_fmac_f32_e32 v51, v62, v62
	v_add_f32_e32 v48, v48, v49
	v_add_f32_e32 v49, v50, v51
	v_add_f32_e32 v48, v48, v49
	v_add_f32_e32 v48, v66, v48
	ds_bpermute_b32 v49, v120, v48
	v_cvt_pk_bf16_f32 v50, v52, v53
	v_cvt_pk_bf16_f32 v51, v54, v55
	v_cvt_pk_bf16_f32 v52, v60, v61
	v_cvt_pk_bf16_f32 v53, v62, v63
	s_waitcnt lgkmcnt(0)
	v_add_f32_e32 v48, v48, v49
	ds_bpermute_b32 v49, v114, v48
	global_store_dwordx4 v[70:71], v[50:53], off offset:256
	s_and_saveexec_b64 s[42:43], s[4:5]
	s_cbranch_execz .LBB0_575
	v_lshlrev_b64 v[50:51], 6, v[64:65]
	v_lshl_add_u64 v[50:51], s[18:19], 0, v[50:51]
	v_lshl_add_u64 v[50:51], s[40:41], 2, v[50:51]
	s_lshl_b32 s8, s56, 2
	v_lshl_add_u64 v[50:51], v[50:51], 0, s[8:9]
	s_waitcnt lgkmcnt(0)
	v_add_f32_e32 v48, v48, v49
	global_store_dword v[50:51], v48, off
.LBB0_575:
	s_or_b64 exec, exec, s[42:43]
	v_add_u32_e32 v48, 0x90, v150
	s_waitcnt lgkmcnt(0)
	v_ashrrev_i32_e32 v49, 31, v48
	v_lshlrev_b64 v[50:51], 11, v[48:49]
	v_lshl_add_u64 v[50:51], s[14:15], 0, v[50:51]
	v_lshl_add_u64 v[54:55], v[148:149], 1, v[50:51]
	s_waitcnt vmcnt(11)
	v_lshlrev_b32_e32 v56, 16, v196
	v_and_b32_e32 v50, 0xffff0000, v196
	v_lshlrev_b32_e32 v57, 16, v197
	v_and_b32_e32 v51, 0xffff0000, v197
	v_lshlrev_b32_e32 v58, 16, v198
	v_and_b32_e32 v52, 0xffff0000, v198
	v_lshlrev_b32_e32 v59, 16, v199
	v_and_b32_e32 v53, 0xffff0000, v199
	v_add_f32_e32 v56, v44, v56
	v_add_f32_e32 v50, v45, v50
	v_add_f32_e32 v57, v46, v57
	v_add_f32_e32 v51, v47, v51
	v_add_f32_e32 v58, v40, v58
	v_add_f32_e32 v52, v41, v52
	v_add_f32_e32 v59, v42, v59
	v_add_f32_e32 v53, v43, v53
	v_cvt_pk_bf16_f32 v40, v56, v50
	v_cvt_pk_bf16_f32 v41, v57, v51
	v_cvt_pk_bf16_f32 v42, v58, v52
	v_cvt_pk_bf16_f32 v43, v59, v53
	v_mul_f32_e32 v50, v50, v50
	v_mul_f32_e32 v51, v51, v51
	v_mul_f32_e32 v52, v52, v52
	v_mul_f32_e32 v53, v53, v53
	v_fmac_f32_e32 v50, v56, v56
	v_fmac_f32_e32 v51, v57, v57
	v_fmac_f32_e32 v52, v58, v58
	v_fmac_f32_e32 v53, v59, v59
	v_add_f32_e32 v50, v50, v51
	v_add_f32_e32 v51, v52, v53
	v_add_f32_e32 v50, v50, v51
	global_store_dwordx4 v[54:55], v[40:43], off
	s_waitcnt vmcnt(11)
	v_lshlrev_b32_e32 v51, 16, v200
	v_and_b32_e32 v44, 0xffff0000, v200
	v_lshlrev_b32_e32 v52, 16, v201
	v_and_b32_e32 v45, 0xffff0000, v201
	v_lshlrev_b32_e32 v53, 16, v202
	v_and_b32_e32 v46, 0xffff0000, v202
	v_lshlrev_b32_e32 v56, 16, v203
	v_and_b32_e32 v47, 0xffff0000, v203
	v_add_f32_e32 v37, v37, v44
	v_add_f32_e32 v39, v39, v45
	v_add_f32_e32 v45, v33, v46
	v_add_f32_e32 v47, v35, v47
	v_add_f32_e32 v36, v36, v51
	v_add_f32_e32 v38, v38, v52
	v_add_f32_e32 v44, v32, v53
	v_add_f32_e32 v46, v34, v56
	v_mul_f32_e32 v32, v37, v37
	v_mul_f32_e32 v33, v39, v39
	v_mul_f32_e32 v34, v45, v45
	v_mul_f32_e32 v35, v47, v47
	v_fmac_f32_e32 v32, v36, v36
	v_fmac_f32_e32 v33, v38, v38
	v_fmac_f32_e32 v34, v44, v44
	v_fmac_f32_e32 v35, v46, v46
	v_add_f32_e32 v32, v32, v33
	v_add_f32_e32 v33, v34, v35
	v_add_f32_e32 v32, v32, v33
	v_add_f32_e32 v32, v50, v32
	ds_bpermute_b32 v33, v120, v32
	v_cvt_pk_bf16_f32 v34, v36, v37
	v_cvt_pk_bf16_f32 v35, v38, v39
	v_cvt_pk_bf16_f32 v36, v44, v45
	v_cvt_pk_bf16_f32 v37, v46, v47
	s_waitcnt lgkmcnt(0)
	v_add_f32_e32 v32, v32, v33
	ds_bpermute_b32 v33, v114, v32
	global_store_dwordx4 v[54:55], v[34:37], off offset:256
	s_and_saveexec_b64 s[42:43], s[4:5]
	s_cbranch_execz .LBB0_577
	v_lshlrev_b64 v[34:35], 6, v[48:49]
	v_lshl_add_u64 v[34:35], s[18:19], 0, v[34:35]
	v_lshl_add_u64 v[34:35], s[40:41], 2, v[34:35]
	s_lshl_b32 s8, s56, 2
	v_lshl_add_u64 v[34:35], v[34:35], 0, s[8:9]
	s_waitcnt lgkmcnt(0)
	v_add_f32_e32 v32, v32, v33
	global_store_dword v[34:35], v32, off
.LBB0_577:
	s_or_b64 exec, exec, s[42:43]
	v_add_u32_e32 v32, 0xa0, v150
	s_waitcnt lgkmcnt(0)
	v_ashrrev_i32_e32 v33, 31, v32
	v_lshlrev_b64 v[34:35], 11, v[32:33]
	v_lshl_add_u64 v[34:35], s[14:15], 0, v[34:35]
	v_lshl_add_u64 v[38:39], v[148:149], 1, v[34:35]
	s_waitcnt vmcnt(9)
	v_lshlrev_b32_e32 v40, 16, v204
	v_and_b32_e32 v34, 0xffff0000, v204
	v_lshlrev_b32_e32 v41, 16, v205
	v_and_b32_e32 v35, 0xffff0000, v205
	v_lshlrev_b32_e32 v42, 16, v206
	v_and_b32_e32 v36, 0xffff0000, v206
	v_lshlrev_b32_e32 v43, 16, v207
	v_and_b32_e32 v37, 0xffff0000, v207
	v_add_f32_e32 v40, v28, v40
	v_add_f32_e32 v34, v29, v34
	v_add_f32_e32 v41, v30, v41
	v_add_f32_e32 v35, v31, v35
	v_add_f32_e32 v42, v24, v42
	v_add_f32_e32 v36, v25, v36
	v_add_f32_e32 v43, v26, v43
	v_add_f32_e32 v37, v27, v37
	v_cvt_pk_bf16_f32 v24, v40, v34
	v_cvt_pk_bf16_f32 v25, v41, v35
	v_cvt_pk_bf16_f32 v26, v42, v36
	v_cvt_pk_bf16_f32 v27, v43, v37
	v_mul_f32_e32 v34, v34, v34
	v_mul_f32_e32 v35, v35, v35
	v_mul_f32_e32 v36, v36, v36
	v_mul_f32_e32 v37, v37, v37
	v_fmac_f32_e32 v34, v40, v40
	v_fmac_f32_e32 v35, v41, v41
	v_fmac_f32_e32 v36, v42, v42
	v_fmac_f32_e32 v37, v43, v43
	v_add_f32_e32 v34, v34, v35
	v_add_f32_e32 v35, v36, v37
	v_add_f32_e32 v34, v34, v35
	global_store_dwordx4 v[38:39], v[24:27], off
	s_waitcnt vmcnt(9)
	v_lshlrev_b32_e32 v35, 16, v208
	v_and_b32_e32 v28, 0xffff0000, v208
	v_lshlrev_b32_e32 v36, 16, v209
	v_and_b32_e32 v29, 0xffff0000, v209
	v_lshlrev_b32_e32 v37, 16, v210
	v_and_b32_e32 v30, 0xffff0000, v210
	v_lshlrev_b32_e32 v40, 16, v211
	v_and_b32_e32 v31, 0xffff0000, v211
	v_add_f32_e32 v21, v21, v28
	v_add_f32_e32 v23, v23, v29
	v_add_f32_e32 v29, v17, v30
	v_add_f32_e32 v31, v19, v31
	v_add_f32_e32 v20, v20, v35
	v_add_f32_e32 v22, v22, v36
	v_add_f32_e32 v28, v16, v37
	v_add_f32_e32 v30, v18, v40
	v_mul_f32_e32 v16, v21, v21
	v_mul_f32_e32 v17, v23, v23
	v_mul_f32_e32 v18, v29, v29
	v_mul_f32_e32 v19, v31, v31
	v_fmac_f32_e32 v16, v20, v20
	v_fmac_f32_e32 v17, v22, v22
	v_fmac_f32_e32 v18, v28, v28
	v_fmac_f32_e32 v19, v30, v30
	v_add_f32_e32 v16, v16, v17
	v_add_f32_e32 v17, v18, v19
	v_add_f32_e32 v16, v16, v17
	v_add_f32_e32 v16, v34, v16
	ds_bpermute_b32 v17, v120, v16
	v_cvt_pk_bf16_f32 v18, v20, v21
	v_cvt_pk_bf16_f32 v19, v22, v23
	v_cvt_pk_bf16_f32 v20, v28, v29
	v_cvt_pk_bf16_f32 v21, v30, v31
	s_waitcnt lgkmcnt(0)
	v_add_f32_e32 v16, v16, v17
	ds_bpermute_b32 v17, v114, v16
	global_store_dwordx4 v[38:39], v[18:21], off offset:256
	s_and_saveexec_b64 s[42:43], s[4:5]
	s_cbranch_execz .LBB0_579
	v_lshlrev_b64 v[18:19], 6, v[32:33]
	v_lshl_add_u64 v[18:19], s[18:19], 0, v[18:19]
	v_lshl_add_u64 v[18:19], s[40:41], 2, v[18:19]
	s_lshl_b32 s8, s56, 2
	v_lshl_add_u64 v[18:19], v[18:19], 0, s[8:9]
	s_waitcnt lgkmcnt(0)
	v_add_f32_e32 v16, v16, v17
	global_store_dword v[18:19], v16, off
.LBB0_579:
	s_or_b64 exec, exec, s[42:43]
	v_add_u32_e32 v16, 0xb0, v150
	s_waitcnt lgkmcnt(0)
	v_ashrrev_i32_e32 v17, 31, v16
	v_lshlrev_b64 v[18:19], 11, v[16:17]
	v_lshl_add_u64 v[18:19], s[14:15], 0, v[18:19]
	v_lshl_add_u64 v[22:23], v[148:149], 1, v[18:19]
	s_waitcnt vmcnt(7)
	v_lshlrev_b32_e32 v24, 16, v212
	v_and_b32_e32 v18, 0xffff0000, v212
	v_lshlrev_b32_e32 v25, 16, v213
	v_and_b32_e32 v19, 0xffff0000, v213
	v_lshlrev_b32_e32 v26, 16, v214
	v_and_b32_e32 v20, 0xffff0000, v214
	v_lshlrev_b32_e32 v27, 16, v215
	v_and_b32_e32 v21, 0xffff0000, v215
	v_add_f32_e32 v24, v12, v24
	v_add_f32_e32 v18, v13, v18
	v_add_f32_e32 v25, v14, v25
	v_add_f32_e32 v19, v15, v19
	v_add_f32_e32 v26, v8, v26
	v_add_f32_e32 v20, v9, v20
	v_add_f32_e32 v27, v10, v27
	v_add_f32_e32 v21, v11, v21
	v_cvt_pk_bf16_f32 v8, v24, v18
	v_cvt_pk_bf16_f32 v9, v25, v19
	v_cvt_pk_bf16_f32 v10, v26, v20
	v_cvt_pk_bf16_f32 v11, v27, v21
	v_mul_f32_e32 v18, v18, v18
	v_mul_f32_e32 v19, v19, v19
	v_mul_f32_e32 v20, v20, v20
	v_mul_f32_e32 v21, v21, v21
	v_fmac_f32_e32 v18, v24, v24
	v_fmac_f32_e32 v19, v25, v25
	v_fmac_f32_e32 v20, v26, v26
	v_fmac_f32_e32 v21, v27, v27
	v_add_f32_e32 v18, v18, v19
	v_add_f32_e32 v19, v20, v21
	v_add_f32_e32 v18, v18, v19
	global_store_dwordx4 v[22:23], v[8:11], off
	s_waitcnt vmcnt(7)
	v_lshlrev_b32_e32 v19, 16, v216
	v_and_b32_e32 v12, 0xffff0000, v216
	v_lshlrev_b32_e32 v20, 16, v217
	v_and_b32_e32 v13, 0xffff0000, v217
	v_lshlrev_b32_e32 v21, 16, v218
	v_and_b32_e32 v14, 0xffff0000, v218
	v_lshlrev_b32_e32 v24, 16, v219
	v_and_b32_e32 v15, 0xffff0000, v219
	v_add_f32_e32 v5, v5, v12
	v_add_f32_e32 v7, v7, v13
	v_add_f32_e32 v13, v1, v14
	v_add_f32_e32 v15, v3, v15
	v_add_f32_e32 v4, v4, v19
	v_add_f32_e32 v6, v6, v20
	v_add_f32_e32 v12, v0, v21
	v_add_f32_e32 v14, v2, v24
	v_mul_f32_e32 v0, v5, v5
	v_mul_f32_e32 v1, v7, v7
	v_mul_f32_e32 v2, v13, v13
	v_mul_f32_e32 v3, v15, v15
	v_fmac_f32_e32 v0, v4, v4
	v_fmac_f32_e32 v1, v6, v6
	v_fmac_f32_e32 v2, v12, v12
	v_fmac_f32_e32 v3, v14, v14
	v_add_f32_e32 v0, v0, v1
	v_add_f32_e32 v1, v2, v3
	v_add_f32_e32 v0, v0, v1
	v_add_f32_e32 v0, v18, v0
	ds_bpermute_b32 v1, v120, v0
	v_cvt_pk_bf16_f32 v2, v4, v5
	v_cvt_pk_bf16_f32 v3, v6, v7
	v_cvt_pk_bf16_f32 v4, v12, v13
	v_cvt_pk_bf16_f32 v5, v14, v15
	s_waitcnt lgkmcnt(0)
	v_add_f32_e32 v0, v0, v1
	ds_bpermute_b32 v1, v114, v0
	global_store_dwordx4 v[22:23], v[2:5], off offset:256
	s_and_saveexec_b64 s[42:43], s[4:5]
	s_cbranch_execz .LBB0_581
	v_lshlrev_b64 v[2:3], 6, v[16:17]
	v_lshl_add_u64 v[2:3], s[18:19], 0, v[2:3]
	v_lshl_add_u64 v[2:3], s[40:41], 2, v[2:3]
	s_lshl_b32 s8, s56, 2
	v_lshl_add_u64 v[2:3], v[2:3], 0, s[8:9]
	s_waitcnt lgkmcnt(0)
	v_add_f32_e32 v0, v0, v1
	global_store_dword v[2:3], v0, off

.LBB0_972:
	v_lshl_add_u32 v150, s38, 8, v131
	v_ashrrev_i32_e32 v151, 31, v150
	v_lshl_or_b32 v148, s0, 8, v153
	v_lshlrev_b64 v[160:161], 11, v[150:151]
	v_ashrrev_i32_e32 v149, 31, v148
	v_lshl_add_u64 v[160:161], s[14:15], 0, v[160:161]
	v_lshl_add_u64 v[164:165], v[148:149], 1, v[160:161]
	v_mov_b32_e32 v232, v164
	v_mov_b32_e32 v233, v165
	global_load_dwordx4 v[188:191], v[232:233], off
	global_load_dwordx4 v[192:195], v[232:233], off offset:256
	s_mov_b64 s[100:101], 0x8000
	v_lshl_add_u64 v[230:231], v[232:233], 0, s[100:101]
	global_load_dwordx4 v[196:199], v[230:231], off
	global_load_dwordx4 v[200:203], v[230:231], off offset:256
	s_mov_b64 s[100:101], 0x10000
	v_lshl_add_u64 v[230:231], v[232:233], 0, s[100:101]
	global_load_dwordx4 v[204:207], v[230:231], off
	global_load_dwordx4 v[208:211], v[230:231], off offset:256
	s_mov_b64 s[100:101], 0x18000
	v_lshl_add_u64 v[230:231], v[232:233], 0, s[100:101]
	global_load_dwordx4 v[212:215], v[230:231], off
	global_load_dwordx4 v[216:219], v[230:231], off offset:256
	v_and_b32_e32 v170, 64, v158
	v_add_u32_e32 v170, 64, v170
	v_xor_b32_e32 v171, 32, v158
	s_lshl_b32 s38, s0, 2
	s_ashr_i32 s39, s38, 31
	s_waitcnt vmcnt(7)
	v_lshlrev_b32_e32 v159, 16, v188
	v_and_b32_e32 v160, 0xffff0000, v188
	v_lshlrev_b32_e32 v166, 16, v189
	v_and_b32_e32 v161, 0xffff0000, v189
	v_lshlrev_b32_e32 v167, 16, v190
	v_and_b32_e32 v162, 0xffff0000, v190
	v_lshlrev_b32_e32 v168, 16, v191
	v_and_b32_e32 v163, 0xffff0000, v191
	v_add_f32_e32 v159, v124, v159
	v_add_f32_e32 v169, v125, v160
	v_add_f32_e32 v126, v126, v166
	v_add_f32_e32 v127, v127, v161
	v_add_f32_e32 v166, v120, v167
	v_add_f32_e32 v121, v121, v162
	v_add_f32_e32 v167, v122, v168
	v_add_f32_e32 v168, v123, v163
	v_cvt_pk_bf16_f32 v122, v159, v169
	v_cvt_pk_bf16_f32 v123, v126, v127
	v_cvt_pk_bf16_f32 v124, v166, v121
	v_cvt_pk_bf16_f32 v125, v167, v168
	v_mul_f32_e32 v169, v169, v169
	v_mul_f32_e32 v127, v127, v127
	v_mul_f32_e32 v121, v121, v121
	v_mul_f32_e32 v168, v168, v168
	v_fmac_f32_e32 v169, v159, v159
	v_fmac_f32_e32 v127, v126, v126
	v_fmac_f32_e32 v121, v166, v166
	v_fmac_f32_e32 v168, v167, v167
	v_add_f32_e32 v126, v169, v127
	v_add_f32_e32 v121, v121, v168
	v_add_f32_e32 v121, v126, v121
	v_xor_b32_e32 v120, 16, v158
	v_cmp_lt_i32_e32 vcc, v120, v170
	global_store_dwordx4 v[164:165], v[122:125], off
	s_waitcnt vmcnt(7)
	v_lshlrev_b32_e32 v126, 16, v192
	v_and_b32_e32 v127, 0xffff0000, v192
	v_lshlrev_b32_e32 v159, 16, v193
	v_and_b32_e32 v160, 0xffff0000, v193
	v_lshlrev_b32_e32 v161, 16, v194
	v_and_b32_e32 v162, 0xffff0000, v194
	v_lshlrev_b32_e32 v166, 16, v195
	v_and_b32_e32 v163, 0xffff0000, v195
	v_add_f32_e32 v117, v117, v127
	v_add_f32_e32 v119, v119, v160
	v_add_f32_e32 v127, v113, v162
	v_add_f32_e32 v115, v115, v163
	v_add_f32_e32 v116, v116, v126
	v_add_f32_e32 v118, v118, v159
	v_add_f32_e32 v126, v112, v161
	v_add_f32_e32 v159, v114, v166
	v_mul_f32_e32 v112, v117, v117
	v_mul_f32_e32 v113, v119, v119
	v_mul_f32_e32 v114, v127, v127
	v_mul_f32_e32 v160, v115, v115
	v_fmac_f32_e32 v112, v116, v116
	v_fmac_f32_e32 v113, v118, v118
	v_fmac_f32_e32 v114, v126, v126
	v_fmac_f32_e32 v160, v159, v159
	v_add_f32_e32 v112, v112, v113
	v_add_f32_e32 v113, v114, v160
	v_cndmask_b32_e32 v120, v158, v120, vcc
	v_add_f32_e32 v112, v112, v113
	v_lshlrev_b32_e32 v120, 2, v120
	v_add_f32_e32 v112, v121, v112
	ds_bpermute_b32 v113, v120, v112
	v_cmp_lt_i32_e32 vcc, v171, v170
	v_cvt_pk_bf16_f32 v116, v116, v117
	v_cvt_pk_bf16_f32 v117, v118, v119
	v_cvt_pk_bf16_f32 v118, v126, v127
	s_waitcnt lgkmcnt(0)
	v_add_f32_e32 v112, v112, v113
	v_cvt_pk_bf16_f32 v119, v159, v115
	v_cndmask_b32_e32 v114, v158, v171, vcc
	v_lshlrev_b32_e32 v114, 2, v114
	ds_bpermute_b32 v113, v114, v112
	global_store_dwordx4 v[164:165], v[116:119], off offset:256
	s_and_saveexec_b64 s[40:41], s[4:5]
	s_cbranch_execz .LBB0_974
	v_lshlrev_b64 v[116:117], 6, v[150:151]
	v_lshl_add_u64 v[116:117], s[18:19], 0, v[116:117]
	v_lshl_add_u64 v[116:117], s[38:39], 2, v[116:117]
	s_lshl_b32 s0, s56, 2
	v_lshl_add_u64 v[116:117], v[116:117], 0, s[0:1]
	s_waitcnt lgkmcnt(0)
	v_add_f32_e32 v112, v112, v113
	global_store_dword v[116:117], v112, off
.LBB0_974:
	s_or_b64 exec, exec, s[40:41]
	v_or_b32_e32 v112, 16, v150
	s_waitcnt lgkmcnt(0)
	v_ashrrev_i32_e32 v113, 31, v112
	v_lshlrev_b64 v[116:117], 11, v[112:113]
	v_lshl_add_u64 v[116:117], s[14:15], 0, v[116:117]
	v_lshl_add_u64 v[122:123], v[148:149], 1, v[116:117]
	s_mov_b64 s[100:101], 0x40000
	v_lshl_add_u64 v[230:231], v[232:233], 0, s[100:101]
	global_load_dwordx4 v[188:191], v[230:231], off
	global_load_dwordx4 v[192:195], v[230:231], off offset:256
	s_waitcnt vmcnt(9)
	v_lshlrev_b32_e32 v115, 16, v196
	v_and_b32_e32 v116, 0xffff0000, v196
	v_lshlrev_b32_e32 v121, 16, v197
	v_and_b32_e32 v117, 0xffff0000, v197
	v_lshlrev_b32_e32 v124, 16, v198
	v_and_b32_e32 v118, 0xffff0000, v198
	v_lshlrev_b32_e32 v125, 16, v199
	v_and_b32_e32 v119, 0xffff0000, v199
	v_add_f32_e32 v115, v108, v115
	v_add_f32_e32 v116, v109, v116
	v_add_f32_e32 v121, v110, v121
	v_add_f32_e32 v117, v111, v117
	v_add_f32_e32 v124, v104, v124
	v_add_f32_e32 v118, v105, v118
	v_add_f32_e32 v125, v106, v125
	v_add_f32_e32 v119, v107, v119
	v_cvt_pk_bf16_f32 v104, v115, v116
	v_cvt_pk_bf16_f32 v105, v121, v117
	v_cvt_pk_bf16_f32 v106, v124, v118
	v_cvt_pk_bf16_f32 v107, v125, v119
	v_mul_f32_e32 v116, v116, v116
	v_mul_f32_e32 v117, v117, v117
	v_mul_f32_e32 v118, v118, v118
	v_mul_f32_e32 v119, v119, v119
	v_fmac_f32_e32 v116, v115, v115
	v_fmac_f32_e32 v117, v121, v121
	v_fmac_f32_e32 v118, v124, v124
	v_fmac_f32_e32 v119, v125, v125
	v_add_f32_e32 v115, v116, v117
	v_add_f32_e32 v116, v118, v119
	v_add_f32_e32 v115, v115, v116
	global_store_dwordx4 v[122:123], v[104:107], off
	s_waitcnt vmcnt(9)
	v_lshlrev_b32_e32 v116, 16, v200
	v_and_b32_e32 v108, 0xffff0000, v200
	v_lshlrev_b32_e32 v117, 16, v201
	v_and_b32_e32 v109, 0xffff0000, v201
	v_lshlrev_b32_e32 v118, 16, v202
	v_and_b32_e32 v110, 0xffff0000, v202
	v_lshlrev_b32_e32 v119, 16, v203
	v_and_b32_e32 v111, 0xffff0000, v203
	v_add_f32_e32 v101, v101, v108
	v_add_f32_e32 v103, v103, v109
	v_add_f32_e32 v109, v97, v110
	v_add_f32_e32 v111, v99, v111
	v_add_f32_e32 v100, v100, v116
	v_add_f32_e32 v102, v102, v117
	v_add_f32_e32 v108, v96, v118
	v_add_f32_e32 v110, v98, v119
	v_mul_f32_e32 v96, v101, v101
	v_mul_f32_e32 v97, v103, v103
	v_mul_f32_e32 v98, v109, v109
	v_mul_f32_e32 v99, v111, v111
	v_fmac_f32_e32 v96, v100, v100
	v_fmac_f32_e32 v97, v102, v102
	v_fmac_f32_e32 v98, v108, v108
	v_fmac_f32_e32 v99, v110, v110
	v_add_f32_e32 v96, v96, v97
	v_add_f32_e32 v97, v98, v99
	v_add_f32_e32 v96, v96, v97
	v_add_f32_e32 v96, v115, v96
	ds_bpermute_b32 v97, v120, v96
	v_cvt_pk_bf16_f32 v98, v100, v101
	v_cvt_pk_bf16_f32 v99, v102, v103
	v_cvt_pk_bf16_f32 v100, v108, v109
	v_cvt_pk_bf16_f32 v101, v110, v111
	s_waitcnt lgkmcnt(0)
	v_add_f32_e32 v96, v96, v97
	ds_bpermute_b32 v97, v114, v96
	global_store_dwordx4 v[122:123], v[98:101], off offset:256
	s_and_saveexec_b64 s[40:41], s[4:5]
	s_cbranch_execz .LBB0_976
	v_lshlrev_b64 v[98:99], 6, v[112:113]
	v_lshl_add_u64 v[98:99], s[18:19], 0, v[98:99]
	v_lshl_add_u64 v[98:99], s[38:39], 2, v[98:99]
	s_lshl_b32 s0, s56, 2
	v_lshl_add_u64 v[98:99], v[98:99], 0, s[0:1]
	s_waitcnt lgkmcnt(0)
	v_add_f32_e32 v96, v96, v97
	global_store_dword v[98:99], v96, off
.LBB0_976:
	s_or_b64 exec, exec, s[40:41]
	v_or_b32_e32 v96, 32, v150
	s_waitcnt lgkmcnt(0)
	v_ashrrev_i32_e32 v97, 31, v96
	v_lshlrev_b64 v[98:99], 11, v[96:97]
	v_lshl_add_u64 v[98:99], s[14:15], 0, v[98:99]
	v_lshl_add_u64 v[102:103], v[148:149], 1, v[98:99]
	s_mov_b64 s[100:101], 0x48000
	v_lshl_add_u64 v[230:231], v[232:233], 0, s[100:101]
	global_load_dwordx4 v[196:199], v[230:231], off
	global_load_dwordx4 v[200:203], v[230:231], off offset:256
	s_waitcnt vmcnt(11)
	v_lshlrev_b32_e32 v104, 16, v204
	v_and_b32_e32 v98, 0xffff0000, v204
	v_lshlrev_b32_e32 v105, 16, v205
	v_and_b32_e32 v99, 0xffff0000, v205
	v_lshlrev_b32_e32 v106, 16, v206
	v_and_b32_e32 v100, 0xffff0000, v206
	v_lshlrev_b32_e32 v107, 16, v207
	v_and_b32_e32 v101, 0xffff0000, v207
	v_add_f32_e32 v104, v92, v104
	v_add_f32_e32 v98, v93, v98
	v_add_f32_e32 v105, v94, v105
	v_add_f32_e32 v99, v95, v99
	v_add_f32_e32 v106, v88, v106
	v_add_f32_e32 v100, v89, v100
	v_add_f32_e32 v107, v90, v107
	v_add_f32_e32 v101, v91, v101
	v_cvt_pk_bf16_f32 v88, v104, v98
	v_cvt_pk_bf16_f32 v89, v105, v99
	v_cvt_pk_bf16_f32 v90, v106, v100
	v_cvt_pk_bf16_f32 v91, v107, v101
	v_mul_f32_e32 v98, v98, v98
	v_mul_f32_e32 v99, v99, v99
	v_mul_f32_e32 v100, v100, v100
	v_mul_f32_e32 v101, v101, v101
	v_fmac_f32_e32 v98, v104, v104
	v_fmac_f32_e32 v99, v105, v105
	v_fmac_f32_e32 v100, v106, v106
	v_fmac_f32_e32 v101, v107, v107
	v_add_f32_e32 v98, v98, v99
	v_add_f32_e32 v99, v100, v101
	v_add_f32_e32 v98, v98, v99
	global_store_dwordx4 v[102:103], v[88:91], off
	s_waitcnt vmcnt(11)
	v_lshlrev_b32_e32 v99, 16, v208
	v_and_b32_e32 v92, 0xffff0000, v208
	v_lshlrev_b32_e32 v100, 16, v209
	v_and_b32_e32 v93, 0xffff0000, v209
	v_lshlrev_b32_e32 v101, 16, v210
	v_and_b32_e32 v94, 0xffff0000, v210
	v_lshlrev_b32_e32 v104, 16, v211
	v_and_b32_e32 v95, 0xffff0000, v211
	v_add_f32_e32 v85, v85, v92
	v_add_f32_e32 v87, v87, v93
	v_add_f32_e32 v93, v81, v94
	v_add_f32_e32 v95, v83, v95
	v_add_f32_e32 v84, v84, v99
	v_add_f32_e32 v86, v86, v100
	v_add_f32_e32 v92, v80, v101
	v_add_f32_e32 v94, v82, v104
	v_mul_f32_e32 v80, v85, v85
	v_mul_f32_e32 v81, v87, v87
	v_mul_f32_e32 v82, v93, v93
	v_mul_f32_e32 v83, v95, v95
	v_fmac_f32_e32 v80, v84, v84
	v_fmac_f32_e32 v81, v86, v86
	v_fmac_f32_e32 v82, v92, v92
	v_fmac_f32_e32 v83, v94, v94
	v_add_f32_e32 v80, v80, v81
	v_add_f32_e32 v81, v82, v83
	v_add_f32_e32 v80, v80, v81
	v_add_f32_e32 v80, v98, v80
	ds_bpermute_b32 v81, v120, v80
	v_cvt_pk_bf16_f32 v82, v84, v85
	v_cvt_pk_bf16_f32 v83, v86, v87
	v_cvt_pk_bf16_f32 v84, v92, v93
	v_cvt_pk_bf16_f32 v85, v94, v95
	s_waitcnt lgkmcnt(0)
	v_add_f32_e32 v80, v80, v81
	ds_bpermute_b32 v81, v114, v80
	global_store_dwordx4 v[102:103], v[82:85], off offset:256
	s_and_saveexec_b64 s[40:41], s[4:5]
	s_cbranch_execz .LBB0_978
	v_lshlrev_b64 v[82:83], 6, v[96:97]
	v_lshl_add_u64 v[82:83], s[18:19], 0, v[82:83]
	v_lshl_add_u64 v[82:83], s[38:39], 2, v[82:83]
	s_lshl_b32 s0, s56, 2
	v_lshl_add_u64 v[82:83], v[82:83], 0, s[0:1]
	s_waitcnt lgkmcnt(0)
	v_add_f32_e32 v80, v80, v81
	global_store_dword v[82:83], v80, off
.LBB0_978:
	s_or_b64 exec, exec, s[40:41]
	v_or_b32_e32 v80, 48, v150
	s_waitcnt lgkmcnt(0)
	v_ashrrev_i32_e32 v81, 31, v80
	v_lshlrev_b64 v[82:83], 11, v[80:81]
	v_lshl_add_u64 v[82:83], s[14:15], 0, v[82:83]
	v_lshl_add_u64 v[86:87], v[148:149], 1, v[82:83]
	s_mov_b64 s[100:101], 0x50000
	v_lshl_add_u64 v[230:231], v[232:233], 0, s[100:101]
	global_load_dwordx4 v[204:207], v[230:231], off
	global_load_dwordx4 v[208:211], v[230:231], off offset:256
	s_waitcnt vmcnt(13)
	v_lshlrev_b32_e32 v88, 16, v212
	v_and_b32_e32 v82, 0xffff0000, v212
	v_lshlrev_b32_e32 v89, 16, v213
	v_and_b32_e32 v83, 0xffff0000, v213
	v_lshlrev_b32_e32 v90, 16, v214
	v_and_b32_e32 v84, 0xffff0000, v214
	v_lshlrev_b32_e32 v91, 16, v215
	v_and_b32_e32 v85, 0xffff0000, v215
	v_add_f32_e32 v88, v76, v88
	v_add_f32_e32 v82, v77, v82
	v_add_f32_e32 v89, v78, v89
	v_add_f32_e32 v83, v79, v83
	v_add_f32_e32 v90, v72, v90
	v_add_f32_e32 v84, v73, v84
	v_add_f32_e32 v91, v74, v91
	v_add_f32_e32 v85, v75, v85
	v_cvt_pk_bf16_f32 v72, v88, v82
	v_cvt_pk_bf16_f32 v73, v89, v83
	v_cvt_pk_bf16_f32 v74, v90, v84
	v_cvt_pk_bf16_f32 v75, v91, v85
	v_mul_f32_e32 v82, v82, v82
	v_mul_f32_e32 v83, v83, v83
	v_mul_f32_e32 v84, v84, v84
	v_mul_f32_e32 v85, v85, v85
	v_fmac_f32_e32 v82, v88, v88
	v_fmac_f32_e32 v83, v89, v89
	v_fmac_f32_e32 v84, v90, v90
	v_fmac_f32_e32 v85, v91, v91
	v_add_f32_e32 v82, v82, v83
	v_add_f32_e32 v83, v84, v85
	v_add_f32_e32 v82, v82, v83
	global_store_dwordx4 v[86:87], v[72:75], off
	s_waitcnt vmcnt(13)
	v_lshlrev_b32_e32 v83, 16, v216
	v_and_b32_e32 v76, 0xffff0000, v216
	v_lshlrev_b32_e32 v84, 16, v217
	v_and_b32_e32 v77, 0xffff0000, v217
	v_lshlrev_b32_e32 v85, 16, v218
	v_and_b32_e32 v78, 0xffff0000, v218
	v_lshlrev_b32_e32 v88, 16, v219
	v_and_b32_e32 v79, 0xffff0000, v219
	v_add_f32_e32 v69, v69, v76
	v_add_f32_e32 v71, v71, v77
	v_add_f32_e32 v77, v65, v78
	v_add_f32_e32 v79, v67, v79
	v_add_f32_e32 v68, v68, v83
	v_add_f32_e32 v70, v70, v84
	v_add_f32_e32 v76, v64, v85
	v_add_f32_e32 v78, v66, v88
	v_mul_f32_e32 v64, v69, v69
	v_mul_f32_e32 v65, v71, v71
	v_mul_f32_e32 v66, v77, v77
	v_mul_f32_e32 v67, v79, v79
	v_fmac_f32_e32 v64, v68, v68
	v_fmac_f32_e32 v65, v70, v70
	v_fmac_f32_e32 v66, v76, v76
	v_fmac_f32_e32 v67, v78, v78
	v_add_f32_e32 v64, v64, v65
	v_add_f32_e32 v65, v66, v67
	v_add_f32_e32 v64, v64, v65
	v_add_f32_e32 v64, v82, v64
	ds_bpermute_b32 v65, v120, v64
	v_cvt_pk_bf16_f32 v66, v68, v69
	v_cvt_pk_bf16_f32 v67, v70, v71
	v_cvt_pk_bf16_f32 v68, v76, v77
	v_cvt_pk_bf16_f32 v69, v78, v79
	s_waitcnt lgkmcnt(0)
	v_add_f32_e32 v64, v64, v65
	ds_bpermute_b32 v65, v114, v64
	global_store_dwordx4 v[86:87], v[66:69], off offset:256
	s_and_saveexec_b64 s[40:41], s[4:5]
	s_cbranch_execz .LBB0_980
	v_lshlrev_b64 v[66:67], 6, v[80:81]
	v_lshl_add_u64 v[66:67], s[18:19], 0, v[66:67]
	v_lshl_add_u64 v[66:67], s[38:39], 2, v[66:67]
	s_lshl_b32 s0, s56, 2
	v_lshl_add_u64 v[66:67], v[66:67], 0, s[0:1]
	s_waitcnt lgkmcnt(0)
	v_add_f32_e32 v64, v64, v65
	global_store_dword v[66:67], v64, off
.LBB0_980:
	s_or_b64 exec, exec, s[40:41]
	v_add_u32_e32 v64, 0x80, v150
	s_waitcnt lgkmcnt(0)
	v_ashrrev_i32_e32 v65, 31, v64
	v_lshlrev_b64 v[66:67], 11, v[64:65]
	v_lshl_add_u64 v[66:67], s[14:15], 0, v[66:67]
	v_lshl_add_u64 v[70:71], v[148:149], 1, v[66:67]
	s_mov_b64 s[100:101], 0x58000
	v_lshl_add_u64 v[230:231], v[232:233], 0, s[100:101]
	global_load_dwordx4 v[212:215], v[230:231], off
	global_load_dwordx4 v[216:219], v[230:231], off offset:256
	s_waitcnt vmcnt(13)
	v_lshlrev_b32_e32 v72, 16, v188
	v_and_b32_e32 v66, 0xffff0000, v188
	v_lshlrev_b32_e32 v73, 16, v189
	v_and_b32_e32 v67, 0xffff0000, v189
	v_lshlrev_b32_e32 v74, 16, v190
	v_and_b32_e32 v68, 0xffff0000, v190
	v_lshlrev_b32_e32 v75, 16, v191
	v_and_b32_e32 v69, 0xffff0000, v191
	v_add_f32_e32 v72, v60, v72
	v_add_f32_e32 v66, v61, v66
	v_add_f32_e32 v73, v62, v73
	v_add_f32_e32 v67, v63, v67
	v_add_f32_e32 v74, v56, v74
	v_add_f32_e32 v68, v57, v68
	v_add_f32_e32 v75, v58, v75
	v_add_f32_e32 v69, v59, v69
	v_cvt_pk_bf16_f32 v56, v72, v66
	v_cvt_pk_bf16_f32 v57, v73, v67
	v_cvt_pk_bf16_f32 v58, v74, v68
	v_cvt_pk_bf16_f32 v59, v75, v69
	v_mul_f32_e32 v66, v66, v66
	v_mul_f32_e32 v67, v67, v67
	v_mul_f32_e32 v68, v68, v68
	v_mul_f32_e32 v69, v69, v69
	v_fmac_f32_e32 v66, v72, v72
	v_fmac_f32_e32 v67, v73, v73
	v_fmac_f32_e32 v68, v74, v74
	v_fmac_f32_e32 v69, v75, v75
	v_add_f32_e32 v66, v66, v67
	v_add_f32_e32 v67, v68, v69
	v_add_f32_e32 v66, v66, v67
	global_store_dwordx4 v[70:71], v[56:59], off
	s_waitcnt vmcnt(13)
	v_lshlrev_b32_e32 v67, 16, v192
	v_and_b32_e32 v60, 0xffff0000, v192
	v_lshlrev_b32_e32 v68, 16, v193
	v_and_b32_e32 v61, 0xffff0000, v193
	v_lshlrev_b32_e32 v69, 16, v194
	v_and_b32_e32 v62, 0xffff0000, v194
	v_lshlrev_b32_e32 v72, 16, v195
	v_and_b32_e32 v63, 0xffff0000, v195
	v_add_f32_e32 v53, v53, v60
	v_add_f32_e32 v55, v55, v61
	v_add_f32_e32 v61, v49, v62
	v_add_f32_e32 v63, v51, v63
	v_add_f32_e32 v52, v52, v67
	v_add_f32_e32 v54, v54, v68
	v_add_f32_e32 v60, v48, v69
	v_add_f32_e32 v62, v50, v72
	v_mul_f32_e32 v48, v53, v53
	v_mul_f32_e32 v49, v55, v55
	v_mul_f32_e32 v50, v61, v61
	v_mul_f32_e32 v51, v63, v63
	v_fmac_f32_e32 v48, v52, v52
	v_fmac_f32_e32 v49, v54, v54
	v_fmac_f32_e32 v50, v60, v60
	v_fmac_f32_e32 v51, v62, v62
	v_add_f32_e32 v48, v48, v49
	v_add_f32_e32 v49, v50, v51
	v_add_f32_e32 v48, v48, v49
	v_add_f32_e32 v48, v66, v48
	ds_bpermute_b32 v49, v120, v48
	v_cvt_pk_bf16_f32 v50, v52, v53
	v_cvt_pk_bf16_f32 v51, v54, v55
	v_cvt_pk_bf16_f32 v52, v60, v61
	v_cvt_pk_bf16_f32 v53, v62, v63
	s_waitcnt lgkmcnt(0)
	v_add_f32_e32 v48, v48, v49
	ds_bpermute_b32 v49, v114, v48
	global_store_dwordx4 v[70:71], v[50:53], off offset:256
	s_and_saveexec_b64 s[40:41], s[4:5]
	s_cbranch_execz .LBB0_982
	v_lshlrev_b64 v[50:51], 6, v[64:65]
	v_lshl_add_u64 v[50:51], s[18:19], 0, v[50:51]
	v_lshl_add_u64 v[50:51], s[38:39], 2, v[50:51]
	s_lshl_b32 s0, s56, 2
	v_lshl_add_u64 v[50:51], v[50:51], 0, s[0:1]
	s_waitcnt lgkmcnt(0)
	v_add_f32_e32 v48, v48, v49
	global_store_dword v[50:51], v48, off
.LBB0_982:
	s_or_b64 exec, exec, s[40:41]
	v_add_u32_e32 v48, 0x90, v150
	s_waitcnt lgkmcnt(0)
	v_ashrrev_i32_e32 v49, 31, v48
	v_lshlrev_b64 v[50:51], 11, v[48:49]
	v_lshl_add_u64 v[50:51], s[14:15], 0, v[50:51]
	v_lshl_add_u64 v[54:55], v[148:149], 1, v[50:51]
	s_waitcnt vmcnt(11)
	v_lshlrev_b32_e32 v56, 16, v196
	v_and_b32_e32 v50, 0xffff0000, v196
	v_lshlrev_b32_e32 v57, 16, v197
	v_and_b32_e32 v51, 0xffff0000, v197
	v_lshlrev_b32_e32 v58, 16, v198
	v_and_b32_e32 v52, 0xffff0000, v198
	v_lshlrev_b32_e32 v59, 16, v199
	v_and_b32_e32 v53, 0xffff0000, v199
	v_add_f32_e32 v56, v44, v56
	v_add_f32_e32 v50, v45, v50
	v_add_f32_e32 v57, v46, v57
	v_add_f32_e32 v51, v47, v51
	v_add_f32_e32 v58, v40, v58
	v_add_f32_e32 v52, v41, v52
	v_add_f32_e32 v59, v42, v59
	v_add_f32_e32 v53, v43, v53
	v_cvt_pk_bf16_f32 v40, v56, v50
	v_cvt_pk_bf16_f32 v41, v57, v51
	v_cvt_pk_bf16_f32 v42, v58, v52
	v_cvt_pk_bf16_f32 v43, v59, v53
	v_mul_f32_e32 v50, v50, v50
	v_mul_f32_e32 v51, v51, v51
	v_mul_f32_e32 v52, v52, v52
	v_mul_f32_e32 v53, v53, v53
	v_fmac_f32_e32 v50, v56, v56
	v_fmac_f32_e32 v51, v57, v57
	v_fmac_f32_e32 v52, v58, v58
	v_fmac_f32_e32 v53, v59, v59
	v_add_f32_e32 v50, v50, v51
	v_add_f32_e32 v51, v52, v53
	v_add_f32_e32 v50, v50, v51
	global_store_dwordx4 v[54:55], v[40:43], off
	s_waitcnt vmcnt(11)
	v_lshlrev_b32_e32 v51, 16, v200
	v_and_b32_e32 v44, 0xffff0000, v200
	v_lshlrev_b32_e32 v52, 16, v201
	v_and_b32_e32 v45, 0xffff0000, v201
	v_lshlrev_b32_e32 v53, 16, v202
	v_and_b32_e32 v46, 0xffff0000, v202
	v_lshlrev_b32_e32 v56, 16, v203
	v_and_b32_e32 v47, 0xffff0000, v203
	v_add_f32_e32 v37, v37, v44
	v_add_f32_e32 v39, v39, v45
	v_add_f32_e32 v45, v33, v46
	v_add_f32_e32 v47, v35, v47
	v_add_f32_e32 v36, v36, v51
	v_add_f32_e32 v38, v38, v52
	v_add_f32_e32 v44, v32, v53
	v_add_f32_e32 v46, v34, v56
	v_mul_f32_e32 v32, v37, v37
	v_mul_f32_e32 v33, v39, v39
	v_mul_f32_e32 v34, v45, v45
	v_mul_f32_e32 v35, v47, v47
	v_fmac_f32_e32 v32, v36, v36
	v_fmac_f32_e32 v33, v38, v38
	v_fmac_f32_e32 v34, v44, v44
	v_fmac_f32_e32 v35, v46, v46
	v_add_f32_e32 v32, v32, v33
	v_add_f32_e32 v33, v34, v35
	v_add_f32_e32 v32, v32, v33
	v_add_f32_e32 v32, v50, v32
	ds_bpermute_b32 v33, v120, v32
	v_cvt_pk_bf16_f32 v34, v36, v37
	v_cvt_pk_bf16_f32 v35, v38, v39
	v_cvt_pk_bf16_f32 v36, v44, v45
	v_cvt_pk_bf16_f32 v37, v46, v47
	s_waitcnt lgkmcnt(0)
	v_add_f32_e32 v32, v32, v33
	ds_bpermute_b32 v33, v114, v32
	global_store_dwordx4 v[54:55], v[34:37], off offset:256
	s_and_saveexec_b64 s[40:41], s[4:5]
	s_cbranch_execz .LBB0_984
	v_lshlrev_b64 v[34:35], 6, v[48:49]
	v_lshl_add_u64 v[34:35], s[18:19], 0, v[34:35]
	v_lshl_add_u64 v[34:35], s[38:39], 2, v[34:35]
	s_lshl_b32 s0, s56, 2
	v_lshl_add_u64 v[34:35], v[34:35], 0, s[0:1]
	s_waitcnt lgkmcnt(0)
	v_add_f32_e32 v32, v32, v33
	global_store_dword v[34:35], v32, off
.LBB0_984:
	s_or_b64 exec, exec, s[40:41]
	v_add_u32_e32 v32, 0xa0, v150
	s_waitcnt lgkmcnt(0)
	v_ashrrev_i32_e32 v33, 31, v32
	v_lshlrev_b64 v[34:35], 11, v[32:33]
	v_lshl_add_u64 v[34:35], s[14:15], 0, v[34:35]
	v_lshl_add_u64 v[38:39], v[148:149], 1, v[34:35]
	s_waitcnt vmcnt(9)
	v_lshlrev_b32_e32 v40, 16, v204
	v_and_b32_e32 v34, 0xffff0000, v204
	v_lshlrev_b32_e32 v41, 16, v205
	v_and_b32_e32 v35, 0xffff0000, v205
	v_lshlrev_b32_e32 v42, 16, v206
	v_and_b32_e32 v36, 0xffff0000, v206
	v_lshlrev_b32_e32 v43, 16, v207
	v_and_b32_e32 v37, 0xffff0000, v207
	v_add_f32_e32 v40, v28, v40
	v_add_f32_e32 v34, v29, v34
	v_add_f32_e32 v41, v30, v41
	v_add_f32_e32 v35, v31, v35
	v_add_f32_e32 v42, v24, v42
	v_add_f32_e32 v36, v25, v36
	v_add_f32_e32 v43, v26, v43
	v_add_f32_e32 v37, v27, v37
	v_cvt_pk_bf16_f32 v24, v40, v34
	v_cvt_pk_bf16_f32 v25, v41, v35
	v_cvt_pk_bf16_f32 v26, v42, v36
	v_cvt_pk_bf16_f32 v27, v43, v37
	v_mul_f32_e32 v34, v34, v34
	v_mul_f32_e32 v35, v35, v35
	v_mul_f32_e32 v36, v36, v36
	v_mul_f32_e32 v37, v37, v37
	v_fmac_f32_e32 v34, v40, v40
	v_fmac_f32_e32 v35, v41, v41
	v_fmac_f32_e32 v36, v42, v42
	v_fmac_f32_e32 v37, v43, v43
	v_add_f32_e32 v34, v34, v35
	v_add_f32_e32 v35, v36, v37
	v_add_f32_e32 v34, v34, v35
	global_store_dwordx4 v[38:39], v[24:27], off
	s_waitcnt vmcnt(9)
	v_lshlrev_b32_e32 v35, 16, v208
	v_and_b32_e32 v28, 0xffff0000, v208
	v_lshlrev_b32_e32 v36, 16, v209
	v_and_b32_e32 v29, 0xffff0000, v209
	v_lshlrev_b32_e32 v37, 16, v210
	v_and_b32_e32 v30, 0xffff0000, v210
	v_lshlrev_b32_e32 v40, 16, v211
	v_and_b32_e32 v31, 0xffff0000, v211
	v_add_f32_e32 v21, v21, v28
	v_add_f32_e32 v23, v23, v29
	v_add_f32_e32 v29, v17, v30
	v_add_f32_e32 v31, v19, v31
	v_add_f32_e32 v20, v20, v35
	v_add_f32_e32 v22, v22, v36
	v_add_f32_e32 v28, v16, v37
	v_add_f32_e32 v30, v18, v40
	v_mul_f32_e32 v16, v21, v21
	v_mul_f32_e32 v17, v23, v23
	v_mul_f32_e32 v18, v29, v29
	v_mul_f32_e32 v19, v31, v31
	v_fmac_f32_e32 v16, v20, v20
	v_fmac_f32_e32 v17, v22, v22
	v_fmac_f32_e32 v18, v28, v28
	v_fmac_f32_e32 v19, v30, v30
	v_add_f32_e32 v16, v16, v17
	v_add_f32_e32 v17, v18, v19
	v_add_f32_e32 v16, v16, v17
	v_add_f32_e32 v16, v34, v16
	ds_bpermute_b32 v17, v120, v16
	v_cvt_pk_bf16_f32 v18, v20, v21
	v_cvt_pk_bf16_f32 v19, v22, v23
	v_cvt_pk_bf16_f32 v20, v28, v29
	v_cvt_pk_bf16_f32 v21, v30, v31
	s_waitcnt lgkmcnt(0)
	v_add_f32_e32 v16, v16, v17
	ds_bpermute_b32 v17, v114, v16
	global_store_dwordx4 v[38:39], v[18:21], off offset:256
	s_and_saveexec_b64 s[40:41], s[4:5]
	s_cbranch_execz .LBB0_986
	v_lshlrev_b64 v[18:19], 6, v[32:33]
	v_lshl_add_u64 v[18:19], s[18:19], 0, v[18:19]
	v_lshl_add_u64 v[18:19], s[38:39], 2, v[18:19]
	s_lshl_b32 s0, s56, 2
	v_lshl_add_u64 v[18:19], v[18:19], 0, s[0:1]
	s_waitcnt lgkmcnt(0)
	v_add_f32_e32 v16, v16, v17
	global_store_dword v[18:19], v16, off
.LBB0_986:
	s_or_b64 exec, exec, s[40:41]
	v_add_u32_e32 v16, 0xb0, v150
	s_waitcnt lgkmcnt(0)
	v_ashrrev_i32_e32 v17, 31, v16
	v_lshlrev_b64 v[18:19], 11, v[16:17]
	v_lshl_add_u64 v[18:19], s[14:15], 0, v[18:19]
	v_lshl_add_u64 v[22:23], v[148:149], 1, v[18:19]
	s_waitcnt vmcnt(7)
	v_lshlrev_b32_e32 v24, 16, v212
	v_and_b32_e32 v18, 0xffff0000, v212
	v_lshlrev_b32_e32 v25, 16, v213
	v_and_b32_e32 v19, 0xffff0000, v213
	v_lshlrev_b32_e32 v26, 16, v214
	v_and_b32_e32 v20, 0xffff0000, v214
	v_lshlrev_b32_e32 v27, 16, v215
	v_and_b32_e32 v21, 0xffff0000, v215
	v_add_f32_e32 v24, v12, v24
	v_add_f32_e32 v18, v13, v18
	v_add_f32_e32 v25, v14, v25
	v_add_f32_e32 v19, v15, v19
	v_add_f32_e32 v26, v8, v26
	v_add_f32_e32 v20, v9, v20
	v_add_f32_e32 v27, v10, v27
	v_add_f32_e32 v21, v11, v21
	v_cvt_pk_bf16_f32 v8, v24, v18
	v_cvt_pk_bf16_f32 v9, v25, v19
	v_cvt_pk_bf16_f32 v10, v26, v20
	v_cvt_pk_bf16_f32 v11, v27, v21
	v_mul_f32_e32 v18, v18, v18
	v_mul_f32_e32 v19, v19, v19
	v_mul_f32_e32 v20, v20, v20
	v_mul_f32_e32 v21, v21, v21
	v_fmac_f32_e32 v18, v24, v24
	v_fmac_f32_e32 v19, v25, v25
	v_fmac_f32_e32 v20, v26, v26
	v_fmac_f32_e32 v21, v27, v27
	v_add_f32_e32 v18, v18, v19
	v_add_f32_e32 v19, v20, v21
	v_add_f32_e32 v18, v18, v19
	global_store_dwordx4 v[22:23], v[8:11], off
	s_waitcnt vmcnt(7)
	v_lshlrev_b32_e32 v19, 16, v216
	v_and_b32_e32 v12, 0xffff0000, v216
	v_lshlrev_b32_e32 v20, 16, v217
	v_and_b32_e32 v13, 0xffff0000, v217
	v_lshlrev_b32_e32 v21, 16, v218
	v_and_b32_e32 v14, 0xffff0000, v218
	v_lshlrev_b32_e32 v24, 16, v219
	v_and_b32_e32 v15, 0xffff0000, v219
	v_add_f32_e32 v5, v5, v12
	v_add_f32_e32 v7, v7, v13
	v_add_f32_e32 v13, v1, v14
	v_add_f32_e32 v15, v3, v15
	v_add_f32_e32 v4, v4, v19
	v_add_f32_e32 v6, v6, v20
	v_add_f32_e32 v12, v0, v21
	v_add_f32_e32 v14, v2, v24
	v_mul_f32_e32 v0, v5, v5
	v_mul_f32_e32 v1, v7, v7
	v_mul_f32_e32 v2, v13, v13
	v_mul_f32_e32 v3, v15, v15
	v_fmac_f32_e32 v0, v4, v4
	v_fmac_f32_e32 v1, v6, v6
	v_fmac_f32_e32 v2, v12, v12
	v_fmac_f32_e32 v3, v14, v14
	v_add_f32_e32 v0, v0, v1
	v_add_f32_e32 v1, v2, v3
	v_add_f32_e32 v0, v0, v1
	v_add_f32_e32 v0, v18, v0
	ds_bpermute_b32 v1, v120, v0
	v_cvt_pk_bf16_f32 v2, v4, v5
	v_cvt_pk_bf16_f32 v3, v6, v7
	v_cvt_pk_bf16_f32 v4, v12, v13
	v_cvt_pk_bf16_f32 v5, v14, v15
	s_waitcnt lgkmcnt(0)
	v_add_f32_e32 v0, v0, v1
	ds_bpermute_b32 v1, v114, v0
	global_store_dwordx4 v[22:23], v[2:5], off offset:256
	s_and_saveexec_b64 s[40:41], s[4:5]
	s_cbranch_execz .LBB0_988
	v_lshlrev_b64 v[2:3], 6, v[16:17]
	v_lshl_add_u64 v[2:3], s[18:19], 0, v[2:3]
	v_lshl_add_u64 v[2:3], s[38:39], 2, v[2:3]
	s_lshl_b32 s0, s56, 2
	v_lshl_add_u64 v[2:3], v[2:3], 0, s[0:1]
	s_waitcnt lgkmcnt(0)
	v_add_f32_e32 v0, v0, v1
	global_store_dword v[2:3], v0, off

.LBB0_1148:
	v_lshl_add_u32 v150, s12, 8, v131
	v_ashrrev_i32_e32 v151, 31, v150
	v_lshl_or_b32 v148, s8, 8, v153
	v_lshlrev_b64 v[160:161], 11, v[150:151]
	v_ashrrev_i32_e32 v149, 31, v148
	v_lshl_add_u64 v[160:161], s[14:15], 0, v[160:161]
	v_lshl_add_u64 v[164:165], v[148:149], 1, v[160:161]
	v_mov_b32_e32 v232, v164
	v_mov_b32_e32 v233, v165
	global_load_dwordx4 v[188:191], v[232:233], off
	global_load_dwordx4 v[192:195], v[232:233], off offset:256
	s_mov_b64 s[100:101], 0x8000
	v_lshl_add_u64 v[230:231], v[232:233], 0, s[100:101]
	global_load_dwordx4 v[196:199], v[230:231], off
	global_load_dwordx4 v[200:203], v[230:231], off offset:256
	s_mov_b64 s[100:101], 0x10000
	v_lshl_add_u64 v[230:231], v[232:233], 0, s[100:101]
	global_load_dwordx4 v[204:207], v[230:231], off
	global_load_dwordx4 v[208:211], v[230:231], off offset:256
	s_mov_b64 s[100:101], 0x18000
	v_lshl_add_u64 v[230:231], v[232:233], 0, s[100:101]
	global_load_dwordx4 v[212:215], v[230:231], off
	global_load_dwordx4 v[216:219], v[230:231], off offset:256
	v_and_b32_e32 v170, 64, v158
	v_add_u32_e32 v170, 64, v170
	v_xor_b32_e32 v171, 32, v158
	s_lshl_b32 s30, s8, 2
	s_ashr_i32 s31, s30, 31
	s_waitcnt vmcnt(7)
	v_lshlrev_b32_e32 v159, 16, v188
	v_and_b32_e32 v160, 0xffff0000, v188
	v_lshlrev_b32_e32 v166, 16, v189
	v_and_b32_e32 v161, 0xffff0000, v189
	v_lshlrev_b32_e32 v167, 16, v190
	v_and_b32_e32 v162, 0xffff0000, v190
	v_lshlrev_b32_e32 v168, 16, v191
	v_and_b32_e32 v163, 0xffff0000, v191
	v_add_f32_e32 v159, v124, v159
	v_add_f32_e32 v169, v125, v160
	v_add_f32_e32 v126, v126, v166
	v_add_f32_e32 v127, v127, v161
	v_add_f32_e32 v166, v120, v167
	v_add_f32_e32 v121, v121, v162
	v_add_f32_e32 v167, v122, v168
	v_add_f32_e32 v168, v123, v163
	v_cvt_pk_bf16_f32 v122, v159, v169
	v_cvt_pk_bf16_f32 v123, v126, v127
	v_cvt_pk_bf16_f32 v124, v166, v121
	v_cvt_pk_bf16_f32 v125, v167, v168
	v_mul_f32_e32 v169, v169, v169
	v_mul_f32_e32 v127, v127, v127
	v_mul_f32_e32 v121, v121, v121
	v_mul_f32_e32 v168, v168, v168
	v_fmac_f32_e32 v169, v159, v159
	v_fmac_f32_e32 v127, v126, v126
	v_fmac_f32_e32 v121, v166, v166
	v_fmac_f32_e32 v168, v167, v167
	v_add_f32_e32 v126, v169, v127
	v_add_f32_e32 v121, v121, v168
	v_add_f32_e32 v121, v126, v121
	v_xor_b32_e32 v120, 16, v158
	v_cmp_lt_i32_e32 vcc, v120, v170
	global_store_dwordx4 v[164:165], v[122:125], off
	s_waitcnt vmcnt(7)
	v_lshlrev_b32_e32 v126, 16, v192
	v_and_b32_e32 v127, 0xffff0000, v192
	v_lshlrev_b32_e32 v159, 16, v193
	v_and_b32_e32 v160, 0xffff0000, v193
	v_lshlrev_b32_e32 v161, 16, v194
	v_and_b32_e32 v162, 0xffff0000, v194
	v_lshlrev_b32_e32 v166, 16, v195
	v_and_b32_e32 v163, 0xffff0000, v195
	v_add_f32_e32 v117, v117, v127
	v_add_f32_e32 v119, v119, v160
	v_add_f32_e32 v127, v113, v162
	v_add_f32_e32 v115, v115, v163
	v_add_f32_e32 v116, v116, v126
	v_add_f32_e32 v118, v118, v159
	v_add_f32_e32 v126, v112, v161
	v_add_f32_e32 v159, v114, v166
	v_mul_f32_e32 v112, v117, v117
	v_mul_f32_e32 v113, v119, v119
	v_mul_f32_e32 v114, v127, v127
	v_mul_f32_e32 v160, v115, v115
	v_fmac_f32_e32 v112, v116, v116
	v_fmac_f32_e32 v113, v118, v118
	v_fmac_f32_e32 v114, v126, v126
	v_fmac_f32_e32 v160, v159, v159
	v_add_f32_e32 v112, v112, v113
	v_add_f32_e32 v113, v114, v160
	v_cndmask_b32_e32 v120, v158, v120, vcc
	v_add_f32_e32 v112, v112, v113
	v_lshlrev_b32_e32 v120, 2, v120
	v_add_f32_e32 v112, v121, v112
	ds_bpermute_b32 v113, v120, v112
	v_cmp_lt_i32_e32 vcc, v171, v170
	v_cvt_pk_bf16_f32 v116, v116, v117
	v_cvt_pk_bf16_f32 v117, v118, v119
	v_cvt_pk_bf16_f32 v118, v126, v127
	s_waitcnt lgkmcnt(0)
	v_add_f32_e32 v112, v112, v113
	v_cvt_pk_bf16_f32 v119, v159, v115
	v_cndmask_b32_e32 v114, v158, v171, vcc
	v_lshlrev_b32_e32 v114, 2, v114
	ds_bpermute_b32 v113, v114, v112
	global_store_dwordx4 v[164:165], v[116:119], off offset:256
	s_and_saveexec_b64 s[36:37], s[4:5]
	s_cbranch_execz .LBB0_1150
	v_lshlrev_b64 v[116:117], 6, v[150:151]
	v_lshl_add_u64 v[116:117], s[18:19], 0, v[116:117]
	v_lshl_add_u64 v[116:117], s[30:31], 2, v[116:117]
	s_lshl_b32 s8, s50, 2
	v_lshl_add_u64 v[116:117], v[116:117], 0, s[8:9]
	s_waitcnt lgkmcnt(0)
	v_add_f32_e32 v112, v112, v113
	global_store_dword v[116:117], v112, off
.LBB0_1150:
	s_or_b64 exec, exec, s[36:37]
	v_or_b32_e32 v112, 16, v150
	s_waitcnt lgkmcnt(0)
	v_ashrrev_i32_e32 v113, 31, v112
	v_lshlrev_b64 v[116:117], 11, v[112:113]
	v_lshl_add_u64 v[116:117], s[14:15], 0, v[116:117]
	v_lshl_add_u64 v[122:123], v[148:149], 1, v[116:117]
	s_mov_b64 s[100:101], 0x40000
	v_lshl_add_u64 v[230:231], v[232:233], 0, s[100:101]
	global_load_dwordx4 v[188:191], v[230:231], off
	global_load_dwordx4 v[192:195], v[230:231], off offset:256
	s_waitcnt vmcnt(9)
	v_lshlrev_b32_e32 v115, 16, v196
	v_and_b32_e32 v116, 0xffff0000, v196
	v_lshlrev_b32_e32 v121, 16, v197
	v_and_b32_e32 v117, 0xffff0000, v197
	v_lshlrev_b32_e32 v124, 16, v198
	v_and_b32_e32 v118, 0xffff0000, v198
	v_lshlrev_b32_e32 v125, 16, v199
	v_and_b32_e32 v119, 0xffff0000, v199
	v_add_f32_e32 v115, v108, v115
	v_add_f32_e32 v116, v109, v116
	v_add_f32_e32 v121, v110, v121
	v_add_f32_e32 v117, v111, v117
	v_add_f32_e32 v124, v104, v124
	v_add_f32_e32 v118, v105, v118
	v_add_f32_e32 v125, v106, v125
	v_add_f32_e32 v119, v107, v119
	v_cvt_pk_bf16_f32 v104, v115, v116
	v_cvt_pk_bf16_f32 v105, v121, v117
	v_cvt_pk_bf16_f32 v106, v124, v118
	v_cvt_pk_bf16_f32 v107, v125, v119
	v_mul_f32_e32 v116, v116, v116
	v_mul_f32_e32 v117, v117, v117
	v_mul_f32_e32 v118, v118, v118
	v_mul_f32_e32 v119, v119, v119
	v_fmac_f32_e32 v116, v115, v115
	v_fmac_f32_e32 v117, v121, v121
	v_fmac_f32_e32 v118, v124, v124
	v_fmac_f32_e32 v119, v125, v125
	v_add_f32_e32 v115, v116, v117
	v_add_f32_e32 v116, v118, v119
	v_add_f32_e32 v115, v115, v116
	global_store_dwordx4 v[122:123], v[104:107], off
	s_waitcnt vmcnt(9)
	v_lshlrev_b32_e32 v116, 16, v200
	v_and_b32_e32 v108, 0xffff0000, v200
	v_lshlrev_b32_e32 v117, 16, v201
	v_and_b32_e32 v109, 0xffff0000, v201
	v_lshlrev_b32_e32 v118, 16, v202
	v_and_b32_e32 v110, 0xffff0000, v202
	v_lshlrev_b32_e32 v119, 16, v203
	v_and_b32_e32 v111, 0xffff0000, v203
	v_add_f32_e32 v101, v101, v108
	v_add_f32_e32 v103, v103, v109
	v_add_f32_e32 v109, v97, v110
	v_add_f32_e32 v111, v99, v111
	v_add_f32_e32 v100, v100, v116
	v_add_f32_e32 v102, v102, v117
	v_add_f32_e32 v108, v96, v118
	v_add_f32_e32 v110, v98, v119
	v_mul_f32_e32 v96, v101, v101
	v_mul_f32_e32 v97, v103, v103
	v_mul_f32_e32 v98, v109, v109
	v_mul_f32_e32 v99, v111, v111
	v_fmac_f32_e32 v96, v100, v100
	v_fmac_f32_e32 v97, v102, v102
	v_fmac_f32_e32 v98, v108, v108
	v_fmac_f32_e32 v99, v110, v110
	v_add_f32_e32 v96, v96, v97
	v_add_f32_e32 v97, v98, v99
	v_add_f32_e32 v96, v96, v97
	v_add_f32_e32 v96, v115, v96
	ds_bpermute_b32 v97, v120, v96
	v_cvt_pk_bf16_f32 v98, v100, v101
	v_cvt_pk_bf16_f32 v99, v102, v103
	v_cvt_pk_bf16_f32 v100, v108, v109
	v_cvt_pk_bf16_f32 v101, v110, v111
	s_waitcnt lgkmcnt(0)
	v_add_f32_e32 v96, v96, v97
	ds_bpermute_b32 v97, v114, v96
	global_store_dwordx4 v[122:123], v[98:101], off offset:256
	s_and_saveexec_b64 s[36:37], s[4:5]
	s_cbranch_execz .LBB0_1152
	v_lshlrev_b64 v[98:99], 6, v[112:113]
	v_lshl_add_u64 v[98:99], s[18:19], 0, v[98:99]
	v_lshl_add_u64 v[98:99], s[30:31], 2, v[98:99]
	s_lshl_b32 s8, s50, 2
	v_lshl_add_u64 v[98:99], v[98:99], 0, s[8:9]
	s_waitcnt lgkmcnt(0)
	v_add_f32_e32 v96, v96, v97
	global_store_dword v[98:99], v96, off
.LBB0_1152:
	s_or_b64 exec, exec, s[36:37]
	v_or_b32_e32 v96, 32, v150
	s_waitcnt lgkmcnt(0)
	v_ashrrev_i32_e32 v97, 31, v96
	v_lshlrev_b64 v[98:99], 11, v[96:97]
	v_lshl_add_u64 v[98:99], s[14:15], 0, v[98:99]
	v_lshl_add_u64 v[102:103], v[148:149], 1, v[98:99]
	s_mov_b64 s[100:101], 0x48000
	v_lshl_add_u64 v[230:231], v[232:233], 0, s[100:101]
	global_load_dwordx4 v[196:199], v[230:231], off
	global_load_dwordx4 v[200:203], v[230:231], off offset:256
	s_waitcnt vmcnt(11)
	v_lshlrev_b32_e32 v104, 16, v204
	v_and_b32_e32 v98, 0xffff0000, v204
	v_lshlrev_b32_e32 v105, 16, v205
	v_and_b32_e32 v99, 0xffff0000, v205
	v_lshlrev_b32_e32 v106, 16, v206
	v_and_b32_e32 v100, 0xffff0000, v206
	v_lshlrev_b32_e32 v107, 16, v207
	v_and_b32_e32 v101, 0xffff0000, v207
	v_add_f32_e32 v104, v92, v104
	v_add_f32_e32 v98, v93, v98
	v_add_f32_e32 v105, v94, v105
	v_add_f32_e32 v99, v95, v99
	v_add_f32_e32 v106, v88, v106
	v_add_f32_e32 v100, v89, v100
	v_add_f32_e32 v107, v90, v107
	v_add_f32_e32 v101, v91, v101
	v_cvt_pk_bf16_f32 v88, v104, v98
	v_cvt_pk_bf16_f32 v89, v105, v99
	v_cvt_pk_bf16_f32 v90, v106, v100
	v_cvt_pk_bf16_f32 v91, v107, v101
	v_mul_f32_e32 v98, v98, v98
	v_mul_f32_e32 v99, v99, v99
	v_mul_f32_e32 v100, v100, v100
	v_mul_f32_e32 v101, v101, v101
	v_fmac_f32_e32 v98, v104, v104
	v_fmac_f32_e32 v99, v105, v105
	v_fmac_f32_e32 v100, v106, v106
	v_fmac_f32_e32 v101, v107, v107
	v_add_f32_e32 v98, v98, v99
	v_add_f32_e32 v99, v100, v101
	v_add_f32_e32 v98, v98, v99
	global_store_dwordx4 v[102:103], v[88:91], off
	s_waitcnt vmcnt(11)
	v_lshlrev_b32_e32 v99, 16, v208
	v_and_b32_e32 v92, 0xffff0000, v208
	v_lshlrev_b32_e32 v100, 16, v209
	v_and_b32_e32 v93, 0xffff0000, v209
	v_lshlrev_b32_e32 v101, 16, v210
	v_and_b32_e32 v94, 0xffff0000, v210
	v_lshlrev_b32_e32 v104, 16, v211
	v_and_b32_e32 v95, 0xffff0000, v211
	v_add_f32_e32 v85, v85, v92
	v_add_f32_e32 v87, v87, v93
	v_add_f32_e32 v93, v81, v94
	v_add_f32_e32 v95, v83, v95
	v_add_f32_e32 v84, v84, v99
	v_add_f32_e32 v86, v86, v100
	v_add_f32_e32 v92, v80, v101
	v_add_f32_e32 v94, v82, v104
	v_mul_f32_e32 v80, v85, v85
	v_mul_f32_e32 v81, v87, v87
	v_mul_f32_e32 v82, v93, v93
	v_mul_f32_e32 v83, v95, v95
	v_fmac_f32_e32 v80, v84, v84
	v_fmac_f32_e32 v81, v86, v86
	v_fmac_f32_e32 v82, v92, v92
	v_fmac_f32_e32 v83, v94, v94
	v_add_f32_e32 v80, v80, v81
	v_add_f32_e32 v81, v82, v83
	v_add_f32_e32 v80, v80, v81
	v_add_f32_e32 v80, v98, v80
	ds_bpermute_b32 v81, v120, v80
	v_cvt_pk_bf16_f32 v82, v84, v85
	v_cvt_pk_bf16_f32 v83, v86, v87
	v_cvt_pk_bf16_f32 v84, v92, v93
	v_cvt_pk_bf16_f32 v85, v94, v95
	s_waitcnt lgkmcnt(0)
	v_add_f32_e32 v80, v80, v81
	ds_bpermute_b32 v81, v114, v80
	global_store_dwordx4 v[102:103], v[82:85], off offset:256
	s_and_saveexec_b64 s[36:37], s[4:5]
	s_cbranch_execz .LBB0_1154
	v_lshlrev_b64 v[82:83], 6, v[96:97]
	v_lshl_add_u64 v[82:83], s[18:19], 0, v[82:83]
	v_lshl_add_u64 v[82:83], s[30:31], 2, v[82:83]
	s_lshl_b32 s8, s50, 2
	v_lshl_add_u64 v[82:83], v[82:83], 0, s[8:9]
	s_waitcnt lgkmcnt(0)
	v_add_f32_e32 v80, v80, v81
	global_store_dword v[82:83], v80, off
.LBB0_1154:
	s_or_b64 exec, exec, s[36:37]
	v_or_b32_e32 v80, 48, v150
	s_waitcnt lgkmcnt(0)
	v_ashrrev_i32_e32 v81, 31, v80
	v_lshlrev_b64 v[82:83], 11, v[80:81]
	v_lshl_add_u64 v[82:83], s[14:15], 0, v[82:83]
	v_lshl_add_u64 v[86:87], v[148:149], 1, v[82:83]
	s_mov_b64 s[100:101], 0x50000
	v_lshl_add_u64 v[230:231], v[232:233], 0, s[100:101]
	global_load_dwordx4 v[204:207], v[230:231], off
	global_load_dwordx4 v[208:211], v[230:231], off offset:256
	s_waitcnt vmcnt(13)
	v_lshlrev_b32_e32 v88, 16, v212
	v_and_b32_e32 v82, 0xffff0000, v212
	v_lshlrev_b32_e32 v89, 16, v213
	v_and_b32_e32 v83, 0xffff0000, v213
	v_lshlrev_b32_e32 v90, 16, v214
	v_and_b32_e32 v84, 0xffff0000, v214
	v_lshlrev_b32_e32 v91, 16, v215
	v_and_b32_e32 v85, 0xffff0000, v215
	v_add_f32_e32 v88, v76, v88
	v_add_f32_e32 v82, v77, v82
	v_add_f32_e32 v89, v78, v89
	v_add_f32_e32 v83, v79, v83
	v_add_f32_e32 v90, v72, v90
	v_add_f32_e32 v84, v73, v84
	v_add_f32_e32 v91, v74, v91
	v_add_f32_e32 v85, v75, v85
	v_cvt_pk_bf16_f32 v72, v88, v82
	v_cvt_pk_bf16_f32 v73, v89, v83
	v_cvt_pk_bf16_f32 v74, v90, v84
	v_cvt_pk_bf16_f32 v75, v91, v85
	v_mul_f32_e32 v82, v82, v82
	v_mul_f32_e32 v83, v83, v83
	v_mul_f32_e32 v84, v84, v84
	v_mul_f32_e32 v85, v85, v85
	v_fmac_f32_e32 v82, v88, v88
	v_fmac_f32_e32 v83, v89, v89
	v_fmac_f32_e32 v84, v90, v90
	v_fmac_f32_e32 v85, v91, v91
	v_add_f32_e32 v82, v82, v83
	v_add_f32_e32 v83, v84, v85
	v_add_f32_e32 v82, v82, v83
	global_store_dwordx4 v[86:87], v[72:75], off
	s_waitcnt vmcnt(13)
	v_lshlrev_b32_e32 v83, 16, v216
	v_and_b32_e32 v76, 0xffff0000, v216
	v_lshlrev_b32_e32 v84, 16, v217
	v_and_b32_e32 v77, 0xffff0000, v217
	v_lshlrev_b32_e32 v85, 16, v218
	v_and_b32_e32 v78, 0xffff0000, v218
	v_lshlrev_b32_e32 v88, 16, v219
	v_and_b32_e32 v79, 0xffff0000, v219
	v_add_f32_e32 v69, v69, v76
	v_add_f32_e32 v71, v71, v77
	v_add_f32_e32 v77, v65, v78
	v_add_f32_e32 v79, v67, v79
	v_add_f32_e32 v68, v68, v83
	v_add_f32_e32 v70, v70, v84
	v_add_f32_e32 v76, v64, v85
	v_add_f32_e32 v78, v66, v88
	v_mul_f32_e32 v64, v69, v69
	v_mul_f32_e32 v65, v71, v71
	v_mul_f32_e32 v66, v77, v77
	v_mul_f32_e32 v67, v79, v79
	v_fmac_f32_e32 v64, v68, v68
	v_fmac_f32_e32 v65, v70, v70
	v_fmac_f32_e32 v66, v76, v76
	v_fmac_f32_e32 v67, v78, v78
	v_add_f32_e32 v64, v64, v65
	v_add_f32_e32 v65, v66, v67
	v_add_f32_e32 v64, v64, v65
	v_add_f32_e32 v64, v82, v64
	ds_bpermute_b32 v65, v120, v64
	v_cvt_pk_bf16_f32 v66, v68, v69
	v_cvt_pk_bf16_f32 v67, v70, v71
	v_cvt_pk_bf16_f32 v68, v76, v77
	v_cvt_pk_bf16_f32 v69, v78, v79
	s_waitcnt lgkmcnt(0)
	v_add_f32_e32 v64, v64, v65
	ds_bpermute_b32 v65, v114, v64
	global_store_dwordx4 v[86:87], v[66:69], off offset:256
	s_and_saveexec_b64 s[36:37], s[4:5]
	s_cbranch_execz .LBB0_1156
	v_lshlrev_b64 v[66:67], 6, v[80:81]
	v_lshl_add_u64 v[66:67], s[18:19], 0, v[66:67]
	v_lshl_add_u64 v[66:67], s[30:31], 2, v[66:67]
	s_lshl_b32 s8, s50, 2
	v_lshl_add_u64 v[66:67], v[66:67], 0, s[8:9]
	s_waitcnt lgkmcnt(0)
	v_add_f32_e32 v64, v64, v65
	global_store_dword v[66:67], v64, off
.LBB0_1156:
	s_or_b64 exec, exec, s[36:37]
	v_add_u32_e32 v64, 0x80, v150
	s_waitcnt lgkmcnt(0)
	v_ashrrev_i32_e32 v65, 31, v64
	v_lshlrev_b64 v[66:67], 11, v[64:65]
	v_lshl_add_u64 v[66:67], s[14:15], 0, v[66:67]
	v_lshl_add_u64 v[70:71], v[148:149], 1, v[66:67]
	s_mov_b64 s[100:101], 0x58000
	v_lshl_add_u64 v[230:231], v[232:233], 0, s[100:101]
	global_load_dwordx4 v[212:215], v[230:231], off
	global_load_dwordx4 v[216:219], v[230:231], off offset:256
	s_waitcnt vmcnt(13)
	v_lshlrev_b32_e32 v72, 16, v188
	v_and_b32_e32 v66, 0xffff0000, v188
	v_lshlrev_b32_e32 v73, 16, v189
	v_and_b32_e32 v67, 0xffff0000, v189
	v_lshlrev_b32_e32 v74, 16, v190
	v_and_b32_e32 v68, 0xffff0000, v190
	v_lshlrev_b32_e32 v75, 16, v191
	v_and_b32_e32 v69, 0xffff0000, v191
	v_add_f32_e32 v72, v60, v72
	v_add_f32_e32 v66, v61, v66
	v_add_f32_e32 v73, v62, v73
	v_add_f32_e32 v67, v63, v67
	v_add_f32_e32 v74, v56, v74
	v_add_f32_e32 v68, v57, v68
	v_add_f32_e32 v75, v58, v75
	v_add_f32_e32 v69, v59, v69
	v_cvt_pk_bf16_f32 v56, v72, v66
	v_cvt_pk_bf16_f32 v57, v73, v67
	v_cvt_pk_bf16_f32 v58, v74, v68
	v_cvt_pk_bf16_f32 v59, v75, v69
	v_mul_f32_e32 v66, v66, v66
	v_mul_f32_e32 v67, v67, v67
	v_mul_f32_e32 v68, v68, v68
	v_mul_f32_e32 v69, v69, v69
	v_fmac_f32_e32 v66, v72, v72
	v_fmac_f32_e32 v67, v73, v73
	v_fmac_f32_e32 v68, v74, v74
	v_fmac_f32_e32 v69, v75, v75
	v_add_f32_e32 v66, v66, v67
	v_add_f32_e32 v67, v68, v69
	v_add_f32_e32 v66, v66, v67
	global_store_dwordx4 v[70:71], v[56:59], off
	s_waitcnt vmcnt(13)
	v_lshlrev_b32_e32 v67, 16, v192
	v_and_b32_e32 v60, 0xffff0000, v192
	v_lshlrev_b32_e32 v68, 16, v193
	v_and_b32_e32 v61, 0xffff0000, v193
	v_lshlrev_b32_e32 v69, 16, v194
	v_and_b32_e32 v62, 0xffff0000, v194
	v_lshlrev_b32_e32 v72, 16, v195
	v_and_b32_e32 v63, 0xffff0000, v195
	v_add_f32_e32 v53, v53, v60
	v_add_f32_e32 v55, v55, v61
	v_add_f32_e32 v61, v49, v62
	v_add_f32_e32 v63, v51, v63
	v_add_f32_e32 v52, v52, v67
	v_add_f32_e32 v54, v54, v68
	v_add_f32_e32 v60, v48, v69
	v_add_f32_e32 v62, v50, v72
	v_mul_f32_e32 v48, v53, v53
	v_mul_f32_e32 v49, v55, v55
	v_mul_f32_e32 v50, v61, v61
	v_mul_f32_e32 v51, v63, v63
	v_fmac_f32_e32 v48, v52, v52
	v_fmac_f32_e32 v49, v54, v54
	v_fmac_f32_e32 v50, v60, v60
	v_fmac_f32_e32 v51, v62, v62
	v_add_f32_e32 v48, v48, v49
	v_add_f32_e32 v49, v50, v51
	v_add_f32_e32 v48, v48, v49
	v_add_f32_e32 v48, v66, v48
	ds_bpermute_b32 v49, v120, v48
	v_cvt_pk_bf16_f32 v50, v52, v53
	v_cvt_pk_bf16_f32 v51, v54, v55
	v_cvt_pk_bf16_f32 v52, v60, v61
	v_cvt_pk_bf16_f32 v53, v62, v63
	s_waitcnt lgkmcnt(0)
	v_add_f32_e32 v48, v48, v49
	ds_bpermute_b32 v49, v114, v48
	global_store_dwordx4 v[70:71], v[50:53], off offset:256
	s_and_saveexec_b64 s[36:37], s[4:5]
	s_cbranch_execz .LBB0_1158
	v_lshlrev_b64 v[50:51], 6, v[64:65]
	v_lshl_add_u64 v[50:51], s[18:19], 0, v[50:51]
	v_lshl_add_u64 v[50:51], s[30:31], 2, v[50:51]
	s_lshl_b32 s8, s50, 2
	v_lshl_add_u64 v[50:51], v[50:51], 0, s[8:9]
	s_waitcnt lgkmcnt(0)
	v_add_f32_e32 v48, v48, v49
	global_store_dword v[50:51], v48, off
.LBB0_1158:
	s_or_b64 exec, exec, s[36:37]
	v_add_u32_e32 v48, 0x90, v150
	s_waitcnt lgkmcnt(0)
	v_ashrrev_i32_e32 v49, 31, v48
	v_lshlrev_b64 v[50:51], 11, v[48:49]
	v_lshl_add_u64 v[50:51], s[14:15], 0, v[50:51]
	v_lshl_add_u64 v[54:55], v[148:149], 1, v[50:51]
	s_waitcnt vmcnt(11)
	v_lshlrev_b32_e32 v56, 16, v196
	v_and_b32_e32 v50, 0xffff0000, v196
	v_lshlrev_b32_e32 v57, 16, v197
	v_and_b32_e32 v51, 0xffff0000, v197
	v_lshlrev_b32_e32 v58, 16, v198
	v_and_b32_e32 v52, 0xffff0000, v198
	v_lshlrev_b32_e32 v59, 16, v199
	v_and_b32_e32 v53, 0xffff0000, v199
	v_add_f32_e32 v56, v44, v56
	v_add_f32_e32 v50, v45, v50
	v_add_f32_e32 v57, v46, v57
	v_add_f32_e32 v51, v47, v51
	v_add_f32_e32 v58, v40, v58
	v_add_f32_e32 v52, v41, v52
	v_add_f32_e32 v59, v42, v59
	v_add_f32_e32 v53, v43, v53
	v_cvt_pk_bf16_f32 v40, v56, v50
	v_cvt_pk_bf16_f32 v41, v57, v51
	v_cvt_pk_bf16_f32 v42, v58, v52
	v_cvt_pk_bf16_f32 v43, v59, v53
	v_mul_f32_e32 v50, v50, v50
	v_mul_f32_e32 v51, v51, v51
	v_mul_f32_e32 v52, v52, v52
	v_mul_f32_e32 v53, v53, v53
	v_fmac_f32_e32 v50, v56, v56
	v_fmac_f32_e32 v51, v57, v57
	v_fmac_f32_e32 v52, v58, v58
	v_fmac_f32_e32 v53, v59, v59
	v_add_f32_e32 v50, v50, v51
	v_add_f32_e32 v51, v52, v53
	v_add_f32_e32 v50, v50, v51
	global_store_dwordx4 v[54:55], v[40:43], off
	s_waitcnt vmcnt(11)
	v_lshlrev_b32_e32 v51, 16, v200
	v_and_b32_e32 v44, 0xffff0000, v200
	v_lshlrev_b32_e32 v52, 16, v201
	v_and_b32_e32 v45, 0xffff0000, v201
	v_lshlrev_b32_e32 v53, 16, v202
	v_and_b32_e32 v46, 0xffff0000, v202
	v_lshlrev_b32_e32 v56, 16, v203
	v_and_b32_e32 v47, 0xffff0000, v203
	v_add_f32_e32 v37, v37, v44
	v_add_f32_e32 v39, v39, v45
	v_add_f32_e32 v45, v33, v46
	v_add_f32_e32 v47, v35, v47
	v_add_f32_e32 v36, v36, v51
	v_add_f32_e32 v38, v38, v52
	v_add_f32_e32 v44, v32, v53
	v_add_f32_e32 v46, v34, v56
	v_mul_f32_e32 v32, v37, v37
	v_mul_f32_e32 v33, v39, v39
	v_mul_f32_e32 v34, v45, v45
	v_mul_f32_e32 v35, v47, v47
	v_fmac_f32_e32 v32, v36, v36
	v_fmac_f32_e32 v33, v38, v38
	v_fmac_f32_e32 v34, v44, v44
	v_fmac_f32_e32 v35, v46, v46
	v_add_f32_e32 v32, v32, v33
	v_add_f32_e32 v33, v34, v35
	v_add_f32_e32 v32, v32, v33
	v_add_f32_e32 v32, v50, v32
	ds_bpermute_b32 v33, v120, v32
	v_cvt_pk_bf16_f32 v34, v36, v37
	v_cvt_pk_bf16_f32 v35, v38, v39
	v_cvt_pk_bf16_f32 v36, v44, v45
	v_cvt_pk_bf16_f32 v37, v46, v47
	s_waitcnt lgkmcnt(0)
	v_add_f32_e32 v32, v32, v33
	ds_bpermute_b32 v33, v114, v32
	global_store_dwordx4 v[54:55], v[34:37], off offset:256
	s_and_saveexec_b64 s[36:37], s[4:5]
	s_cbranch_execz .LBB0_1160
	v_lshlrev_b64 v[34:35], 6, v[48:49]
	v_lshl_add_u64 v[34:35], s[18:19], 0, v[34:35]
	v_lshl_add_u64 v[34:35], s[30:31], 2, v[34:35]
	s_lshl_b32 s8, s50, 2
	v_lshl_add_u64 v[34:35], v[34:35], 0, s[8:9]
	s_waitcnt lgkmcnt(0)
	v_add_f32_e32 v32, v32, v33
	global_store_dword v[34:35], v32, off
.LBB0_1160:
	s_or_b64 exec, exec, s[36:37]
	v_add_u32_e32 v32, 0xa0, v150
	s_waitcnt lgkmcnt(0)
	v_ashrrev_i32_e32 v33, 31, v32
	v_lshlrev_b64 v[34:35], 11, v[32:33]
	v_lshl_add_u64 v[34:35], s[14:15], 0, v[34:35]
	v_lshl_add_u64 v[38:39], v[148:149], 1, v[34:35]
	s_waitcnt vmcnt(9)
	v_lshlrev_b32_e32 v40, 16, v204
	v_and_b32_e32 v34, 0xffff0000, v204
	v_lshlrev_b32_e32 v41, 16, v205
	v_and_b32_e32 v35, 0xffff0000, v205
	v_lshlrev_b32_e32 v42, 16, v206
	v_and_b32_e32 v36, 0xffff0000, v206
	v_lshlrev_b32_e32 v43, 16, v207
	v_and_b32_e32 v37, 0xffff0000, v207
	v_add_f32_e32 v40, v28, v40
	v_add_f32_e32 v34, v29, v34
	v_add_f32_e32 v41, v30, v41
	v_add_f32_e32 v35, v31, v35
	v_add_f32_e32 v42, v24, v42
	v_add_f32_e32 v36, v25, v36
	v_add_f32_e32 v43, v26, v43
	v_add_f32_e32 v37, v27, v37
	v_cvt_pk_bf16_f32 v24, v40, v34
	v_cvt_pk_bf16_f32 v25, v41, v35
	v_cvt_pk_bf16_f32 v26, v42, v36
	v_cvt_pk_bf16_f32 v27, v43, v37
	v_mul_f32_e32 v34, v34, v34
	v_mul_f32_e32 v35, v35, v35
	v_mul_f32_e32 v36, v36, v36
	v_mul_f32_e32 v37, v37, v37
	v_fmac_f32_e32 v34, v40, v40
	v_fmac_f32_e32 v35, v41, v41
	v_fmac_f32_e32 v36, v42, v42
	v_fmac_f32_e32 v37, v43, v43
	v_add_f32_e32 v34, v34, v35
	v_add_f32_e32 v35, v36, v37
	v_add_f32_e32 v34, v34, v35
	global_store_dwordx4 v[38:39], v[24:27], off
	s_waitcnt vmcnt(9)
	v_lshlrev_b32_e32 v35, 16, v208
	v_and_b32_e32 v28, 0xffff0000, v208
	v_lshlrev_b32_e32 v36, 16, v209
	v_and_b32_e32 v29, 0xffff0000, v209
	v_lshlrev_b32_e32 v37, 16, v210
	v_and_b32_e32 v30, 0xffff0000, v210
	v_lshlrev_b32_e32 v40, 16, v211
	v_and_b32_e32 v31, 0xffff0000, v211
	v_add_f32_e32 v21, v21, v28
	v_add_f32_e32 v23, v23, v29
	v_add_f32_e32 v29, v17, v30
	v_add_f32_e32 v31, v19, v31
	v_add_f32_e32 v20, v20, v35
	v_add_f32_e32 v22, v22, v36
	v_add_f32_e32 v28, v16, v37
	v_add_f32_e32 v30, v18, v40
	v_mul_f32_e32 v16, v21, v21
	v_mul_f32_e32 v17, v23, v23
	v_mul_f32_e32 v18, v29, v29
	v_mul_f32_e32 v19, v31, v31
	v_fmac_f32_e32 v16, v20, v20
	v_fmac_f32_e32 v17, v22, v22
	v_fmac_f32_e32 v18, v28, v28
	v_fmac_f32_e32 v19, v30, v30
	v_add_f32_e32 v16, v16, v17
	v_add_f32_e32 v17, v18, v19
	v_add_f32_e32 v16, v16, v17
	v_add_f32_e32 v16, v34, v16
	ds_bpermute_b32 v17, v120, v16
	v_cvt_pk_bf16_f32 v18, v20, v21
	v_cvt_pk_bf16_f32 v19, v22, v23
	v_cvt_pk_bf16_f32 v20, v28, v29
	v_cvt_pk_bf16_f32 v21, v30, v31
	s_waitcnt lgkmcnt(0)
	v_add_f32_e32 v16, v16, v17
	ds_bpermute_b32 v17, v114, v16
	global_store_dwordx4 v[38:39], v[18:21], off offset:256
	s_and_saveexec_b64 s[36:37], s[4:5]
	s_cbranch_execz .LBB0_1162
	v_lshlrev_b64 v[18:19], 6, v[32:33]
	v_lshl_add_u64 v[18:19], s[18:19], 0, v[18:19]
	v_lshl_add_u64 v[18:19], s[30:31], 2, v[18:19]
	s_lshl_b32 s8, s50, 2
	v_lshl_add_u64 v[18:19], v[18:19], 0, s[8:9]
	s_waitcnt lgkmcnt(0)
	v_add_f32_e32 v16, v16, v17
	global_store_dword v[18:19], v16, off
.LBB0_1162:
	s_or_b64 exec, exec, s[36:37]
	v_add_u32_e32 v16, 0xb0, v150
	s_waitcnt lgkmcnt(0)
	v_ashrrev_i32_e32 v17, 31, v16
	v_lshlrev_b64 v[18:19], 11, v[16:17]
	v_lshl_add_u64 v[18:19], s[14:15], 0, v[18:19]
	v_lshl_add_u64 v[22:23], v[148:149], 1, v[18:19]
	s_waitcnt vmcnt(7)
	v_lshlrev_b32_e32 v24, 16, v212
	v_and_b32_e32 v18, 0xffff0000, v212
	v_lshlrev_b32_e32 v25, 16, v213
	v_and_b32_e32 v19, 0xffff0000, v213
	v_lshlrev_b32_e32 v26, 16, v214
	v_and_b32_e32 v20, 0xffff0000, v214
	v_lshlrev_b32_e32 v27, 16, v215
	v_and_b32_e32 v21, 0xffff0000, v215
	v_add_f32_e32 v24, v12, v24
	v_add_f32_e32 v18, v13, v18
	v_add_f32_e32 v25, v14, v25
	v_add_f32_e32 v19, v15, v19
	v_add_f32_e32 v26, v8, v26
	v_add_f32_e32 v20, v9, v20
	v_add_f32_e32 v27, v10, v27
	v_add_f32_e32 v21, v11, v21
	v_cvt_pk_bf16_f32 v8, v24, v18
	v_cvt_pk_bf16_f32 v9, v25, v19
	v_cvt_pk_bf16_f32 v10, v26, v20
	v_cvt_pk_bf16_f32 v11, v27, v21
	v_mul_f32_e32 v18, v18, v18
	v_mul_f32_e32 v19, v19, v19
	v_mul_f32_e32 v20, v20, v20
	v_mul_f32_e32 v21, v21, v21
	v_fmac_f32_e32 v18, v24, v24
	v_fmac_f32_e32 v19, v25, v25
	v_fmac_f32_e32 v20, v26, v26
	v_fmac_f32_e32 v21, v27, v27
	v_add_f32_e32 v18, v18, v19
	v_add_f32_e32 v19, v20, v21
	v_add_f32_e32 v18, v18, v19
	global_store_dwordx4 v[22:23], v[8:11], off
	s_waitcnt vmcnt(7)
	v_lshlrev_b32_e32 v19, 16, v216
	v_and_b32_e32 v12, 0xffff0000, v216
	v_lshlrev_b32_e32 v20, 16, v217
	v_and_b32_e32 v13, 0xffff0000, v217
	v_lshlrev_b32_e32 v21, 16, v218
	v_and_b32_e32 v14, 0xffff0000, v218
	v_lshlrev_b32_e32 v24, 16, v219
	v_and_b32_e32 v15, 0xffff0000, v219
	v_add_f32_e32 v5, v5, v12
	v_add_f32_e32 v7, v7, v13
	v_add_f32_e32 v13, v1, v14
	v_add_f32_e32 v15, v3, v15
	v_add_f32_e32 v4, v4, v19
	v_add_f32_e32 v6, v6, v20
	v_add_f32_e32 v12, v0, v21
	v_add_f32_e32 v14, v2, v24
	v_mul_f32_e32 v0, v5, v5
	v_mul_f32_e32 v1, v7, v7
	v_mul_f32_e32 v2, v13, v13
	v_mul_f32_e32 v3, v15, v15
	v_fmac_f32_e32 v0, v4, v4
	v_fmac_f32_e32 v1, v6, v6
	v_fmac_f32_e32 v2, v12, v12
	v_fmac_f32_e32 v3, v14, v14
	v_add_f32_e32 v0, v0, v1
	v_add_f32_e32 v1, v2, v3
	v_add_f32_e32 v0, v0, v1
	v_add_f32_e32 v0, v18, v0
	ds_bpermute_b32 v1, v120, v0
	v_cvt_pk_bf16_f32 v2, v4, v5
	v_cvt_pk_bf16_f32 v3, v6, v7
	v_cvt_pk_bf16_f32 v4, v12, v13
	v_cvt_pk_bf16_f32 v5, v14, v15
	s_waitcnt lgkmcnt(0)
	v_add_f32_e32 v0, v0, v1
	ds_bpermute_b32 v1, v114, v0
	global_store_dwordx4 v[22:23], v[2:5], off offset:256
	s_and_saveexec_b64 s[36:37], s[4:5]
	s_cbranch_execz .LBB0_1164
	v_lshlrev_b64 v[2:3], 6, v[16:17]
	v_lshl_add_u64 v[2:3], s[18:19], 0, v[2:3]
	v_lshl_add_u64 v[2:3], s[30:31], 2, v[2:3]
	s_lshl_b32 s8, s50, 2
	v_lshl_add_u64 v[2:3], v[2:3], 0, s[8:9]
	s_waitcnt lgkmcnt(0)
	v_add_f32_e32 v0, v0, v1
	global_store_dword v[2:3], v0, off

.LBB0_1560:
	v_lshl_add_u32 v148, s38, 8, v150
	v_ashrrev_i32_e32 v149, 31, v148
	v_lshl_or_b32 v146, s0, 8, v152
	v_lshlrev_b64 v[158:159], 11, v[148:149]
	v_ashrrev_i32_e32 v147, 31, v146
	v_lshl_add_u64 v[158:159], s[14:15], 0, v[158:159]
	v_lshl_add_u64 v[162:163], v[146:147], 1, v[158:159]
	v_mov_b32_e32 v232, v162
	v_mov_b32_e32 v233, v163
	global_load_dwordx4 v[188:191], v[232:233], off
	global_load_dwordx4 v[192:195], v[232:233], off offset:256
	s_mov_b64 s[100:101], 0x8000
	v_lshl_add_u64 v[230:231], v[232:233], 0, s[100:101]
	global_load_dwordx4 v[196:199], v[230:231], off
	global_load_dwordx4 v[200:203], v[230:231], off offset:256
	s_mov_b64 s[100:101], 0x10000
	v_lshl_add_u64 v[230:231], v[232:233], 0, s[100:101]
	global_load_dwordx4 v[204:207], v[230:231], off
	global_load_dwordx4 v[208:211], v[230:231], off offset:256
	s_mov_b64 s[100:101], 0x18000
	v_lshl_add_u64 v[230:231], v[232:233], 0, s[100:101]
	global_load_dwordx4 v[212:215], v[230:231], off
	global_load_dwordx4 v[216:219], v[230:231], off offset:256
	v_and_b32_e32 v169, 64, v157
	v_add_u32_e32 v169, 64, v169
	v_xor_b32_e32 v170, 32, v157
	s_lshl_b32 s38, s0, 2
	s_ashr_i32 s39, s38, 31
	s_waitcnt vmcnt(7)
	v_lshlrev_b32_e32 v164, 16, v188
	v_and_b32_e32 v158, 0xffff0000, v188
	v_lshlrev_b32_e32 v165, 16, v189
	v_and_b32_e32 v159, 0xffff0000, v189
	v_lshlrev_b32_e32 v166, 16, v190
	v_and_b32_e32 v160, 0xffff0000, v190
	v_lshlrev_b32_e32 v167, 16, v191
	v_and_b32_e32 v161, 0xffff0000, v191
	v_add_f32_e32 v164, v124, v164
	v_add_f32_e32 v168, v125, v158
	v_add_f32_e32 v126, v126, v165
	v_add_f32_e32 v127, v127, v159
	v_add_f32_e32 v165, v120, v166
	v_add_f32_e32 v121, v121, v160
	v_add_f32_e32 v166, v122, v167
	v_add_f32_e32 v167, v123, v161
	v_cvt_pk_bf16_f32 v122, v164, v168
	v_cvt_pk_bf16_f32 v123, v126, v127
	v_cvt_pk_bf16_f32 v124, v165, v121
	v_cvt_pk_bf16_f32 v125, v166, v167
	v_mul_f32_e32 v168, v168, v168
	v_mul_f32_e32 v127, v127, v127
	v_mul_f32_e32 v121, v121, v121
	v_mul_f32_e32 v167, v167, v167
	v_fmac_f32_e32 v168, v164, v164
	v_fmac_f32_e32 v127, v126, v126
	v_fmac_f32_e32 v121, v165, v165
	v_fmac_f32_e32 v167, v166, v166
	v_add_f32_e32 v126, v168, v127
	v_add_f32_e32 v121, v121, v167
	v_add_f32_e32 v121, v126, v121
	v_xor_b32_e32 v120, 16, v157
	v_cmp_lt_i32_e32 vcc, v120, v169
	global_store_dwordx4 v[162:163], v[122:125], off
	s_waitcnt vmcnt(7)
	v_lshlrev_b32_e32 v126, 16, v192
	v_and_b32_e32 v127, 0xffff0000, v192
	v_lshlrev_b32_e32 v158, 16, v193
	v_and_b32_e32 v159, 0xffff0000, v193
	v_lshlrev_b32_e32 v164, 16, v194
	v_and_b32_e32 v160, 0xffff0000, v194
	v_lshlrev_b32_e32 v165, 16, v195
	v_and_b32_e32 v161, 0xffff0000, v195
	v_add_f32_e32 v117, v117, v127
	v_add_f32_e32 v119, v119, v159
	v_add_f32_e32 v127, v113, v160
	v_add_f32_e32 v115, v115, v161
	v_add_f32_e32 v116, v116, v126
	v_add_f32_e32 v118, v118, v158
	v_add_f32_e32 v126, v112, v164
	v_add_f32_e32 v158, v114, v165
	v_mul_f32_e32 v112, v117, v117
	v_mul_f32_e32 v113, v119, v119
	v_mul_f32_e32 v114, v127, v127
	v_mul_f32_e32 v159, v115, v115
	v_fmac_f32_e32 v112, v116, v116
	v_fmac_f32_e32 v113, v118, v118
	v_fmac_f32_e32 v114, v126, v126
	v_fmac_f32_e32 v159, v158, v158
	v_add_f32_e32 v112, v112, v113
	v_add_f32_e32 v113, v114, v159
	v_cndmask_b32_e32 v120, v157, v120, vcc
	v_add_f32_e32 v112, v112, v113
	v_lshlrev_b32_e32 v120, 2, v120
	v_add_f32_e32 v112, v121, v112
	ds_bpermute_b32 v113, v120, v112
	v_cmp_lt_i32_e32 vcc, v170, v169
	v_cvt_pk_bf16_f32 v116, v116, v117
	v_cvt_pk_bf16_f32 v117, v118, v119
	v_cvt_pk_bf16_f32 v118, v126, v127
	s_waitcnt lgkmcnt(0)
	v_add_f32_e32 v112, v112, v113
	v_cvt_pk_bf16_f32 v119, v158, v115
	v_cndmask_b32_e32 v114, v157, v170, vcc
	v_lshlrev_b32_e32 v114, 2, v114
	ds_bpermute_b32 v113, v114, v112
	global_store_dwordx4 v[162:163], v[116:119], off offset:256
	s_and_saveexec_b64 s[40:41], s[4:5]
	s_cbranch_execz .LBB0_1562
	v_lshlrev_b64 v[116:117], 6, v[148:149]
	v_lshl_add_u64 v[116:117], s[18:19], 0, v[116:117]
	v_lshl_add_u64 v[116:117], s[38:39], 2, v[116:117]
	s_lshl_b32 s0, s52, 2
	v_lshl_add_u64 v[116:117], v[116:117], 0, s[0:1]
	s_waitcnt lgkmcnt(0)
	v_add_f32_e32 v112, v112, v113
	global_store_dword v[116:117], v112, off
.LBB0_1562:
	s_or_b64 exec, exec, s[40:41]
	v_or_b32_e32 v112, 16, v148
	s_waitcnt lgkmcnt(0)
	v_ashrrev_i32_e32 v113, 31, v112
	v_lshlrev_b64 v[116:117], 11, v[112:113]
	v_lshl_add_u64 v[116:117], s[14:15], 0, v[116:117]
	v_lshl_add_u64 v[122:123], v[146:147], 1, v[116:117]
	s_mov_b64 s[100:101], 0x40000
	v_lshl_add_u64 v[230:231], v[232:233], 0, s[100:101]
	global_load_dwordx4 v[188:191], v[230:231], off
	global_load_dwordx4 v[192:195], v[230:231], off offset:256
	s_waitcnt vmcnt(9)
	v_lshlrev_b32_e32 v115, 16, v196
	v_and_b32_e32 v116, 0xffff0000, v196
	v_lshlrev_b32_e32 v121, 16, v197
	v_and_b32_e32 v117, 0xffff0000, v197
	v_lshlrev_b32_e32 v124, 16, v198
	v_and_b32_e32 v118, 0xffff0000, v198
	v_lshlrev_b32_e32 v125, 16, v199
	v_and_b32_e32 v119, 0xffff0000, v199
	v_add_f32_e32 v115, v108, v115
	v_add_f32_e32 v116, v109, v116
	v_add_f32_e32 v121, v110, v121
	v_add_f32_e32 v117, v111, v117
	v_add_f32_e32 v124, v104, v124
	v_add_f32_e32 v118, v105, v118
	v_add_f32_e32 v125, v106, v125
	v_add_f32_e32 v119, v107, v119
	v_cvt_pk_bf16_f32 v104, v115, v116
	v_cvt_pk_bf16_f32 v105, v121, v117
	v_cvt_pk_bf16_f32 v106, v124, v118
	v_cvt_pk_bf16_f32 v107, v125, v119
	v_mul_f32_e32 v116, v116, v116
	v_mul_f32_e32 v117, v117, v117
	v_mul_f32_e32 v118, v118, v118
	v_mul_f32_e32 v119, v119, v119
	v_fmac_f32_e32 v116, v115, v115
	v_fmac_f32_e32 v117, v121, v121
	v_fmac_f32_e32 v118, v124, v124
	v_fmac_f32_e32 v119, v125, v125
	v_add_f32_e32 v115, v116, v117
	v_add_f32_e32 v116, v118, v119
	v_add_f32_e32 v115, v115, v116
	global_store_dwordx4 v[122:123], v[104:107], off
	s_waitcnt vmcnt(9)
	v_lshlrev_b32_e32 v116, 16, v200
	v_and_b32_e32 v108, 0xffff0000, v200
	v_lshlrev_b32_e32 v117, 16, v201
	v_and_b32_e32 v109, 0xffff0000, v201
	v_lshlrev_b32_e32 v118, 16, v202
	v_and_b32_e32 v110, 0xffff0000, v202
	v_lshlrev_b32_e32 v119, 16, v203
	v_and_b32_e32 v111, 0xffff0000, v203
	v_add_f32_e32 v101, v101, v108
	v_add_f32_e32 v103, v103, v109
	v_add_f32_e32 v109, v97, v110
	v_add_f32_e32 v111, v99, v111
	v_add_f32_e32 v100, v100, v116
	v_add_f32_e32 v102, v102, v117
	v_add_f32_e32 v108, v96, v118
	v_add_f32_e32 v110, v98, v119
	v_mul_f32_e32 v96, v101, v101
	v_mul_f32_e32 v97, v103, v103
	v_mul_f32_e32 v98, v109, v109
	v_mul_f32_e32 v99, v111, v111
	v_fmac_f32_e32 v96, v100, v100
	v_fmac_f32_e32 v97, v102, v102
	v_fmac_f32_e32 v98, v108, v108
	v_fmac_f32_e32 v99, v110, v110
	v_add_f32_e32 v96, v96, v97
	v_add_f32_e32 v97, v98, v99
	v_add_f32_e32 v96, v96, v97
	v_add_f32_e32 v96, v115, v96
	ds_bpermute_b32 v97, v120, v96
	v_cvt_pk_bf16_f32 v98, v100, v101
	v_cvt_pk_bf16_f32 v99, v102, v103
	v_cvt_pk_bf16_f32 v100, v108, v109
	v_cvt_pk_bf16_f32 v101, v110, v111
	s_waitcnt lgkmcnt(0)
	v_add_f32_e32 v96, v96, v97
	ds_bpermute_b32 v97, v114, v96
	global_store_dwordx4 v[122:123], v[98:101], off offset:256
	s_and_saveexec_b64 s[40:41], s[4:5]
	s_cbranch_execz .LBB0_1564
	v_lshlrev_b64 v[98:99], 6, v[112:113]
	v_lshl_add_u64 v[98:99], s[18:19], 0, v[98:99]
	v_lshl_add_u64 v[98:99], s[38:39], 2, v[98:99]
	s_lshl_b32 s0, s52, 2
	v_lshl_add_u64 v[98:99], v[98:99], 0, s[0:1]
	s_waitcnt lgkmcnt(0)
	v_add_f32_e32 v96, v96, v97
	global_store_dword v[98:99], v96, off
.LBB0_1564:
	s_or_b64 exec, exec, s[40:41]
	v_or_b32_e32 v96, 32, v148
	s_waitcnt lgkmcnt(0)
	v_ashrrev_i32_e32 v97, 31, v96
	v_lshlrev_b64 v[98:99], 11, v[96:97]
	v_lshl_add_u64 v[98:99], s[14:15], 0, v[98:99]
	v_lshl_add_u64 v[102:103], v[146:147], 1, v[98:99]
	s_mov_b64 s[100:101], 0x48000
	v_lshl_add_u64 v[230:231], v[232:233], 0, s[100:101]
	global_load_dwordx4 v[196:199], v[230:231], off
	global_load_dwordx4 v[200:203], v[230:231], off offset:256
	s_waitcnt vmcnt(11)
	v_lshlrev_b32_e32 v104, 16, v204
	v_and_b32_e32 v98, 0xffff0000, v204
	v_lshlrev_b32_e32 v105, 16, v205
	v_and_b32_e32 v99, 0xffff0000, v205
	v_lshlrev_b32_e32 v106, 16, v206
	v_and_b32_e32 v100, 0xffff0000, v206
	v_lshlrev_b32_e32 v107, 16, v207
	v_and_b32_e32 v101, 0xffff0000, v207
	v_add_f32_e32 v104, v92, v104
	v_add_f32_e32 v98, v93, v98
	v_add_f32_e32 v105, v94, v105
	v_add_f32_e32 v99, v95, v99
	v_add_f32_e32 v106, v88, v106
	v_add_f32_e32 v100, v89, v100
	v_add_f32_e32 v107, v90, v107
	v_add_f32_e32 v101, v91, v101
	v_cvt_pk_bf16_f32 v88, v104, v98
	v_cvt_pk_bf16_f32 v89, v105, v99
	v_cvt_pk_bf16_f32 v90, v106, v100
	v_cvt_pk_bf16_f32 v91, v107, v101
	v_mul_f32_e32 v98, v98, v98
	v_mul_f32_e32 v99, v99, v99
	v_mul_f32_e32 v100, v100, v100
	v_mul_f32_e32 v101, v101, v101
	v_fmac_f32_e32 v98, v104, v104
	v_fmac_f32_e32 v99, v105, v105
	v_fmac_f32_e32 v100, v106, v106
	v_fmac_f32_e32 v101, v107, v107
	v_add_f32_e32 v98, v98, v99
	v_add_f32_e32 v99, v100, v101
	v_add_f32_e32 v98, v98, v99
	global_store_dwordx4 v[102:103], v[88:91], off
	s_waitcnt vmcnt(11)
	v_lshlrev_b32_e32 v99, 16, v208
	v_and_b32_e32 v92, 0xffff0000, v208
	v_lshlrev_b32_e32 v100, 16, v209
	v_and_b32_e32 v93, 0xffff0000, v209
	v_lshlrev_b32_e32 v101, 16, v210
	v_and_b32_e32 v94, 0xffff0000, v210
	v_lshlrev_b32_e32 v104, 16, v211
	v_and_b32_e32 v95, 0xffff0000, v211
	v_add_f32_e32 v85, v85, v92
	v_add_f32_e32 v87, v87, v93
	v_add_f32_e32 v93, v81, v94
	v_add_f32_e32 v95, v83, v95
	v_add_f32_e32 v84, v84, v99
	v_add_f32_e32 v86, v86, v100
	v_add_f32_e32 v92, v80, v101
	v_add_f32_e32 v94, v82, v104
	v_mul_f32_e32 v80, v85, v85
	v_mul_f32_e32 v81, v87, v87
	v_mul_f32_e32 v82, v93, v93
	v_mul_f32_e32 v83, v95, v95
	v_fmac_f32_e32 v80, v84, v84
	v_fmac_f32_e32 v81, v86, v86
	v_fmac_f32_e32 v82, v92, v92
	v_fmac_f32_e32 v83, v94, v94
	v_add_f32_e32 v80, v80, v81
	v_add_f32_e32 v81, v82, v83
	v_add_f32_e32 v80, v80, v81
	v_add_f32_e32 v80, v98, v80
	ds_bpermute_b32 v81, v120, v80
	v_cvt_pk_bf16_f32 v82, v84, v85
	v_cvt_pk_bf16_f32 v83, v86, v87
	v_cvt_pk_bf16_f32 v84, v92, v93
	v_cvt_pk_bf16_f32 v85, v94, v95
	s_waitcnt lgkmcnt(0)
	v_add_f32_e32 v80, v80, v81
	ds_bpermute_b32 v81, v114, v80
	global_store_dwordx4 v[102:103], v[82:85], off offset:256
	s_and_saveexec_b64 s[40:41], s[4:5]
	s_cbranch_execz .LBB0_1566
	v_lshlrev_b64 v[82:83], 6, v[96:97]
	v_lshl_add_u64 v[82:83], s[18:19], 0, v[82:83]
	v_lshl_add_u64 v[82:83], s[38:39], 2, v[82:83]
	s_lshl_b32 s0, s52, 2
	v_lshl_add_u64 v[82:83], v[82:83], 0, s[0:1]
	s_waitcnt lgkmcnt(0)
	v_add_f32_e32 v80, v80, v81
	global_store_dword v[82:83], v80, off
.LBB0_1566:
	s_or_b64 exec, exec, s[40:41]
	v_or_b32_e32 v80, 48, v148
	s_waitcnt lgkmcnt(0)
	v_ashrrev_i32_e32 v81, 31, v80
	v_lshlrev_b64 v[82:83], 11, v[80:81]
	v_lshl_add_u64 v[82:83], s[14:15], 0, v[82:83]
	v_lshl_add_u64 v[86:87], v[146:147], 1, v[82:83]
	s_mov_b64 s[100:101], 0x50000
	v_lshl_add_u64 v[230:231], v[232:233], 0, s[100:101]
	global_load_dwordx4 v[204:207], v[230:231], off
	global_load_dwordx4 v[208:211], v[230:231], off offset:256
	s_waitcnt vmcnt(13)
	v_lshlrev_b32_e32 v88, 16, v212
	v_and_b32_e32 v82, 0xffff0000, v212
	v_lshlrev_b32_e32 v89, 16, v213
	v_and_b32_e32 v83, 0xffff0000, v213
	v_lshlrev_b32_e32 v90, 16, v214
	v_and_b32_e32 v84, 0xffff0000, v214
	v_lshlrev_b32_e32 v91, 16, v215
	v_and_b32_e32 v85, 0xffff0000, v215
	v_add_f32_e32 v88, v76, v88
	v_add_f32_e32 v82, v77, v82
	v_add_f32_e32 v89, v78, v89
	v_add_f32_e32 v83, v79, v83
	v_add_f32_e32 v90, v72, v90
	v_add_f32_e32 v84, v73, v84
	v_add_f32_e32 v91, v74, v91
	v_add_f32_e32 v85, v75, v85
	v_cvt_pk_bf16_f32 v72, v88, v82
	v_cvt_pk_bf16_f32 v73, v89, v83
	v_cvt_pk_bf16_f32 v74, v90, v84
	v_cvt_pk_bf16_f32 v75, v91, v85
	v_mul_f32_e32 v82, v82, v82
	v_mul_f32_e32 v83, v83, v83
	v_mul_f32_e32 v84, v84, v84
	v_mul_f32_e32 v85, v85, v85
	v_fmac_f32_e32 v82, v88, v88
	v_fmac_f32_e32 v83, v89, v89
	v_fmac_f32_e32 v84, v90, v90
	v_fmac_f32_e32 v85, v91, v91
	v_add_f32_e32 v82, v82, v83
	v_add_f32_e32 v83, v84, v85
	v_add_f32_e32 v82, v82, v83
	global_store_dwordx4 v[86:87], v[72:75], off
	s_waitcnt vmcnt(13)
	v_lshlrev_b32_e32 v83, 16, v216
	v_and_b32_e32 v76, 0xffff0000, v216
	v_lshlrev_b32_e32 v84, 16, v217
	v_and_b32_e32 v77, 0xffff0000, v217
	v_lshlrev_b32_e32 v85, 16, v218
	v_and_b32_e32 v78, 0xffff0000, v218
	v_lshlrev_b32_e32 v88, 16, v219
	v_and_b32_e32 v79, 0xffff0000, v219
	v_add_f32_e32 v69, v69, v76
	v_add_f32_e32 v71, v71, v77
	v_add_f32_e32 v77, v65, v78
	v_add_f32_e32 v79, v67, v79
	v_add_f32_e32 v68, v68, v83
	v_add_f32_e32 v70, v70, v84
	v_add_f32_e32 v76, v64, v85
	v_add_f32_e32 v78, v66, v88
	v_mul_f32_e32 v64, v69, v69
	v_mul_f32_e32 v65, v71, v71
	v_mul_f32_e32 v66, v77, v77
	v_mul_f32_e32 v67, v79, v79
	v_fmac_f32_e32 v64, v68, v68
	v_fmac_f32_e32 v65, v70, v70
	v_fmac_f32_e32 v66, v76, v76
	v_fmac_f32_e32 v67, v78, v78
	v_add_f32_e32 v64, v64, v65
	v_add_f32_e32 v65, v66, v67
	v_add_f32_e32 v64, v64, v65
	v_add_f32_e32 v64, v82, v64
	ds_bpermute_b32 v65, v120, v64
	v_cvt_pk_bf16_f32 v66, v68, v69
	v_cvt_pk_bf16_f32 v67, v70, v71
	v_cvt_pk_bf16_f32 v68, v76, v77
	v_cvt_pk_bf16_f32 v69, v78, v79
	s_waitcnt lgkmcnt(0)
	v_add_f32_e32 v64, v64, v65
	ds_bpermute_b32 v65, v114, v64
	global_store_dwordx4 v[86:87], v[66:69], off offset:256
	s_and_saveexec_b64 s[40:41], s[4:5]
	s_cbranch_execz .LBB0_1568
	v_lshlrev_b64 v[66:67], 6, v[80:81]
	v_lshl_add_u64 v[66:67], s[18:19], 0, v[66:67]
	v_lshl_add_u64 v[66:67], s[38:39], 2, v[66:67]
	s_lshl_b32 s0, s52, 2
	v_lshl_add_u64 v[66:67], v[66:67], 0, s[0:1]
	s_waitcnt lgkmcnt(0)
	v_add_f32_e32 v64, v64, v65
	global_store_dword v[66:67], v64, off
.LBB0_1568:
	s_or_b64 exec, exec, s[40:41]
	v_add_u32_e32 v64, 0x80, v148
	s_waitcnt lgkmcnt(0)
	v_ashrrev_i32_e32 v65, 31, v64
	v_lshlrev_b64 v[66:67], 11, v[64:65]
	v_lshl_add_u64 v[66:67], s[14:15], 0, v[66:67]
	v_lshl_add_u64 v[70:71], v[146:147], 1, v[66:67]
	s_mov_b64 s[100:101], 0x58000
	v_lshl_add_u64 v[230:231], v[232:233], 0, s[100:101]
	global_load_dwordx4 v[212:215], v[230:231], off
	global_load_dwordx4 v[216:219], v[230:231], off offset:256
	s_waitcnt vmcnt(13)
	v_lshlrev_b32_e32 v72, 16, v188
	v_and_b32_e32 v66, 0xffff0000, v188
	v_lshlrev_b32_e32 v73, 16, v189
	v_and_b32_e32 v67, 0xffff0000, v189
	v_lshlrev_b32_e32 v74, 16, v190
	v_and_b32_e32 v68, 0xffff0000, v190
	v_lshlrev_b32_e32 v75, 16, v191
	v_and_b32_e32 v69, 0xffff0000, v191
	v_add_f32_e32 v72, v60, v72
	v_add_f32_e32 v66, v61, v66
	v_add_f32_e32 v73, v62, v73
	v_add_f32_e32 v67, v63, v67
	v_add_f32_e32 v74, v56, v74
	v_add_f32_e32 v68, v57, v68
	v_add_f32_e32 v75, v58, v75
	v_add_f32_e32 v69, v59, v69
	v_cvt_pk_bf16_f32 v56, v72, v66
	v_cvt_pk_bf16_f32 v57, v73, v67
	v_cvt_pk_bf16_f32 v58, v74, v68
	v_cvt_pk_bf16_f32 v59, v75, v69
	v_mul_f32_e32 v66, v66, v66
	v_mul_f32_e32 v67, v67, v67
	v_mul_f32_e32 v68, v68, v68
	v_mul_f32_e32 v69, v69, v69
	v_fmac_f32_e32 v66, v72, v72
	v_fmac_f32_e32 v67, v73, v73
	v_fmac_f32_e32 v68, v74, v74
	v_fmac_f32_e32 v69, v75, v75
	v_add_f32_e32 v66, v66, v67
	v_add_f32_e32 v67, v68, v69
	v_add_f32_e32 v66, v66, v67
	global_store_dwordx4 v[70:71], v[56:59], off
	s_waitcnt vmcnt(13)
	v_lshlrev_b32_e32 v67, 16, v192
	v_and_b32_e32 v60, 0xffff0000, v192
	v_lshlrev_b32_e32 v68, 16, v193
	v_and_b32_e32 v61, 0xffff0000, v193
	v_lshlrev_b32_e32 v69, 16, v194
	v_and_b32_e32 v62, 0xffff0000, v194
	v_lshlrev_b32_e32 v72, 16, v195
	v_and_b32_e32 v63, 0xffff0000, v195
	v_add_f32_e32 v53, v53, v60
	v_add_f32_e32 v55, v55, v61
	v_add_f32_e32 v61, v49, v62
	v_add_f32_e32 v63, v51, v63
	v_add_f32_e32 v52, v52, v67
	v_add_f32_e32 v54, v54, v68
	v_add_f32_e32 v60, v48, v69
	v_add_f32_e32 v62, v50, v72
	v_mul_f32_e32 v48, v53, v53
	v_mul_f32_e32 v49, v55, v55
	v_mul_f32_e32 v50, v61, v61
	v_mul_f32_e32 v51, v63, v63
	v_fmac_f32_e32 v48, v52, v52
	v_fmac_f32_e32 v49, v54, v54
	v_fmac_f32_e32 v50, v60, v60
	v_fmac_f32_e32 v51, v62, v62
	v_add_f32_e32 v48, v48, v49
	v_add_f32_e32 v49, v50, v51
	v_add_f32_e32 v48, v48, v49
	v_add_f32_e32 v48, v66, v48
	ds_bpermute_b32 v49, v120, v48
	v_cvt_pk_bf16_f32 v50, v52, v53
	v_cvt_pk_bf16_f32 v51, v54, v55
	v_cvt_pk_bf16_f32 v52, v60, v61
	v_cvt_pk_bf16_f32 v53, v62, v63
	s_waitcnt lgkmcnt(0)
	v_add_f32_e32 v48, v48, v49
	ds_bpermute_b32 v49, v114, v48
	global_store_dwordx4 v[70:71], v[50:53], off offset:256
	s_and_saveexec_b64 s[40:41], s[4:5]
	s_cbranch_execz .LBB0_1570
	v_lshlrev_b64 v[50:51], 6, v[64:65]
	v_lshl_add_u64 v[50:51], s[18:19], 0, v[50:51]
	v_lshl_add_u64 v[50:51], s[38:39], 2, v[50:51]
	s_lshl_b32 s0, s52, 2
	v_lshl_add_u64 v[50:51], v[50:51], 0, s[0:1]
	s_waitcnt lgkmcnt(0)
	v_add_f32_e32 v48, v48, v49
	global_store_dword v[50:51], v48, off
.LBB0_1570:
	s_or_b64 exec, exec, s[40:41]
	v_add_u32_e32 v48, 0x90, v148
	s_waitcnt lgkmcnt(0)
	v_ashrrev_i32_e32 v49, 31, v48
	v_lshlrev_b64 v[50:51], 11, v[48:49]
	v_lshl_add_u64 v[50:51], s[14:15], 0, v[50:51]
	v_lshl_add_u64 v[54:55], v[146:147], 1, v[50:51]
	s_waitcnt vmcnt(11)
	v_lshlrev_b32_e32 v56, 16, v196
	v_and_b32_e32 v50, 0xffff0000, v196
	v_lshlrev_b32_e32 v57, 16, v197
	v_and_b32_e32 v51, 0xffff0000, v197
	v_lshlrev_b32_e32 v58, 16, v198
	v_and_b32_e32 v52, 0xffff0000, v198
	v_lshlrev_b32_e32 v59, 16, v199
	v_and_b32_e32 v53, 0xffff0000, v199
	v_add_f32_e32 v56, v44, v56
	v_add_f32_e32 v50, v45, v50
	v_add_f32_e32 v57, v46, v57
	v_add_f32_e32 v51, v47, v51
	v_add_f32_e32 v58, v40, v58
	v_add_f32_e32 v52, v41, v52
	v_add_f32_e32 v59, v42, v59
	v_add_f32_e32 v53, v43, v53
	v_cvt_pk_bf16_f32 v40, v56, v50
	v_cvt_pk_bf16_f32 v41, v57, v51
	v_cvt_pk_bf16_f32 v42, v58, v52
	v_cvt_pk_bf16_f32 v43, v59, v53
	v_mul_f32_e32 v50, v50, v50
	v_mul_f32_e32 v51, v51, v51
	v_mul_f32_e32 v52, v52, v52
	v_mul_f32_e32 v53, v53, v53
	v_fmac_f32_e32 v50, v56, v56
	v_fmac_f32_e32 v51, v57, v57
	v_fmac_f32_e32 v52, v58, v58
	v_fmac_f32_e32 v53, v59, v59
	v_add_f32_e32 v50, v50, v51
	v_add_f32_e32 v51, v52, v53
	v_add_f32_e32 v50, v50, v51
	global_store_dwordx4 v[54:55], v[40:43], off
	s_waitcnt vmcnt(11)
	v_lshlrev_b32_e32 v51, 16, v200
	v_and_b32_e32 v44, 0xffff0000, v200
	v_lshlrev_b32_e32 v52, 16, v201
	v_and_b32_e32 v45, 0xffff0000, v201
	v_lshlrev_b32_e32 v53, 16, v202
	v_and_b32_e32 v46, 0xffff0000, v202
	v_lshlrev_b32_e32 v56, 16, v203
	v_and_b32_e32 v47, 0xffff0000, v203
	v_add_f32_e32 v37, v37, v44
	v_add_f32_e32 v39, v39, v45
	v_add_f32_e32 v45, v33, v46
	v_add_f32_e32 v47, v35, v47
	v_add_f32_e32 v36, v36, v51
	v_add_f32_e32 v38, v38, v52
	v_add_f32_e32 v44, v32, v53
	v_add_f32_e32 v46, v34, v56
	v_mul_f32_e32 v32, v37, v37
	v_mul_f32_e32 v33, v39, v39
	v_mul_f32_e32 v34, v45, v45
	v_mul_f32_e32 v35, v47, v47
	v_fmac_f32_e32 v32, v36, v36
	v_fmac_f32_e32 v33, v38, v38
	v_fmac_f32_e32 v34, v44, v44
	v_fmac_f32_e32 v35, v46, v46
	v_add_f32_e32 v32, v32, v33
	v_add_f32_e32 v33, v34, v35
	v_add_f32_e32 v32, v32, v33
	v_add_f32_e32 v32, v50, v32
	ds_bpermute_b32 v33, v120, v32
	v_cvt_pk_bf16_f32 v34, v36, v37
	v_cvt_pk_bf16_f32 v35, v38, v39
	v_cvt_pk_bf16_f32 v36, v44, v45
	v_cvt_pk_bf16_f32 v37, v46, v47
	s_waitcnt lgkmcnt(0)
	v_add_f32_e32 v32, v32, v33
	ds_bpermute_b32 v33, v114, v32
	global_store_dwordx4 v[54:55], v[34:37], off offset:256
	s_and_saveexec_b64 s[40:41], s[4:5]
	s_cbranch_execz .LBB0_1572
	v_lshlrev_b64 v[34:35], 6, v[48:49]
	v_lshl_add_u64 v[34:35], s[18:19], 0, v[34:35]
	v_lshl_add_u64 v[34:35], s[38:39], 2, v[34:35]
	s_lshl_b32 s0, s52, 2
	v_lshl_add_u64 v[34:35], v[34:35], 0, s[0:1]
	s_waitcnt lgkmcnt(0)
	v_add_f32_e32 v32, v32, v33
	global_store_dword v[34:35], v32, off
.LBB0_1572:
	s_or_b64 exec, exec, s[40:41]
	v_add_u32_e32 v32, 0xa0, v148
	s_waitcnt lgkmcnt(0)
	v_ashrrev_i32_e32 v33, 31, v32
	v_lshlrev_b64 v[34:35], 11, v[32:33]
	v_lshl_add_u64 v[34:35], s[14:15], 0, v[34:35]
	v_lshl_add_u64 v[38:39], v[146:147], 1, v[34:35]
	s_waitcnt vmcnt(9)
	v_lshlrev_b32_e32 v40, 16, v204
	v_and_b32_e32 v34, 0xffff0000, v204
	v_lshlrev_b32_e32 v41, 16, v205
	v_and_b32_e32 v35, 0xffff0000, v205
	v_lshlrev_b32_e32 v42, 16, v206
	v_and_b32_e32 v36, 0xffff0000, v206
	v_lshlrev_b32_e32 v43, 16, v207
	v_and_b32_e32 v37, 0xffff0000, v207
	v_add_f32_e32 v40, v28, v40
	v_add_f32_e32 v34, v29, v34
	v_add_f32_e32 v41, v30, v41
	v_add_f32_e32 v35, v31, v35
	v_add_f32_e32 v42, v24, v42
	v_add_f32_e32 v36, v25, v36
	v_add_f32_e32 v43, v26, v43
	v_add_f32_e32 v37, v27, v37
	v_cvt_pk_bf16_f32 v24, v40, v34
	v_cvt_pk_bf16_f32 v25, v41, v35
	v_cvt_pk_bf16_f32 v26, v42, v36
	v_cvt_pk_bf16_f32 v27, v43, v37
	v_mul_f32_e32 v34, v34, v34
	v_mul_f32_e32 v35, v35, v35
	v_mul_f32_e32 v36, v36, v36
	v_mul_f32_e32 v37, v37, v37
	v_fmac_f32_e32 v34, v40, v40
	v_fmac_f32_e32 v35, v41, v41
	v_fmac_f32_e32 v36, v42, v42
	v_fmac_f32_e32 v37, v43, v43
	v_add_f32_e32 v34, v34, v35
	v_add_f32_e32 v35, v36, v37
	v_add_f32_e32 v34, v34, v35
	global_store_dwordx4 v[38:39], v[24:27], off
	s_waitcnt vmcnt(9)
	v_lshlrev_b32_e32 v35, 16, v208
	v_and_b32_e32 v28, 0xffff0000, v208
	v_lshlrev_b32_e32 v36, 16, v209
	v_and_b32_e32 v29, 0xffff0000, v209
	v_lshlrev_b32_e32 v37, 16, v210
	v_and_b32_e32 v30, 0xffff0000, v210
	v_lshlrev_b32_e32 v40, 16, v211
	v_and_b32_e32 v31, 0xffff0000, v211
	v_add_f32_e32 v21, v21, v28
	v_add_f32_e32 v23, v23, v29
	v_add_f32_e32 v29, v17, v30
	v_add_f32_e32 v31, v19, v31
	v_add_f32_e32 v20, v20, v35
	v_add_f32_e32 v22, v22, v36
	v_add_f32_e32 v28, v16, v37
	v_add_f32_e32 v30, v18, v40
	v_mul_f32_e32 v16, v21, v21
	v_mul_f32_e32 v17, v23, v23
	v_mul_f32_e32 v18, v29, v29
	v_mul_f32_e32 v19, v31, v31
	v_fmac_f32_e32 v16, v20, v20
	v_fmac_f32_e32 v17, v22, v22
	v_fmac_f32_e32 v18, v28, v28
	v_fmac_f32_e32 v19, v30, v30
	v_add_f32_e32 v16, v16, v17
	v_add_f32_e32 v17, v18, v19
	v_add_f32_e32 v16, v16, v17
	v_add_f32_e32 v16, v34, v16
	ds_bpermute_b32 v17, v120, v16
	v_cvt_pk_bf16_f32 v18, v20, v21
	v_cvt_pk_bf16_f32 v19, v22, v23
	v_cvt_pk_bf16_f32 v20, v28, v29
	v_cvt_pk_bf16_f32 v21, v30, v31
	s_waitcnt lgkmcnt(0)
	v_add_f32_e32 v16, v16, v17
	ds_bpermute_b32 v17, v114, v16
	global_store_dwordx4 v[38:39], v[18:21], off offset:256
	s_and_saveexec_b64 s[40:41], s[4:5]
	s_cbranch_execz .LBB0_1574
	v_lshlrev_b64 v[18:19], 6, v[32:33]
	v_lshl_add_u64 v[18:19], s[18:19], 0, v[18:19]
	v_lshl_add_u64 v[18:19], s[38:39], 2, v[18:19]
	s_lshl_b32 s0, s52, 2
	v_lshl_add_u64 v[18:19], v[18:19], 0, s[0:1]
	s_waitcnt lgkmcnt(0)
	v_add_f32_e32 v16, v16, v17
	global_store_dword v[18:19], v16, off
.LBB0_1574:
	s_or_b64 exec, exec, s[40:41]
	v_add_u32_e32 v16, 0xb0, v148
	s_waitcnt lgkmcnt(0)
	v_ashrrev_i32_e32 v17, 31, v16
	v_lshlrev_b64 v[18:19], 11, v[16:17]
	v_lshl_add_u64 v[18:19], s[14:15], 0, v[18:19]
	v_lshl_add_u64 v[22:23], v[146:147], 1, v[18:19]
	s_waitcnt vmcnt(7)
	v_lshlrev_b32_e32 v24, 16, v212
	v_and_b32_e32 v18, 0xffff0000, v212
	v_lshlrev_b32_e32 v25, 16, v213
	v_and_b32_e32 v19, 0xffff0000, v213
	v_lshlrev_b32_e32 v26, 16, v214
	v_and_b32_e32 v20, 0xffff0000, v214
	v_lshlrev_b32_e32 v27, 16, v215
	v_and_b32_e32 v21, 0xffff0000, v215
	v_add_f32_e32 v24, v12, v24
	v_add_f32_e32 v18, v13, v18
	v_add_f32_e32 v25, v14, v25
	v_add_f32_e32 v19, v15, v19
	v_add_f32_e32 v26, v8, v26
	v_add_f32_e32 v20, v9, v20
	v_add_f32_e32 v27, v10, v27
	v_add_f32_e32 v21, v11, v21
	v_cvt_pk_bf16_f32 v8, v24, v18
	v_cvt_pk_bf16_f32 v9, v25, v19
	v_cvt_pk_bf16_f32 v10, v26, v20
	v_cvt_pk_bf16_f32 v11, v27, v21
	v_mul_f32_e32 v18, v18, v18
	v_mul_f32_e32 v19, v19, v19
	v_mul_f32_e32 v20, v20, v20
	v_mul_f32_e32 v21, v21, v21
	v_fmac_f32_e32 v18, v24, v24
	v_fmac_f32_e32 v19, v25, v25
	v_fmac_f32_e32 v20, v26, v26
	v_fmac_f32_e32 v21, v27, v27
	v_add_f32_e32 v18, v18, v19
	v_add_f32_e32 v19, v20, v21
	v_add_f32_e32 v18, v18, v19
	global_store_dwordx4 v[22:23], v[8:11], off
	s_waitcnt vmcnt(7)
	v_lshlrev_b32_e32 v19, 16, v216
	v_and_b32_e32 v12, 0xffff0000, v216
	v_lshlrev_b32_e32 v20, 16, v217
	v_and_b32_e32 v13, 0xffff0000, v217
	v_lshlrev_b32_e32 v21, 16, v218
	v_and_b32_e32 v14, 0xffff0000, v218
	v_lshlrev_b32_e32 v24, 16, v219
	v_and_b32_e32 v15, 0xffff0000, v219
	v_add_f32_e32 v5, v5, v12
	v_add_f32_e32 v7, v7, v13
	v_add_f32_e32 v13, v1, v14
	v_add_f32_e32 v15, v3, v15
	v_add_f32_e32 v4, v4, v19
	v_add_f32_e32 v6, v6, v20
	v_add_f32_e32 v12, v0, v21
	v_add_f32_e32 v14, v2, v24
	v_mul_f32_e32 v0, v5, v5
	v_mul_f32_e32 v1, v7, v7
	v_mul_f32_e32 v2, v13, v13
	v_mul_f32_e32 v3, v15, v15
	v_fmac_f32_e32 v0, v4, v4
	v_fmac_f32_e32 v1, v6, v6
	v_fmac_f32_e32 v2, v12, v12
	v_fmac_f32_e32 v3, v14, v14
	v_add_f32_e32 v0, v0, v1
	v_add_f32_e32 v1, v2, v3
	v_add_f32_e32 v0, v0, v1
	v_add_f32_e32 v0, v18, v0
	ds_bpermute_b32 v1, v120, v0
	v_cvt_pk_bf16_f32 v2, v4, v5
	v_cvt_pk_bf16_f32 v3, v6, v7
	v_cvt_pk_bf16_f32 v4, v12, v13
	v_cvt_pk_bf16_f32 v5, v14, v15
	s_waitcnt lgkmcnt(0)
	v_add_f32_e32 v0, v0, v1
	ds_bpermute_b32 v1, v114, v0
	global_store_dwordx4 v[22:23], v[2:5], off offset:256
	s_and_saveexec_b64 s[40:41], s[4:5]
	s_cbranch_execz .LBB0_1576
	v_lshlrev_b64 v[2:3], 6, v[16:17]
	v_lshl_add_u64 v[2:3], s[18:19], 0, v[2:3]
	v_lshl_add_u64 v[2:3], s[38:39], 2, v[2:3]
	s_lshl_b32 s0, s52, 2
	v_lshl_add_u64 v[2:3], v[2:3], 0, s[0:1]
	s_waitcnt lgkmcnt(0)
	v_add_f32_e32 v0, v0, v1
	global_store_dword v[2:3], v0, off

.LBB0_1736:
	v_lshl_add_u32 v148, s12, 8, v150
	v_ashrrev_i32_e32 v149, 31, v148
	v_lshl_or_b32 v146, s8, 8, v152
	v_lshlrev_b64 v[158:159], 11, v[148:149]
	v_ashrrev_i32_e32 v147, 31, v146
	v_lshl_add_u64 v[158:159], s[14:15], 0, v[158:159]
	v_lshl_add_u64 v[162:163], v[146:147], 1, v[158:159]
	v_mov_b32_e32 v232, v162
	v_mov_b32_e32 v233, v163
	global_load_dwordx4 v[188:191], v[232:233], off
	global_load_dwordx4 v[192:195], v[232:233], off offset:256
	s_mov_b64 s[100:101], 0x8000
	v_lshl_add_u64 v[230:231], v[232:233], 0, s[100:101]
	global_load_dwordx4 v[196:199], v[230:231], off
	global_load_dwordx4 v[200:203], v[230:231], off offset:256
	s_mov_b64 s[100:101], 0x10000
	v_lshl_add_u64 v[230:231], v[232:233], 0, s[100:101]
	global_load_dwordx4 v[204:207], v[230:231], off
	global_load_dwordx4 v[208:211], v[230:231], off offset:256
	s_mov_b64 s[100:101], 0x18000
	v_lshl_add_u64 v[230:231], v[232:233], 0, s[100:101]
	global_load_dwordx4 v[212:215], v[230:231], off
	global_load_dwordx4 v[216:219], v[230:231], off offset:256
	v_and_b32_e32 v169, 64, v157
	v_add_u32_e32 v169, 64, v169
	v_xor_b32_e32 v170, 32, v157
	s_lshl_b32 s30, s8, 2
	s_ashr_i32 s31, s30, 31
	s_waitcnt vmcnt(7)
	v_lshlrev_b32_e32 v164, 16, v188
	v_and_b32_e32 v158, 0xffff0000, v188
	v_lshlrev_b32_e32 v165, 16, v189
	v_and_b32_e32 v159, 0xffff0000, v189
	v_lshlrev_b32_e32 v166, 16, v190
	v_and_b32_e32 v160, 0xffff0000, v190
	v_lshlrev_b32_e32 v167, 16, v191
	v_and_b32_e32 v161, 0xffff0000, v191
	v_add_f32_e32 v164, v124, v164
	v_add_f32_e32 v168, v125, v158
	v_add_f32_e32 v126, v126, v165
	v_add_f32_e32 v127, v127, v159
	v_add_f32_e32 v165, v120, v166
	v_add_f32_e32 v121, v121, v160
	v_add_f32_e32 v166, v122, v167
	v_add_f32_e32 v167, v123, v161
	v_cvt_pk_bf16_f32 v122, v164, v168
	v_cvt_pk_bf16_f32 v123, v126, v127
	v_cvt_pk_bf16_f32 v124, v165, v121
	v_cvt_pk_bf16_f32 v125, v166, v167
	v_mul_f32_e32 v168, v168, v168
	v_mul_f32_e32 v127, v127, v127
	v_mul_f32_e32 v121, v121, v121
	v_mul_f32_e32 v167, v167, v167
	v_fmac_f32_e32 v168, v164, v164
	v_fmac_f32_e32 v127, v126, v126
	v_fmac_f32_e32 v121, v165, v165
	v_fmac_f32_e32 v167, v166, v166
	v_add_f32_e32 v126, v168, v127
	v_add_f32_e32 v121, v121, v167
	v_add_f32_e32 v121, v126, v121
	v_xor_b32_e32 v120, 16, v157
	v_cmp_lt_i32_e32 vcc, v120, v169
	global_store_dwordx4 v[162:163], v[122:125], off
	s_waitcnt vmcnt(7)
	v_lshlrev_b32_e32 v126, 16, v192
	v_and_b32_e32 v127, 0xffff0000, v192
	v_lshlrev_b32_e32 v158, 16, v193
	v_and_b32_e32 v159, 0xffff0000, v193
	v_lshlrev_b32_e32 v164, 16, v194
	v_and_b32_e32 v160, 0xffff0000, v194
	v_lshlrev_b32_e32 v165, 16, v195
	v_and_b32_e32 v161, 0xffff0000, v195
	v_add_f32_e32 v117, v117, v127
	v_add_f32_e32 v119, v119, v159
	v_add_f32_e32 v127, v113, v160
	v_add_f32_e32 v115, v115, v161
	v_add_f32_e32 v116, v116, v126
	v_add_f32_e32 v118, v118, v158
	v_add_f32_e32 v126, v112, v164
	v_add_f32_e32 v158, v114, v165
	v_mul_f32_e32 v112, v117, v117
	v_mul_f32_e32 v113, v119, v119
	v_mul_f32_e32 v114, v127, v127
	v_mul_f32_e32 v159, v115, v115
	v_fmac_f32_e32 v112, v116, v116
	v_fmac_f32_e32 v113, v118, v118
	v_fmac_f32_e32 v114, v126, v126
	v_fmac_f32_e32 v159, v158, v158
	v_add_f32_e32 v112, v112, v113
	v_add_f32_e32 v113, v114, v159
	v_cndmask_b32_e32 v120, v157, v120, vcc
	v_add_f32_e32 v112, v112, v113
	v_lshlrev_b32_e32 v120, 2, v120
	v_add_f32_e32 v112, v121, v112
	ds_bpermute_b32 v113, v120, v112
	v_cmp_lt_i32_e32 vcc, v170, v169
	v_cvt_pk_bf16_f32 v116, v116, v117
	v_cvt_pk_bf16_f32 v117, v118, v119
	v_cvt_pk_bf16_f32 v118, v126, v127
	s_waitcnt lgkmcnt(0)
	v_add_f32_e32 v112, v112, v113
	v_cvt_pk_bf16_f32 v119, v158, v115
	v_cndmask_b32_e32 v114, v157, v170, vcc
	v_lshlrev_b32_e32 v114, 2, v114
	ds_bpermute_b32 v113, v114, v112
	global_store_dwordx4 v[162:163], v[116:119], off offset:256
	s_and_saveexec_b64 s[36:37], s[4:5]
	s_cbranch_execz .LBB0_1738
	v_lshlrev_b64 v[116:117], 6, v[148:149]
	v_lshl_add_u64 v[116:117], s[18:19], 0, v[116:117]
	v_lshl_add_u64 v[116:117], s[30:31], 2, v[116:117]
	s_lshl_b32 s8, s46, 2
	v_lshl_add_u64 v[116:117], v[116:117], 0, s[8:9]
	s_waitcnt lgkmcnt(0)
	v_add_f32_e32 v112, v112, v113
	global_store_dword v[116:117], v112, off
.LBB0_1738:
	s_or_b64 exec, exec, s[36:37]
	v_or_b32_e32 v112, 16, v148
	s_waitcnt lgkmcnt(0)
	v_ashrrev_i32_e32 v113, 31, v112
	v_lshlrev_b64 v[116:117], 11, v[112:113]
	v_lshl_add_u64 v[116:117], s[14:15], 0, v[116:117]
	v_lshl_add_u64 v[122:123], v[146:147], 1, v[116:117]
	s_mov_b64 s[100:101], 0x40000
	v_lshl_add_u64 v[230:231], v[232:233], 0, s[100:101]
	global_load_dwordx4 v[188:191], v[230:231], off
	global_load_dwordx4 v[192:195], v[230:231], off offset:256
	s_waitcnt vmcnt(9)
	v_lshlrev_b32_e32 v115, 16, v196
	v_and_b32_e32 v116, 0xffff0000, v196
	v_lshlrev_b32_e32 v121, 16, v197
	v_and_b32_e32 v117, 0xffff0000, v197
	v_lshlrev_b32_e32 v124, 16, v198
	v_and_b32_e32 v118, 0xffff0000, v198
	v_lshlrev_b32_e32 v125, 16, v199
	v_and_b32_e32 v119, 0xffff0000, v199
	v_add_f32_e32 v115, v108, v115
	v_add_f32_e32 v116, v109, v116
	v_add_f32_e32 v121, v110, v121
	v_add_f32_e32 v117, v111, v117
	v_add_f32_e32 v124, v104, v124
	v_add_f32_e32 v118, v105, v118
	v_add_f32_e32 v125, v106, v125
	v_add_f32_e32 v119, v107, v119
	v_cvt_pk_bf16_f32 v104, v115, v116
	v_cvt_pk_bf16_f32 v105, v121, v117
	v_cvt_pk_bf16_f32 v106, v124, v118
	v_cvt_pk_bf16_f32 v107, v125, v119
	v_mul_f32_e32 v116, v116, v116
	v_mul_f32_e32 v117, v117, v117
	v_mul_f32_e32 v118, v118, v118
	v_mul_f32_e32 v119, v119, v119
	v_fmac_f32_e32 v116, v115, v115
	v_fmac_f32_e32 v117, v121, v121
	v_fmac_f32_e32 v118, v124, v124
	v_fmac_f32_e32 v119, v125, v125
	v_add_f32_e32 v115, v116, v117
	v_add_f32_e32 v116, v118, v119
	v_add_f32_e32 v115, v115, v116
	global_store_dwordx4 v[122:123], v[104:107], off
	s_waitcnt vmcnt(9)
	v_lshlrev_b32_e32 v116, 16, v200
	v_and_b32_e32 v108, 0xffff0000, v200
	v_lshlrev_b32_e32 v117, 16, v201
	v_and_b32_e32 v109, 0xffff0000, v201
	v_lshlrev_b32_e32 v118, 16, v202
	v_and_b32_e32 v110, 0xffff0000, v202
	v_lshlrev_b32_e32 v119, 16, v203
	v_and_b32_e32 v111, 0xffff0000, v203
	v_add_f32_e32 v101, v101, v108
	v_add_f32_e32 v103, v103, v109
	v_add_f32_e32 v109, v97, v110
	v_add_f32_e32 v111, v99, v111
	v_add_f32_e32 v100, v100, v116
	v_add_f32_e32 v102, v102, v117
	v_add_f32_e32 v108, v96, v118
	v_add_f32_e32 v110, v98, v119
	v_mul_f32_e32 v96, v101, v101
	v_mul_f32_e32 v97, v103, v103
	v_mul_f32_e32 v98, v109, v109
	v_mul_f32_e32 v99, v111, v111
	v_fmac_f32_e32 v96, v100, v100
	v_fmac_f32_e32 v97, v102, v102
	v_fmac_f32_e32 v98, v108, v108
	v_fmac_f32_e32 v99, v110, v110
	v_add_f32_e32 v96, v96, v97
	v_add_f32_e32 v97, v98, v99
	v_add_f32_e32 v96, v96, v97
	v_add_f32_e32 v96, v115, v96
	ds_bpermute_b32 v97, v120, v96
	v_cvt_pk_bf16_f32 v98, v100, v101
	v_cvt_pk_bf16_f32 v99, v102, v103
	v_cvt_pk_bf16_f32 v100, v108, v109
	v_cvt_pk_bf16_f32 v101, v110, v111
	s_waitcnt lgkmcnt(0)
	v_add_f32_e32 v96, v96, v97
	ds_bpermute_b32 v97, v114, v96
	global_store_dwordx4 v[122:123], v[98:101], off offset:256
	s_and_saveexec_b64 s[36:37], s[4:5]
	s_cbranch_execz .LBB0_1740
	v_lshlrev_b64 v[98:99], 6, v[112:113]
	v_lshl_add_u64 v[98:99], s[18:19], 0, v[98:99]
	v_lshl_add_u64 v[98:99], s[30:31], 2, v[98:99]
	s_lshl_b32 s8, s46, 2
	v_lshl_add_u64 v[98:99], v[98:99], 0, s[8:9]
	s_waitcnt lgkmcnt(0)
	v_add_f32_e32 v96, v96, v97
	global_store_dword v[98:99], v96, off
.LBB0_1740:
	s_or_b64 exec, exec, s[36:37]
	v_or_b32_e32 v96, 32, v148
	s_waitcnt lgkmcnt(0)
	v_ashrrev_i32_e32 v97, 31, v96
	v_lshlrev_b64 v[98:99], 11, v[96:97]
	v_lshl_add_u64 v[98:99], s[14:15], 0, v[98:99]
	v_lshl_add_u64 v[102:103], v[146:147], 1, v[98:99]
	s_mov_b64 s[100:101], 0x48000
	v_lshl_add_u64 v[230:231], v[232:233], 0, s[100:101]
	global_load_dwordx4 v[196:199], v[230:231], off
	global_load_dwordx4 v[200:203], v[230:231], off offset:256
	s_waitcnt vmcnt(11)
	v_lshlrev_b32_e32 v104, 16, v204
	v_and_b32_e32 v98, 0xffff0000, v204
	v_lshlrev_b32_e32 v105, 16, v205
	v_and_b32_e32 v99, 0xffff0000, v205
	v_lshlrev_b32_e32 v106, 16, v206
	v_and_b32_e32 v100, 0xffff0000, v206
	v_lshlrev_b32_e32 v107, 16, v207
	v_and_b32_e32 v101, 0xffff0000, v207
	v_add_f32_e32 v104, v92, v104
	v_add_f32_e32 v98, v93, v98
	v_add_f32_e32 v105, v94, v105
	v_add_f32_e32 v99, v95, v99
	v_add_f32_e32 v106, v88, v106
	v_add_f32_e32 v100, v89, v100
	v_add_f32_e32 v107, v90, v107
	v_add_f32_e32 v101, v91, v101
	v_cvt_pk_bf16_f32 v88, v104, v98
	v_cvt_pk_bf16_f32 v89, v105, v99
	v_cvt_pk_bf16_f32 v90, v106, v100
	v_cvt_pk_bf16_f32 v91, v107, v101
	v_mul_f32_e32 v98, v98, v98
	v_mul_f32_e32 v99, v99, v99
	v_mul_f32_e32 v100, v100, v100
	v_mul_f32_e32 v101, v101, v101
	v_fmac_f32_e32 v98, v104, v104
	v_fmac_f32_e32 v99, v105, v105
	v_fmac_f32_e32 v100, v106, v106
	v_fmac_f32_e32 v101, v107, v107
	v_add_f32_e32 v98, v98, v99
	v_add_f32_e32 v99, v100, v101
	v_add_f32_e32 v98, v98, v99
	global_store_dwordx4 v[102:103], v[88:91], off
	s_waitcnt vmcnt(11)
	v_lshlrev_b32_e32 v99, 16, v208
	v_and_b32_e32 v92, 0xffff0000, v208
	v_lshlrev_b32_e32 v100, 16, v209
	v_and_b32_e32 v93, 0xffff0000, v209
	v_lshlrev_b32_e32 v101, 16, v210
	v_and_b32_e32 v94, 0xffff0000, v210
	v_lshlrev_b32_e32 v104, 16, v211
	v_and_b32_e32 v95, 0xffff0000, v211
	v_add_f32_e32 v85, v85, v92
	v_add_f32_e32 v87, v87, v93
	v_add_f32_e32 v93, v81, v94
	v_add_f32_e32 v95, v83, v95
	v_add_f32_e32 v84, v84, v99
	v_add_f32_e32 v86, v86, v100
	v_add_f32_e32 v92, v80, v101
	v_add_f32_e32 v94, v82, v104
	v_mul_f32_e32 v80, v85, v85
	v_mul_f32_e32 v81, v87, v87
	v_mul_f32_e32 v82, v93, v93
	v_mul_f32_e32 v83, v95, v95
	v_fmac_f32_e32 v80, v84, v84
	v_fmac_f32_e32 v81, v86, v86
	v_fmac_f32_e32 v82, v92, v92
	v_fmac_f32_e32 v83, v94, v94
	v_add_f32_e32 v80, v80, v81
	v_add_f32_e32 v81, v82, v83
	v_add_f32_e32 v80, v80, v81
	v_add_f32_e32 v80, v98, v80
	ds_bpermute_b32 v81, v120, v80
	v_cvt_pk_bf16_f32 v82, v84, v85
	v_cvt_pk_bf16_f32 v83, v86, v87
	v_cvt_pk_bf16_f32 v84, v92, v93
	v_cvt_pk_bf16_f32 v85, v94, v95
	s_waitcnt lgkmcnt(0)
	v_add_f32_e32 v80, v80, v81
	ds_bpermute_b32 v81, v114, v80
	global_store_dwordx4 v[102:103], v[82:85], off offset:256
	s_and_saveexec_b64 s[36:37], s[4:5]
	s_cbranch_execz .LBB0_1742
	v_lshlrev_b64 v[82:83], 6, v[96:97]
	v_lshl_add_u64 v[82:83], s[18:19], 0, v[82:83]
	v_lshl_add_u64 v[82:83], s[30:31], 2, v[82:83]
	s_lshl_b32 s8, s46, 2
	v_lshl_add_u64 v[82:83], v[82:83], 0, s[8:9]
	s_waitcnt lgkmcnt(0)
	v_add_f32_e32 v80, v80, v81
	global_store_dword v[82:83], v80, off
.LBB0_1742:
	s_or_b64 exec, exec, s[36:37]
	v_or_b32_e32 v80, 48, v148
	s_waitcnt lgkmcnt(0)
	v_ashrrev_i32_e32 v81, 31, v80
	v_lshlrev_b64 v[82:83], 11, v[80:81]
	v_lshl_add_u64 v[82:83], s[14:15], 0, v[82:83]
	v_lshl_add_u64 v[86:87], v[146:147], 1, v[82:83]
	s_mov_b64 s[100:101], 0x50000
	v_lshl_add_u64 v[230:231], v[232:233], 0, s[100:101]
	global_load_dwordx4 v[204:207], v[230:231], off
	global_load_dwordx4 v[208:211], v[230:231], off offset:256
	s_waitcnt vmcnt(13)
	v_lshlrev_b32_e32 v88, 16, v212
	v_and_b32_e32 v82, 0xffff0000, v212
	v_lshlrev_b32_e32 v89, 16, v213
	v_and_b32_e32 v83, 0xffff0000, v213
	v_lshlrev_b32_e32 v90, 16, v214
	v_and_b32_e32 v84, 0xffff0000, v214
	v_lshlrev_b32_e32 v91, 16, v215
	v_and_b32_e32 v85, 0xffff0000, v215
	v_add_f32_e32 v88, v76, v88
	v_add_f32_e32 v82, v77, v82
	v_add_f32_e32 v89, v78, v89
	v_add_f32_e32 v83, v79, v83
	v_add_f32_e32 v90, v72, v90
	v_add_f32_e32 v84, v73, v84
	v_add_f32_e32 v91, v74, v91
	v_add_f32_e32 v85, v75, v85
	v_cvt_pk_bf16_f32 v72, v88, v82
	v_cvt_pk_bf16_f32 v73, v89, v83
	v_cvt_pk_bf16_f32 v74, v90, v84
	v_cvt_pk_bf16_f32 v75, v91, v85
	v_mul_f32_e32 v82, v82, v82
	v_mul_f32_e32 v83, v83, v83
	v_mul_f32_e32 v84, v84, v84
	v_mul_f32_e32 v85, v85, v85
	v_fmac_f32_e32 v82, v88, v88
	v_fmac_f32_e32 v83, v89, v89
	v_fmac_f32_e32 v84, v90, v90
	v_fmac_f32_e32 v85, v91, v91
	v_add_f32_e32 v82, v82, v83
	v_add_f32_e32 v83, v84, v85
	v_add_f32_e32 v82, v82, v83
	global_store_dwordx4 v[86:87], v[72:75], off
	s_waitcnt vmcnt(13)
	v_lshlrev_b32_e32 v83, 16, v216
	v_and_b32_e32 v76, 0xffff0000, v216
	v_lshlrev_b32_e32 v84, 16, v217
	v_and_b32_e32 v77, 0xffff0000, v217
	v_lshlrev_b32_e32 v85, 16, v218
	v_and_b32_e32 v78, 0xffff0000, v218
	v_lshlrev_b32_e32 v88, 16, v219
	v_and_b32_e32 v79, 0xffff0000, v219
	v_add_f32_e32 v69, v69, v76
	v_add_f32_e32 v71, v71, v77
	v_add_f32_e32 v77, v65, v78
	v_add_f32_e32 v79, v67, v79
	v_add_f32_e32 v68, v68, v83
	v_add_f32_e32 v70, v70, v84
	v_add_f32_e32 v76, v64, v85
	v_add_f32_e32 v78, v66, v88
	v_mul_f32_e32 v64, v69, v69
	v_mul_f32_e32 v65, v71, v71
	v_mul_f32_e32 v66, v77, v77
	v_mul_f32_e32 v67, v79, v79
	v_fmac_f32_e32 v64, v68, v68
	v_fmac_f32_e32 v65, v70, v70
	v_fmac_f32_e32 v66, v76, v76
	v_fmac_f32_e32 v67, v78, v78
	v_add_f32_e32 v64, v64, v65
	v_add_f32_e32 v65, v66, v67
	v_add_f32_e32 v64, v64, v65
	v_add_f32_e32 v64, v82, v64
	ds_bpermute_b32 v65, v120, v64
	v_cvt_pk_bf16_f32 v66, v68, v69
	v_cvt_pk_bf16_f32 v67, v70, v71
	v_cvt_pk_bf16_f32 v68, v76, v77
	v_cvt_pk_bf16_f32 v69, v78, v79
	s_waitcnt lgkmcnt(0)
	v_add_f32_e32 v64, v64, v65
	ds_bpermute_b32 v65, v114, v64
	global_store_dwordx4 v[86:87], v[66:69], off offset:256
	s_and_saveexec_b64 s[36:37], s[4:5]
	s_cbranch_execz .LBB0_1744
	v_lshlrev_b64 v[66:67], 6, v[80:81]
	v_lshl_add_u64 v[66:67], s[18:19], 0, v[66:67]
	v_lshl_add_u64 v[66:67], s[30:31], 2, v[66:67]
	s_lshl_b32 s8, s46, 2
	v_lshl_add_u64 v[66:67], v[66:67], 0, s[8:9]
	s_waitcnt lgkmcnt(0)
	v_add_f32_e32 v64, v64, v65
	global_store_dword v[66:67], v64, off
.LBB0_1744:
	s_or_b64 exec, exec, s[36:37]
	v_add_u32_e32 v64, 0x80, v148
	s_waitcnt lgkmcnt(0)
	v_ashrrev_i32_e32 v65, 31, v64
	v_lshlrev_b64 v[66:67], 11, v[64:65]
	v_lshl_add_u64 v[66:67], s[14:15], 0, v[66:67]
	v_lshl_add_u64 v[70:71], v[146:147], 1, v[66:67]
	s_mov_b64 s[100:101], 0x58000
	v_lshl_add_u64 v[230:231], v[232:233], 0, s[100:101]
	global_load_dwordx4 v[212:215], v[230:231], off
	global_load_dwordx4 v[216:219], v[230:231], off offset:256
	s_waitcnt vmcnt(13)
	v_lshlrev_b32_e32 v72, 16, v188
	v_and_b32_e32 v66, 0xffff0000, v188
	v_lshlrev_b32_e32 v73, 16, v189
	v_and_b32_e32 v67, 0xffff0000, v189
	v_lshlrev_b32_e32 v74, 16, v190
	v_and_b32_e32 v68, 0xffff0000, v190
	v_lshlrev_b32_e32 v75, 16, v191
	v_and_b32_e32 v69, 0xffff0000, v191
	v_add_f32_e32 v72, v60, v72
	v_add_f32_e32 v66, v61, v66
	v_add_f32_e32 v73, v62, v73
	v_add_f32_e32 v67, v63, v67
	v_add_f32_e32 v74, v56, v74
	v_add_f32_e32 v68, v57, v68
	v_add_f32_e32 v75, v58, v75
	v_add_f32_e32 v69, v59, v69
	v_cvt_pk_bf16_f32 v56, v72, v66
	v_cvt_pk_bf16_f32 v57, v73, v67
	v_cvt_pk_bf16_f32 v58, v74, v68
	v_cvt_pk_bf16_f32 v59, v75, v69
	v_mul_f32_e32 v66, v66, v66
	v_mul_f32_e32 v67, v67, v67
	v_mul_f32_e32 v68, v68, v68
	v_mul_f32_e32 v69, v69, v69
	v_fmac_f32_e32 v66, v72, v72
	v_fmac_f32_e32 v67, v73, v73
	v_fmac_f32_e32 v68, v74, v74
	v_fmac_f32_e32 v69, v75, v75
	v_add_f32_e32 v66, v66, v67
	v_add_f32_e32 v67, v68, v69
	v_add_f32_e32 v66, v66, v67
	global_store_dwordx4 v[70:71], v[56:59], off
	s_waitcnt vmcnt(13)
	v_lshlrev_b32_e32 v67, 16, v192
	v_and_b32_e32 v60, 0xffff0000, v192
	v_lshlrev_b32_e32 v68, 16, v193
	v_and_b32_e32 v61, 0xffff0000, v193
	v_lshlrev_b32_e32 v69, 16, v194
	v_and_b32_e32 v62, 0xffff0000, v194
	v_lshlrev_b32_e32 v72, 16, v195
	v_and_b32_e32 v63, 0xffff0000, v195
	v_add_f32_e32 v53, v53, v60
	v_add_f32_e32 v55, v55, v61
	v_add_f32_e32 v61, v49, v62
	v_add_f32_e32 v63, v51, v63
	v_add_f32_e32 v52, v52, v67
	v_add_f32_e32 v54, v54, v68
	v_add_f32_e32 v60, v48, v69
	v_add_f32_e32 v62, v50, v72
	v_mul_f32_e32 v48, v53, v53
	v_mul_f32_e32 v49, v55, v55
	v_mul_f32_e32 v50, v61, v61
	v_mul_f32_e32 v51, v63, v63
	v_fmac_f32_e32 v48, v52, v52
	v_fmac_f32_e32 v49, v54, v54
	v_fmac_f32_e32 v50, v60, v60
	v_fmac_f32_e32 v51, v62, v62
	v_add_f32_e32 v48, v48, v49
	v_add_f32_e32 v49, v50, v51
	v_add_f32_e32 v48, v48, v49
	v_add_f32_e32 v48, v66, v48
	ds_bpermute_b32 v49, v120, v48
	v_cvt_pk_bf16_f32 v50, v52, v53
	v_cvt_pk_bf16_f32 v51, v54, v55
	v_cvt_pk_bf16_f32 v52, v60, v61
	v_cvt_pk_bf16_f32 v53, v62, v63
	s_waitcnt lgkmcnt(0)
	v_add_f32_e32 v48, v48, v49
	ds_bpermute_b32 v49, v114, v48
	global_store_dwordx4 v[70:71], v[50:53], off offset:256
	s_and_saveexec_b64 s[36:37], s[4:5]
	s_cbranch_execz .LBB0_1746
	v_lshlrev_b64 v[50:51], 6, v[64:65]
	v_lshl_add_u64 v[50:51], s[18:19], 0, v[50:51]
	v_lshl_add_u64 v[50:51], s[30:31], 2, v[50:51]
	s_lshl_b32 s8, s46, 2
	v_lshl_add_u64 v[50:51], v[50:51], 0, s[8:9]
	s_waitcnt lgkmcnt(0)
	v_add_f32_e32 v48, v48, v49
	global_store_dword v[50:51], v48, off
.LBB0_1746:
	s_or_b64 exec, exec, s[36:37]
	v_add_u32_e32 v48, 0x90, v148
	s_waitcnt lgkmcnt(0)
	v_ashrrev_i32_e32 v49, 31, v48
	v_lshlrev_b64 v[50:51], 11, v[48:49]
	v_lshl_add_u64 v[50:51], s[14:15], 0, v[50:51]
	v_lshl_add_u64 v[54:55], v[146:147], 1, v[50:51]
	s_waitcnt vmcnt(11)
	v_lshlrev_b32_e32 v56, 16, v196
	v_and_b32_e32 v50, 0xffff0000, v196
	v_lshlrev_b32_e32 v57, 16, v197
	v_and_b32_e32 v51, 0xffff0000, v197
	v_lshlrev_b32_e32 v58, 16, v198
	v_and_b32_e32 v52, 0xffff0000, v198
	v_lshlrev_b32_e32 v59, 16, v199
	v_and_b32_e32 v53, 0xffff0000, v199
	v_add_f32_e32 v56, v44, v56
	v_add_f32_e32 v50, v45, v50
	v_add_f32_e32 v57, v46, v57
	v_add_f32_e32 v51, v47, v51
	v_add_f32_e32 v58, v40, v58
	v_add_f32_e32 v52, v41, v52
	v_add_f32_e32 v59, v42, v59
	v_add_f32_e32 v53, v43, v53
	v_cvt_pk_bf16_f32 v40, v56, v50
	v_cvt_pk_bf16_f32 v41, v57, v51
	v_cvt_pk_bf16_f32 v42, v58, v52
	v_cvt_pk_bf16_f32 v43, v59, v53
	v_mul_f32_e32 v50, v50, v50
	v_mul_f32_e32 v51, v51, v51
	v_mul_f32_e32 v52, v52, v52
	v_mul_f32_e32 v53, v53, v53
	v_fmac_f32_e32 v50, v56, v56
	v_fmac_f32_e32 v51, v57, v57
	v_fmac_f32_e32 v52, v58, v58
	v_fmac_f32_e32 v53, v59, v59
	v_add_f32_e32 v50, v50, v51
	v_add_f32_e32 v51, v52, v53
	v_add_f32_e32 v50, v50, v51
	global_store_dwordx4 v[54:55], v[40:43], off
	s_waitcnt vmcnt(11)
	v_lshlrev_b32_e32 v51, 16, v200
	v_and_b32_e32 v44, 0xffff0000, v200
	v_lshlrev_b32_e32 v52, 16, v201
	v_and_b32_e32 v45, 0xffff0000, v201
	v_lshlrev_b32_e32 v53, 16, v202
	v_and_b32_e32 v46, 0xffff0000, v202
	v_lshlrev_b32_e32 v56, 16, v203
	v_and_b32_e32 v47, 0xffff0000, v203
	v_add_f32_e32 v37, v37, v44
	v_add_f32_e32 v39, v39, v45
	v_add_f32_e32 v45, v33, v46
	v_add_f32_e32 v47, v35, v47
	v_add_f32_e32 v36, v36, v51
	v_add_f32_e32 v38, v38, v52
	v_add_f32_e32 v44, v32, v53
	v_add_f32_e32 v46, v34, v56
	v_mul_f32_e32 v32, v37, v37
	v_mul_f32_e32 v33, v39, v39
	v_mul_f32_e32 v34, v45, v45
	v_mul_f32_e32 v35, v47, v47
	v_fmac_f32_e32 v32, v36, v36
	v_fmac_f32_e32 v33, v38, v38
	v_fmac_f32_e32 v34, v44, v44
	v_fmac_f32_e32 v35, v46, v46
	v_add_f32_e32 v32, v32, v33
	v_add_f32_e32 v33, v34, v35
	v_add_f32_e32 v32, v32, v33
	v_add_f32_e32 v32, v50, v32
	ds_bpermute_b32 v33, v120, v32
	v_cvt_pk_bf16_f32 v34, v36, v37
	v_cvt_pk_bf16_f32 v35, v38, v39
	v_cvt_pk_bf16_f32 v36, v44, v45
	v_cvt_pk_bf16_f32 v37, v46, v47
	s_waitcnt lgkmcnt(0)
	v_add_f32_e32 v32, v32, v33
	ds_bpermute_b32 v33, v114, v32
	global_store_dwordx4 v[54:55], v[34:37], off offset:256
	s_and_saveexec_b64 s[36:37], s[4:5]
	s_cbranch_execz .LBB0_1748
	v_lshlrev_b64 v[34:35], 6, v[48:49]
	v_lshl_add_u64 v[34:35], s[18:19], 0, v[34:35]
	v_lshl_add_u64 v[34:35], s[30:31], 2, v[34:35]
	s_lshl_b32 s8, s46, 2
	v_lshl_add_u64 v[34:35], v[34:35], 0, s[8:9]
	s_waitcnt lgkmcnt(0)
	v_add_f32_e32 v32, v32, v33
	global_store_dword v[34:35], v32, off
.LBB0_1748:
	s_or_b64 exec, exec, s[36:37]
	v_add_u32_e32 v32, 0xa0, v148
	s_waitcnt lgkmcnt(0)
	v_ashrrev_i32_e32 v33, 31, v32
	v_lshlrev_b64 v[34:35], 11, v[32:33]
	v_lshl_add_u64 v[34:35], s[14:15], 0, v[34:35]
	v_lshl_add_u64 v[38:39], v[146:147], 1, v[34:35]
	s_waitcnt vmcnt(9)
	v_lshlrev_b32_e32 v40, 16, v204
	v_and_b32_e32 v34, 0xffff0000, v204
	v_lshlrev_b32_e32 v41, 16, v205
	v_and_b32_e32 v35, 0xffff0000, v205
	v_lshlrev_b32_e32 v42, 16, v206
	v_and_b32_e32 v36, 0xffff0000, v206
	v_lshlrev_b32_e32 v43, 16, v207
	v_and_b32_e32 v37, 0xffff0000, v207
	v_add_f32_e32 v40, v28, v40
	v_add_f32_e32 v34, v29, v34
	v_add_f32_e32 v41, v30, v41
	v_add_f32_e32 v35, v31, v35
	v_add_f32_e32 v42, v24, v42
	v_add_f32_e32 v36, v25, v36
	v_add_f32_e32 v43, v26, v43
	v_add_f32_e32 v37, v27, v37
	v_cvt_pk_bf16_f32 v24, v40, v34
	v_cvt_pk_bf16_f32 v25, v41, v35
	v_cvt_pk_bf16_f32 v26, v42, v36
	v_cvt_pk_bf16_f32 v27, v43, v37
	v_mul_f32_e32 v34, v34, v34
	v_mul_f32_e32 v35, v35, v35
	v_mul_f32_e32 v36, v36, v36
	v_mul_f32_e32 v37, v37, v37
	v_fmac_f32_e32 v34, v40, v40
	v_fmac_f32_e32 v35, v41, v41
	v_fmac_f32_e32 v36, v42, v42
	v_fmac_f32_e32 v37, v43, v43
	v_add_f32_e32 v34, v34, v35
	v_add_f32_e32 v35, v36, v37
	v_add_f32_e32 v34, v34, v35
	global_store_dwordx4 v[38:39], v[24:27], off
	s_waitcnt vmcnt(9)
	v_lshlrev_b32_e32 v35, 16, v208
	v_and_b32_e32 v28, 0xffff0000, v208
	v_lshlrev_b32_e32 v36, 16, v209
	v_and_b32_e32 v29, 0xffff0000, v209
	v_lshlrev_b32_e32 v37, 16, v210
	v_and_b32_e32 v30, 0xffff0000, v210
	v_lshlrev_b32_e32 v40, 16, v211
	v_and_b32_e32 v31, 0xffff0000, v211
	v_add_f32_e32 v21, v21, v28
	v_add_f32_e32 v23, v23, v29
	v_add_f32_e32 v29, v17, v30
	v_add_f32_e32 v31, v19, v31
	v_add_f32_e32 v20, v20, v35
	v_add_f32_e32 v22, v22, v36
	v_add_f32_e32 v28, v16, v37
	v_add_f32_e32 v30, v18, v40
	v_mul_f32_e32 v16, v21, v21
	v_mul_f32_e32 v17, v23, v23
	v_mul_f32_e32 v18, v29, v29
	v_mul_f32_e32 v19, v31, v31
	v_fmac_f32_e32 v16, v20, v20
	v_fmac_f32_e32 v17, v22, v22
	v_fmac_f32_e32 v18, v28, v28
	v_fmac_f32_e32 v19, v30, v30
	v_add_f32_e32 v16, v16, v17
	v_add_f32_e32 v17, v18, v19
	v_add_f32_e32 v16, v16, v17
	v_add_f32_e32 v16, v34, v16
	ds_bpermute_b32 v17, v120, v16
	v_cvt_pk_bf16_f32 v18, v20, v21
	v_cvt_pk_bf16_f32 v19, v22, v23
	v_cvt_pk_bf16_f32 v20, v28, v29
	v_cvt_pk_bf16_f32 v21, v30, v31
	s_waitcnt lgkmcnt(0)
	v_add_f32_e32 v16, v16, v17
	ds_bpermute_b32 v17, v114, v16
	global_store_dwordx4 v[38:39], v[18:21], off offset:256
	s_and_saveexec_b64 s[36:37], s[4:5]
	s_cbranch_execz .LBB0_1750
	v_lshlrev_b64 v[18:19], 6, v[32:33]
	v_lshl_add_u64 v[18:19], s[18:19], 0, v[18:19]
	v_lshl_add_u64 v[18:19], s[30:31], 2, v[18:19]
	s_lshl_b32 s8, s46, 2
	v_lshl_add_u64 v[18:19], v[18:19], 0, s[8:9]
	s_waitcnt lgkmcnt(0)
	v_add_f32_e32 v16, v16, v17
	global_store_dword v[18:19], v16, off
.LBB0_1750:
	s_or_b64 exec, exec, s[36:37]
	v_add_u32_e32 v16, 0xb0, v148
	s_waitcnt lgkmcnt(0)
	v_ashrrev_i32_e32 v17, 31, v16
	v_lshlrev_b64 v[18:19], 11, v[16:17]
	v_lshl_add_u64 v[18:19], s[14:15], 0, v[18:19]
	v_lshl_add_u64 v[22:23], v[146:147], 1, v[18:19]
	s_waitcnt vmcnt(7)
	v_lshlrev_b32_e32 v24, 16, v212
	v_and_b32_e32 v18, 0xffff0000, v212
	v_lshlrev_b32_e32 v25, 16, v213
	v_and_b32_e32 v19, 0xffff0000, v213
	v_lshlrev_b32_e32 v26, 16, v214
	v_and_b32_e32 v20, 0xffff0000, v214
	v_lshlrev_b32_e32 v27, 16, v215
	v_and_b32_e32 v21, 0xffff0000, v215
	v_add_f32_e32 v24, v12, v24
	v_add_f32_e32 v18, v13, v18
	v_add_f32_e32 v25, v14, v25
	v_add_f32_e32 v19, v15, v19
	v_add_f32_e32 v26, v8, v26
	v_add_f32_e32 v20, v9, v20
	v_add_f32_e32 v27, v10, v27
	v_add_f32_e32 v21, v11, v21
	v_cvt_pk_bf16_f32 v8, v24, v18
	v_cvt_pk_bf16_f32 v9, v25, v19
	v_cvt_pk_bf16_f32 v10, v26, v20
	v_cvt_pk_bf16_f32 v11, v27, v21
	v_mul_f32_e32 v18, v18, v18
	v_mul_f32_e32 v19, v19, v19
	v_mul_f32_e32 v20, v20, v20
	v_mul_f32_e32 v21, v21, v21
	v_fmac_f32_e32 v18, v24, v24
	v_fmac_f32_e32 v19, v25, v25
	v_fmac_f32_e32 v20, v26, v26
	v_fmac_f32_e32 v21, v27, v27
	v_add_f32_e32 v18, v18, v19
	v_add_f32_e32 v19, v20, v21
	v_add_f32_e32 v18, v18, v19
	global_store_dwordx4 v[22:23], v[8:11], off
	s_waitcnt vmcnt(7)
	v_lshlrev_b32_e32 v19, 16, v216
	v_and_b32_e32 v12, 0xffff0000, v216
	v_lshlrev_b32_e32 v20, 16, v217
	v_and_b32_e32 v13, 0xffff0000, v217
	v_lshlrev_b32_e32 v21, 16, v218
	v_and_b32_e32 v14, 0xffff0000, v218
	v_lshlrev_b32_e32 v24, 16, v219
	v_and_b32_e32 v15, 0xffff0000, v219
	v_add_f32_e32 v5, v5, v12
	v_add_f32_e32 v7, v7, v13
	v_add_f32_e32 v13, v1, v14
	v_add_f32_e32 v15, v3, v15
	v_add_f32_e32 v4, v4, v19
	v_add_f32_e32 v6, v6, v20
	v_add_f32_e32 v12, v0, v21
	v_add_f32_e32 v14, v2, v24
	v_mul_f32_e32 v0, v5, v5
	v_mul_f32_e32 v1, v7, v7
	v_mul_f32_e32 v2, v13, v13
	v_mul_f32_e32 v3, v15, v15
	v_fmac_f32_e32 v0, v4, v4
	v_fmac_f32_e32 v1, v6, v6
	v_fmac_f32_e32 v2, v12, v12
	v_fmac_f32_e32 v3, v14, v14
	v_add_f32_e32 v0, v0, v1
	v_add_f32_e32 v1, v2, v3
	v_add_f32_e32 v0, v0, v1
	v_add_f32_e32 v0, v18, v0
	ds_bpermute_b32 v1, v120, v0
	v_cvt_pk_bf16_f32 v2, v4, v5
	v_cvt_pk_bf16_f32 v3, v6, v7
	v_cvt_pk_bf16_f32 v4, v12, v13
	v_cvt_pk_bf16_f32 v5, v14, v15
	s_waitcnt lgkmcnt(0)
	v_add_f32_e32 v0, v0, v1
	ds_bpermute_b32 v1, v114, v0
	global_store_dwordx4 v[22:23], v[2:5], off offset:256
	s_and_saveexec_b64 s[36:37], s[4:5]
	s_cbranch_execz .LBB0_1752
	v_lshlrev_b64 v[2:3], 6, v[16:17]
	v_lshl_add_u64 v[2:3], s[18:19], 0, v[2:3]
	v_lshl_add_u64 v[2:3], s[30:31], 2, v[2:3]
	s_lshl_b32 s8, s46, 2
	v_lshl_add_u64 v[2:3], v[2:3], 0, s[8:9]
	s_waitcnt lgkmcnt(0)
	v_add_f32_e32 v0, v0, v1
	global_store_dword v[2:3], v0, off

.LBB0_2004:
	v_lshl_add_u32 v148, s36, 8, v150
	v_ashrrev_i32_e32 v149, 31, v148
	v_lshl_or_b32 v146, s0, 8, v152
	v_lshlrev_b64 v[158:159], 11, v[148:149]
	v_ashrrev_i32_e32 v147, 31, v146
	v_lshl_add_u64 v[158:159], s[14:15], 0, v[158:159]
	v_lshl_add_u64 v[162:163], v[146:147], 1, v[158:159]
	v_mov_b32_e32 v232, v162
	v_mov_b32_e32 v233, v163
	global_load_dwordx4 v[188:191], v[232:233], off
	global_load_dwordx4 v[192:195], v[232:233], off offset:256
	s_mov_b64 s[100:101], 0x8000
	v_lshl_add_u64 v[230:231], v[232:233], 0, s[100:101]
	global_load_dwordx4 v[196:199], v[230:231], off
	global_load_dwordx4 v[200:203], v[230:231], off offset:256
	s_mov_b64 s[100:101], 0x10000
	v_lshl_add_u64 v[230:231], v[232:233], 0, s[100:101]
	global_load_dwordx4 v[204:207], v[230:231], off
	global_load_dwordx4 v[208:211], v[230:231], off offset:256
	s_mov_b64 s[100:101], 0x18000
	v_lshl_add_u64 v[230:231], v[232:233], 0, s[100:101]
	global_load_dwordx4 v[212:215], v[230:231], off
	global_load_dwordx4 v[216:219], v[230:231], off offset:256
	v_and_b32_e32 v168, 64, v156
	v_add_u32_e32 v168, 64, v168
	v_xor_b32_e32 v169, 32, v156
	s_lshl_b32 s36, s0, 2
	s_ashr_i32 s37, s36, 31
	s_waitcnt vmcnt(7)
	v_lshlrev_b32_e32 v157, 16, v188
	v_and_b32_e32 v158, 0xffff0000, v188
	v_lshlrev_b32_e32 v164, 16, v189
	v_and_b32_e32 v159, 0xffff0000, v189
	v_lshlrev_b32_e32 v165, 16, v190
	v_and_b32_e32 v160, 0xffff0000, v190
	v_lshlrev_b32_e32 v166, 16, v191
	v_and_b32_e32 v161, 0xffff0000, v191
	v_add_f32_e32 v157, v124, v157
	v_add_f32_e32 v167, v125, v158
	v_add_f32_e32 v126, v126, v164
	v_add_f32_e32 v127, v127, v159
	v_add_f32_e32 v164, v120, v165
	v_add_f32_e32 v121, v121, v160
	v_add_f32_e32 v165, v122, v166
	v_add_f32_e32 v166, v123, v161
	v_cvt_pk_bf16_f32 v122, v157, v167
	v_cvt_pk_bf16_f32 v123, v126, v127
	v_cvt_pk_bf16_f32 v124, v164, v121
	v_cvt_pk_bf16_f32 v125, v165, v166
	v_mul_f32_e32 v167, v167, v167
	v_mul_f32_e32 v127, v127, v127
	v_mul_f32_e32 v121, v121, v121
	v_mul_f32_e32 v166, v166, v166
	v_fmac_f32_e32 v167, v157, v157
	v_fmac_f32_e32 v127, v126, v126
	v_fmac_f32_e32 v121, v164, v164
	v_fmac_f32_e32 v166, v165, v165
	v_add_f32_e32 v126, v167, v127
	v_add_f32_e32 v121, v121, v166
	v_add_f32_e32 v121, v126, v121
	v_xor_b32_e32 v120, 16, v156
	v_cmp_lt_i32_e32 vcc, v120, v168
	global_store_dwordx4 v[162:163], v[122:125], off
	s_waitcnt vmcnt(7)
	v_lshlrev_b32_e32 v126, 16, v192
	v_and_b32_e32 v127, 0xffff0000, v192
	v_lshlrev_b32_e32 v157, 16, v193
	v_and_b32_e32 v158, 0xffff0000, v193
	v_lshlrev_b32_e32 v159, 16, v194
	v_and_b32_e32 v160, 0xffff0000, v194
	v_lshlrev_b32_e32 v164, 16, v195
	v_and_b32_e32 v161, 0xffff0000, v195
	v_add_f32_e32 v117, v117, v127
	v_add_f32_e32 v119, v119, v158
	v_add_f32_e32 v127, v113, v160
	v_add_f32_e32 v115, v115, v161
	v_add_f32_e32 v116, v116, v126
	v_add_f32_e32 v118, v118, v157
	v_add_f32_e32 v126, v112, v159
	v_add_f32_e32 v157, v114, v164
	v_mul_f32_e32 v112, v117, v117
	v_mul_f32_e32 v113, v119, v119
	v_mul_f32_e32 v114, v127, v127
	v_mul_f32_e32 v158, v115, v115
	v_fmac_f32_e32 v112, v116, v116
	v_fmac_f32_e32 v113, v118, v118
	v_fmac_f32_e32 v114, v126, v126
	v_fmac_f32_e32 v158, v157, v157
	v_add_f32_e32 v112, v112, v113
	v_add_f32_e32 v113, v114, v158
	v_cndmask_b32_e32 v120, v156, v120, vcc
	v_add_f32_e32 v112, v112, v113
	v_lshlrev_b32_e32 v120, 2, v120
	v_add_f32_e32 v112, v121, v112
	ds_bpermute_b32 v113, v120, v112
	v_cmp_lt_i32_e32 vcc, v169, v168
	v_cvt_pk_bf16_f32 v116, v116, v117
	v_cvt_pk_bf16_f32 v117, v118, v119
	v_cvt_pk_bf16_f32 v118, v126, v127
	s_waitcnt lgkmcnt(0)
	v_add_f32_e32 v112, v112, v113
	v_cvt_pk_bf16_f32 v119, v157, v115
	v_cndmask_b32_e32 v114, v156, v169, vcc
	v_lshlrev_b32_e32 v114, 2, v114
	ds_bpermute_b32 v113, v114, v112
	global_store_dwordx4 v[162:163], v[116:119], off offset:256
	s_and_saveexec_b64 s[38:39], s[4:5]
	s_cbranch_execz .LBB0_2006
	v_lshlrev_b64 v[116:117], 6, v[148:149]
	v_lshl_add_u64 v[116:117], s[18:19], 0, v[116:117]
	v_lshl_add_u64 v[116:117], s[36:37], 2, v[116:117]
	s_lshl_b32 s0, s50, 2
	v_lshl_add_u64 v[116:117], v[116:117], 0, s[0:1]
	s_waitcnt lgkmcnt(0)
	v_add_f32_e32 v112, v112, v113
	global_store_dword v[116:117], v112, off
.LBB0_2006:
	s_or_b64 exec, exec, s[38:39]
	v_or_b32_e32 v112, 16, v148
	s_waitcnt lgkmcnt(0)
	v_ashrrev_i32_e32 v113, 31, v112
	v_lshlrev_b64 v[116:117], 11, v[112:113]
	v_lshl_add_u64 v[116:117], s[14:15], 0, v[116:117]
	v_lshl_add_u64 v[122:123], v[146:147], 1, v[116:117]
	s_mov_b64 s[100:101], 0x40000
	v_lshl_add_u64 v[230:231], v[232:233], 0, s[100:101]
	global_load_dwordx4 v[188:191], v[230:231], off
	global_load_dwordx4 v[192:195], v[230:231], off offset:256
	s_waitcnt vmcnt(9)
	v_lshlrev_b32_e32 v115, 16, v196
	v_and_b32_e32 v116, 0xffff0000, v196
	v_lshlrev_b32_e32 v121, 16, v197
	v_and_b32_e32 v117, 0xffff0000, v197
	v_lshlrev_b32_e32 v124, 16, v198
	v_and_b32_e32 v118, 0xffff0000, v198
	v_lshlrev_b32_e32 v125, 16, v199
	v_and_b32_e32 v119, 0xffff0000, v199
	v_add_f32_e32 v115, v108, v115
	v_add_f32_e32 v116, v109, v116
	v_add_f32_e32 v121, v110, v121
	v_add_f32_e32 v117, v111, v117
	v_add_f32_e32 v124, v104, v124
	v_add_f32_e32 v118, v105, v118
	v_add_f32_e32 v125, v106, v125
	v_add_f32_e32 v119, v107, v119
	v_cvt_pk_bf16_f32 v104, v115, v116
	v_cvt_pk_bf16_f32 v105, v121, v117
	v_cvt_pk_bf16_f32 v106, v124, v118
	v_cvt_pk_bf16_f32 v107, v125, v119
	v_mul_f32_e32 v116, v116, v116
	v_mul_f32_e32 v117, v117, v117
	v_mul_f32_e32 v118, v118, v118
	v_mul_f32_e32 v119, v119, v119
	v_fmac_f32_e32 v116, v115, v115
	v_fmac_f32_e32 v117, v121, v121
	v_fmac_f32_e32 v118, v124, v124
	v_fmac_f32_e32 v119, v125, v125
	v_add_f32_e32 v115, v116, v117
	v_add_f32_e32 v116, v118, v119
	v_add_f32_e32 v115, v115, v116
	global_store_dwordx4 v[122:123], v[104:107], off
	s_waitcnt vmcnt(9)
	v_lshlrev_b32_e32 v116, 16, v200
	v_and_b32_e32 v108, 0xffff0000, v200
	v_lshlrev_b32_e32 v117, 16, v201
	v_and_b32_e32 v109, 0xffff0000, v201
	v_lshlrev_b32_e32 v118, 16, v202
	v_and_b32_e32 v110, 0xffff0000, v202
	v_lshlrev_b32_e32 v119, 16, v203
	v_and_b32_e32 v111, 0xffff0000, v203
	v_add_f32_e32 v101, v101, v108
	v_add_f32_e32 v103, v103, v109
	v_add_f32_e32 v109, v97, v110
	v_add_f32_e32 v111, v99, v111
	v_add_f32_e32 v100, v100, v116
	v_add_f32_e32 v102, v102, v117
	v_add_f32_e32 v108, v96, v118
	v_add_f32_e32 v110, v98, v119
	v_mul_f32_e32 v96, v101, v101
	v_mul_f32_e32 v97, v103, v103
	v_mul_f32_e32 v98, v109, v109
	v_mul_f32_e32 v99, v111, v111
	v_fmac_f32_e32 v96, v100, v100
	v_fmac_f32_e32 v97, v102, v102
	v_fmac_f32_e32 v98, v108, v108
	v_fmac_f32_e32 v99, v110, v110
	v_add_f32_e32 v96, v96, v97
	v_add_f32_e32 v97, v98, v99
	v_add_f32_e32 v96, v96, v97
	v_add_f32_e32 v96, v115, v96
	ds_bpermute_b32 v97, v120, v96
	v_cvt_pk_bf16_f32 v98, v100, v101
	v_cvt_pk_bf16_f32 v99, v102, v103
	v_cvt_pk_bf16_f32 v100, v108, v109
	v_cvt_pk_bf16_f32 v101, v110, v111
	s_waitcnt lgkmcnt(0)
	v_add_f32_e32 v96, v96, v97
	ds_bpermute_b32 v97, v114, v96
	global_store_dwordx4 v[122:123], v[98:101], off offset:256
	s_and_saveexec_b64 s[38:39], s[4:5]
	s_cbranch_execz .LBB0_2008
	v_lshlrev_b64 v[98:99], 6, v[112:113]
	v_lshl_add_u64 v[98:99], s[18:19], 0, v[98:99]
	v_lshl_add_u64 v[98:99], s[36:37], 2, v[98:99]
	s_lshl_b32 s0, s50, 2
	v_lshl_add_u64 v[98:99], v[98:99], 0, s[0:1]
	s_waitcnt lgkmcnt(0)
	v_add_f32_e32 v96, v96, v97
	global_store_dword v[98:99], v96, off
.LBB0_2008:
	s_or_b64 exec, exec, s[38:39]
	v_or_b32_e32 v96, 32, v148
	s_waitcnt lgkmcnt(0)
	v_ashrrev_i32_e32 v97, 31, v96
	v_lshlrev_b64 v[98:99], 11, v[96:97]
	v_lshl_add_u64 v[98:99], s[14:15], 0, v[98:99]
	v_lshl_add_u64 v[102:103], v[146:147], 1, v[98:99]
	s_mov_b64 s[100:101], 0x48000
	v_lshl_add_u64 v[230:231], v[232:233], 0, s[100:101]
	global_load_dwordx4 v[196:199], v[230:231], off
	global_load_dwordx4 v[200:203], v[230:231], off offset:256
	s_waitcnt vmcnt(11)
	v_lshlrev_b32_e32 v104, 16, v204
	v_and_b32_e32 v98, 0xffff0000, v204
	v_lshlrev_b32_e32 v105, 16, v205
	v_and_b32_e32 v99, 0xffff0000, v205
	v_lshlrev_b32_e32 v106, 16, v206
	v_and_b32_e32 v100, 0xffff0000, v206
	v_lshlrev_b32_e32 v107, 16, v207
	v_and_b32_e32 v101, 0xffff0000, v207
	v_add_f32_e32 v104, v92, v104
	v_add_f32_e32 v98, v93, v98
	v_add_f32_e32 v105, v94, v105
	v_add_f32_e32 v99, v95, v99
	v_add_f32_e32 v106, v88, v106
	v_add_f32_e32 v100, v89, v100
	v_add_f32_e32 v107, v90, v107
	v_add_f32_e32 v101, v91, v101
	v_cvt_pk_bf16_f32 v88, v104, v98
	v_cvt_pk_bf16_f32 v89, v105, v99
	v_cvt_pk_bf16_f32 v90, v106, v100
	v_cvt_pk_bf16_f32 v91, v107, v101
	v_mul_f32_e32 v98, v98, v98
	v_mul_f32_e32 v99, v99, v99
	v_mul_f32_e32 v100, v100, v100
	v_mul_f32_e32 v101, v101, v101
	v_fmac_f32_e32 v98, v104, v104
	v_fmac_f32_e32 v99, v105, v105
	v_fmac_f32_e32 v100, v106, v106
	v_fmac_f32_e32 v101, v107, v107
	v_add_f32_e32 v98, v98, v99
	v_add_f32_e32 v99, v100, v101
	v_add_f32_e32 v98, v98, v99
	global_store_dwordx4 v[102:103], v[88:91], off
	s_waitcnt vmcnt(11)
	v_lshlrev_b32_e32 v99, 16, v208
	v_and_b32_e32 v92, 0xffff0000, v208
	v_lshlrev_b32_e32 v100, 16, v209
	v_and_b32_e32 v93, 0xffff0000, v209
	v_lshlrev_b32_e32 v101, 16, v210
	v_and_b32_e32 v94, 0xffff0000, v210
	v_lshlrev_b32_e32 v104, 16, v211
	v_and_b32_e32 v95, 0xffff0000, v211
	v_add_f32_e32 v85, v85, v92
	v_add_f32_e32 v87, v87, v93
	v_add_f32_e32 v93, v81, v94
	v_add_f32_e32 v95, v83, v95
	v_add_f32_e32 v84, v84, v99
	v_add_f32_e32 v86, v86, v100
	v_add_f32_e32 v92, v80, v101
	v_add_f32_e32 v94, v82, v104
	v_mul_f32_e32 v80, v85, v85
	v_mul_f32_e32 v81, v87, v87
	v_mul_f32_e32 v82, v93, v93
	v_mul_f32_e32 v83, v95, v95
	v_fmac_f32_e32 v80, v84, v84
	v_fmac_f32_e32 v81, v86, v86
	v_fmac_f32_e32 v82, v92, v92
	v_fmac_f32_e32 v83, v94, v94
	v_add_f32_e32 v80, v80, v81
	v_add_f32_e32 v81, v82, v83
	v_add_f32_e32 v80, v80, v81
	v_add_f32_e32 v80, v98, v80
	ds_bpermute_b32 v81, v120, v80
	v_cvt_pk_bf16_f32 v82, v84, v85
	v_cvt_pk_bf16_f32 v83, v86, v87
	v_cvt_pk_bf16_f32 v84, v92, v93
	v_cvt_pk_bf16_f32 v85, v94, v95
	s_waitcnt lgkmcnt(0)
	v_add_f32_e32 v80, v80, v81
	ds_bpermute_b32 v81, v114, v80
	global_store_dwordx4 v[102:103], v[82:85], off offset:256
	s_and_saveexec_b64 s[38:39], s[4:5]
	s_cbranch_execz .LBB0_2010
	v_lshlrev_b64 v[82:83], 6, v[96:97]
	v_lshl_add_u64 v[82:83], s[18:19], 0, v[82:83]
	v_lshl_add_u64 v[82:83], s[36:37], 2, v[82:83]
	s_lshl_b32 s0, s50, 2
	v_lshl_add_u64 v[82:83], v[82:83], 0, s[0:1]
	s_waitcnt lgkmcnt(0)
	v_add_f32_e32 v80, v80, v81
	global_store_dword v[82:83], v80, off
.LBB0_2010:
	s_or_b64 exec, exec, s[38:39]
	v_or_b32_e32 v80, 48, v148
	s_waitcnt lgkmcnt(0)
	v_ashrrev_i32_e32 v81, 31, v80
	v_lshlrev_b64 v[82:83], 11, v[80:81]
	v_lshl_add_u64 v[82:83], s[14:15], 0, v[82:83]
	v_lshl_add_u64 v[86:87], v[146:147], 1, v[82:83]
	s_mov_b64 s[100:101], 0x50000
	v_lshl_add_u64 v[230:231], v[232:233], 0, s[100:101]
	global_load_dwordx4 v[204:207], v[230:231], off
	global_load_dwordx4 v[208:211], v[230:231], off offset:256
	s_waitcnt vmcnt(13)
	v_lshlrev_b32_e32 v88, 16, v212
	v_and_b32_e32 v82, 0xffff0000, v212
	v_lshlrev_b32_e32 v89, 16, v213
	v_and_b32_e32 v83, 0xffff0000, v213
	v_lshlrev_b32_e32 v90, 16, v214
	v_and_b32_e32 v84, 0xffff0000, v214
	v_lshlrev_b32_e32 v91, 16, v215
	v_and_b32_e32 v85, 0xffff0000, v215
	v_add_f32_e32 v88, v76, v88
	v_add_f32_e32 v82, v77, v82
	v_add_f32_e32 v89, v78, v89
	v_add_f32_e32 v83, v79, v83
	v_add_f32_e32 v90, v72, v90
	v_add_f32_e32 v84, v73, v84
	v_add_f32_e32 v91, v74, v91
	v_add_f32_e32 v85, v75, v85
	v_cvt_pk_bf16_f32 v72, v88, v82
	v_cvt_pk_bf16_f32 v73, v89, v83
	v_cvt_pk_bf16_f32 v74, v90, v84
	v_cvt_pk_bf16_f32 v75, v91, v85
	v_mul_f32_e32 v82, v82, v82
	v_mul_f32_e32 v83, v83, v83
	v_mul_f32_e32 v84, v84, v84
	v_mul_f32_e32 v85, v85, v85
	v_fmac_f32_e32 v82, v88, v88
	v_fmac_f32_e32 v83, v89, v89
	v_fmac_f32_e32 v84, v90, v90
	v_fmac_f32_e32 v85, v91, v91
	v_add_f32_e32 v82, v82, v83
	v_add_f32_e32 v83, v84, v85
	v_add_f32_e32 v82, v82, v83
	global_store_dwordx4 v[86:87], v[72:75], off
	s_waitcnt vmcnt(13)
	v_lshlrev_b32_e32 v83, 16, v216
	v_and_b32_e32 v76, 0xffff0000, v216
	v_lshlrev_b32_e32 v84, 16, v217
	v_and_b32_e32 v77, 0xffff0000, v217
	v_lshlrev_b32_e32 v85, 16, v218
	v_and_b32_e32 v78, 0xffff0000, v218
	v_lshlrev_b32_e32 v88, 16, v219
	v_and_b32_e32 v79, 0xffff0000, v219
	v_add_f32_e32 v69, v69, v76
	v_add_f32_e32 v71, v71, v77
	v_add_f32_e32 v77, v65, v78
	v_add_f32_e32 v79, v67, v79
	v_add_f32_e32 v68, v68, v83
	v_add_f32_e32 v70, v70, v84
	v_add_f32_e32 v76, v64, v85
	v_add_f32_e32 v78, v66, v88
	v_mul_f32_e32 v64, v69, v69
	v_mul_f32_e32 v65, v71, v71
	v_mul_f32_e32 v66, v77, v77
	v_mul_f32_e32 v67, v79, v79
	v_fmac_f32_e32 v64, v68, v68
	v_fmac_f32_e32 v65, v70, v70
	v_fmac_f32_e32 v66, v76, v76
	v_fmac_f32_e32 v67, v78, v78
	v_add_f32_e32 v64, v64, v65
	v_add_f32_e32 v65, v66, v67
	v_add_f32_e32 v64, v64, v65
	v_add_f32_e32 v64, v82, v64
	ds_bpermute_b32 v65, v120, v64
	v_cvt_pk_bf16_f32 v66, v68, v69
	v_cvt_pk_bf16_f32 v67, v70, v71
	v_cvt_pk_bf16_f32 v68, v76, v77
	v_cvt_pk_bf16_f32 v69, v78, v79
	s_waitcnt lgkmcnt(0)
	v_add_f32_e32 v64, v64, v65
	ds_bpermute_b32 v65, v114, v64
	global_store_dwordx4 v[86:87], v[66:69], off offset:256
	s_and_saveexec_b64 s[38:39], s[4:5]
	s_cbranch_execz .LBB0_2012
	v_lshlrev_b64 v[66:67], 6, v[80:81]
	v_lshl_add_u64 v[66:67], s[18:19], 0, v[66:67]
	v_lshl_add_u64 v[66:67], s[36:37], 2, v[66:67]
	s_lshl_b32 s0, s50, 2
	v_lshl_add_u64 v[66:67], v[66:67], 0, s[0:1]
	s_waitcnt lgkmcnt(0)
	v_add_f32_e32 v64, v64, v65
	global_store_dword v[66:67], v64, off
.LBB0_2012:
	s_or_b64 exec, exec, s[38:39]
	v_add_u32_e32 v64, 0x80, v148
	s_waitcnt lgkmcnt(0)
	v_ashrrev_i32_e32 v65, 31, v64
	v_lshlrev_b64 v[66:67], 11, v[64:65]
	v_lshl_add_u64 v[66:67], s[14:15], 0, v[66:67]
	v_lshl_add_u64 v[70:71], v[146:147], 1, v[66:67]
	s_mov_b64 s[100:101], 0x58000
	v_lshl_add_u64 v[230:231], v[232:233], 0, s[100:101]
	global_load_dwordx4 v[212:215], v[230:231], off
	global_load_dwordx4 v[216:219], v[230:231], off offset:256
	s_waitcnt vmcnt(13)
	v_lshlrev_b32_e32 v72, 16, v188
	v_and_b32_e32 v66, 0xffff0000, v188
	v_lshlrev_b32_e32 v73, 16, v189
	v_and_b32_e32 v67, 0xffff0000, v189
	v_lshlrev_b32_e32 v74, 16, v190
	v_and_b32_e32 v68, 0xffff0000, v190
	v_lshlrev_b32_e32 v75, 16, v191
	v_and_b32_e32 v69, 0xffff0000, v191
	v_add_f32_e32 v72, v60, v72
	v_add_f32_e32 v66, v61, v66
	v_add_f32_e32 v73, v62, v73
	v_add_f32_e32 v67, v63, v67
	v_add_f32_e32 v74, v56, v74
	v_add_f32_e32 v68, v57, v68
	v_add_f32_e32 v75, v58, v75
	v_add_f32_e32 v69, v59, v69
	v_cvt_pk_bf16_f32 v56, v72, v66
	v_cvt_pk_bf16_f32 v57, v73, v67
	v_cvt_pk_bf16_f32 v58, v74, v68
	v_cvt_pk_bf16_f32 v59, v75, v69
	v_mul_f32_e32 v66, v66, v66
	v_mul_f32_e32 v67, v67, v67
	v_mul_f32_e32 v68, v68, v68
	v_mul_f32_e32 v69, v69, v69
	v_fmac_f32_e32 v66, v72, v72
	v_fmac_f32_e32 v67, v73, v73
	v_fmac_f32_e32 v68, v74, v74
	v_fmac_f32_e32 v69, v75, v75
	v_add_f32_e32 v66, v66, v67
	v_add_f32_e32 v67, v68, v69
	v_add_f32_e32 v66, v66, v67
	global_store_dwordx4 v[70:71], v[56:59], off
	s_waitcnt vmcnt(13)
	v_lshlrev_b32_e32 v67, 16, v192
	v_and_b32_e32 v60, 0xffff0000, v192
	v_lshlrev_b32_e32 v68, 16, v193
	v_and_b32_e32 v61, 0xffff0000, v193
	v_lshlrev_b32_e32 v69, 16, v194
	v_and_b32_e32 v62, 0xffff0000, v194
	v_lshlrev_b32_e32 v72, 16, v195
	v_and_b32_e32 v63, 0xffff0000, v195
	v_add_f32_e32 v53, v53, v60
	v_add_f32_e32 v55, v55, v61
	v_add_f32_e32 v61, v49, v62
	v_add_f32_e32 v63, v51, v63
	v_add_f32_e32 v52, v52, v67
	v_add_f32_e32 v54, v54, v68
	v_add_f32_e32 v60, v48, v69
	v_add_f32_e32 v62, v50, v72
	v_mul_f32_e32 v48, v53, v53
	v_mul_f32_e32 v49, v55, v55
	v_mul_f32_e32 v50, v61, v61
	v_mul_f32_e32 v51, v63, v63
	v_fmac_f32_e32 v48, v52, v52
	v_fmac_f32_e32 v49, v54, v54
	v_fmac_f32_e32 v50, v60, v60
	v_fmac_f32_e32 v51, v62, v62
	v_add_f32_e32 v48, v48, v49
	v_add_f32_e32 v49, v50, v51
	v_add_f32_e32 v48, v48, v49
	v_add_f32_e32 v48, v66, v48
	ds_bpermute_b32 v49, v120, v48
	v_cvt_pk_bf16_f32 v50, v52, v53
	v_cvt_pk_bf16_f32 v51, v54, v55
	v_cvt_pk_bf16_f32 v52, v60, v61
	v_cvt_pk_bf16_f32 v53, v62, v63
	s_waitcnt lgkmcnt(0)
	v_add_f32_e32 v48, v48, v49
	ds_bpermute_b32 v49, v114, v48
	global_store_dwordx4 v[70:71], v[50:53], off offset:256
	s_and_saveexec_b64 s[38:39], s[4:5]
	s_cbranch_execz .LBB0_2014
	v_lshlrev_b64 v[50:51], 6, v[64:65]
	v_lshl_add_u64 v[50:51], s[18:19], 0, v[50:51]
	v_lshl_add_u64 v[50:51], s[36:37], 2, v[50:51]
	s_lshl_b32 s0, s50, 2
	v_lshl_add_u64 v[50:51], v[50:51], 0, s[0:1]
	s_waitcnt lgkmcnt(0)
	v_add_f32_e32 v48, v48, v49
	global_store_dword v[50:51], v48, off
.LBB0_2014:
	s_or_b64 exec, exec, s[38:39]
	v_add_u32_e32 v48, 0x90, v148
	s_waitcnt lgkmcnt(0)
	v_ashrrev_i32_e32 v49, 31, v48
	v_lshlrev_b64 v[50:51], 11, v[48:49]
	v_lshl_add_u64 v[50:51], s[14:15], 0, v[50:51]
	v_lshl_add_u64 v[54:55], v[146:147], 1, v[50:51]
	s_waitcnt vmcnt(11)
	v_lshlrev_b32_e32 v56, 16, v196
	v_and_b32_e32 v50, 0xffff0000, v196
	v_lshlrev_b32_e32 v57, 16, v197
	v_and_b32_e32 v51, 0xffff0000, v197
	v_lshlrev_b32_e32 v58, 16, v198
	v_and_b32_e32 v52, 0xffff0000, v198
	v_lshlrev_b32_e32 v59, 16, v199
	v_and_b32_e32 v53, 0xffff0000, v199
	v_add_f32_e32 v56, v44, v56
	v_add_f32_e32 v50, v45, v50
	v_add_f32_e32 v57, v46, v57
	v_add_f32_e32 v51, v47, v51
	v_add_f32_e32 v58, v40, v58
	v_add_f32_e32 v52, v41, v52
	v_add_f32_e32 v59, v42, v59
	v_add_f32_e32 v53, v43, v53
	v_cvt_pk_bf16_f32 v40, v56, v50
	v_cvt_pk_bf16_f32 v41, v57, v51
	v_cvt_pk_bf16_f32 v42, v58, v52
	v_cvt_pk_bf16_f32 v43, v59, v53
	v_mul_f32_e32 v50, v50, v50
	v_mul_f32_e32 v51, v51, v51
	v_mul_f32_e32 v52, v52, v52
	v_mul_f32_e32 v53, v53, v53
	v_fmac_f32_e32 v50, v56, v56
	v_fmac_f32_e32 v51, v57, v57
	v_fmac_f32_e32 v52, v58, v58
	v_fmac_f32_e32 v53, v59, v59
	v_add_f32_e32 v50, v50, v51
	v_add_f32_e32 v51, v52, v53
	v_add_f32_e32 v50, v50, v51
	global_store_dwordx4 v[54:55], v[40:43], off
	s_waitcnt vmcnt(11)
	v_lshlrev_b32_e32 v51, 16, v200
	v_and_b32_e32 v44, 0xffff0000, v200
	v_lshlrev_b32_e32 v52, 16, v201
	v_and_b32_e32 v45, 0xffff0000, v201
	v_lshlrev_b32_e32 v53, 16, v202
	v_and_b32_e32 v46, 0xffff0000, v202
	v_lshlrev_b32_e32 v56, 16, v203
	v_and_b32_e32 v47, 0xffff0000, v203
	v_add_f32_e32 v37, v37, v44
	v_add_f32_e32 v39, v39, v45
	v_add_f32_e32 v45, v33, v46
	v_add_f32_e32 v47, v35, v47
	v_add_f32_e32 v36, v36, v51
	v_add_f32_e32 v38, v38, v52
	v_add_f32_e32 v44, v32, v53
	v_add_f32_e32 v46, v34, v56
	v_mul_f32_e32 v32, v37, v37
	v_mul_f32_e32 v33, v39, v39
	v_mul_f32_e32 v34, v45, v45
	v_mul_f32_e32 v35, v47, v47
	v_fmac_f32_e32 v32, v36, v36
	v_fmac_f32_e32 v33, v38, v38
	v_fmac_f32_e32 v34, v44, v44
	v_fmac_f32_e32 v35, v46, v46
	v_add_f32_e32 v32, v32, v33
	v_add_f32_e32 v33, v34, v35
	v_add_f32_e32 v32, v32, v33
	v_add_f32_e32 v32, v50, v32
	ds_bpermute_b32 v33, v120, v32
	v_cvt_pk_bf16_f32 v34, v36, v37
	v_cvt_pk_bf16_f32 v35, v38, v39
	v_cvt_pk_bf16_f32 v36, v44, v45
	v_cvt_pk_bf16_f32 v37, v46, v47
	s_waitcnt lgkmcnt(0)
	v_add_f32_e32 v32, v32, v33
	ds_bpermute_b32 v33, v114, v32
	global_store_dwordx4 v[54:55], v[34:37], off offset:256
	s_and_saveexec_b64 s[38:39], s[4:5]
	s_cbranch_execz .LBB0_2016
	v_lshlrev_b64 v[34:35], 6, v[48:49]
	v_lshl_add_u64 v[34:35], s[18:19], 0, v[34:35]
	v_lshl_add_u64 v[34:35], s[36:37], 2, v[34:35]
	s_lshl_b32 s0, s50, 2
	v_lshl_add_u64 v[34:35], v[34:35], 0, s[0:1]
	s_waitcnt lgkmcnt(0)
	v_add_f32_e32 v32, v32, v33
	global_store_dword v[34:35], v32, off
.LBB0_2016:
	s_or_b64 exec, exec, s[38:39]
	v_add_u32_e32 v32, 0xa0, v148
	s_waitcnt lgkmcnt(0)
	v_ashrrev_i32_e32 v33, 31, v32
	v_lshlrev_b64 v[34:35], 11, v[32:33]
	v_lshl_add_u64 v[34:35], s[14:15], 0, v[34:35]
	v_lshl_add_u64 v[38:39], v[146:147], 1, v[34:35]
	s_waitcnt vmcnt(9)
	v_lshlrev_b32_e32 v40, 16, v204
	v_and_b32_e32 v34, 0xffff0000, v204
	v_lshlrev_b32_e32 v41, 16, v205
	v_and_b32_e32 v35, 0xffff0000, v205
	v_lshlrev_b32_e32 v42, 16, v206
	v_and_b32_e32 v36, 0xffff0000, v206
	v_lshlrev_b32_e32 v43, 16, v207
	v_and_b32_e32 v37, 0xffff0000, v207
	v_add_f32_e32 v40, v28, v40
	v_add_f32_e32 v34, v29, v34
	v_add_f32_e32 v41, v30, v41
	v_add_f32_e32 v35, v31, v35
	v_add_f32_e32 v42, v24, v42
	v_add_f32_e32 v36, v25, v36
	v_add_f32_e32 v43, v26, v43
	v_add_f32_e32 v37, v27, v37
	v_cvt_pk_bf16_f32 v24, v40, v34
	v_cvt_pk_bf16_f32 v25, v41, v35
	v_cvt_pk_bf16_f32 v26, v42, v36
	v_cvt_pk_bf16_f32 v27, v43, v37
	v_mul_f32_e32 v34, v34, v34
	v_mul_f32_e32 v35, v35, v35
	v_mul_f32_e32 v36, v36, v36
	v_mul_f32_e32 v37, v37, v37
	v_fmac_f32_e32 v34, v40, v40
	v_fmac_f32_e32 v35, v41, v41
	v_fmac_f32_e32 v36, v42, v42
	v_fmac_f32_e32 v37, v43, v43
	v_add_f32_e32 v34, v34, v35
	v_add_f32_e32 v35, v36, v37
	v_add_f32_e32 v34, v34, v35
	global_store_dwordx4 v[38:39], v[24:27], off
	s_waitcnt vmcnt(9)
	v_lshlrev_b32_e32 v35, 16, v208
	v_and_b32_e32 v28, 0xffff0000, v208
	v_lshlrev_b32_e32 v36, 16, v209
	v_and_b32_e32 v29, 0xffff0000, v209
	v_lshlrev_b32_e32 v37, 16, v210
	v_and_b32_e32 v30, 0xffff0000, v210
	v_lshlrev_b32_e32 v40, 16, v211
	v_and_b32_e32 v31, 0xffff0000, v211
	v_add_f32_e32 v21, v21, v28
	v_add_f32_e32 v23, v23, v29
	v_add_f32_e32 v29, v17, v30
	v_add_f32_e32 v31, v19, v31
	v_add_f32_e32 v20, v20, v35
	v_add_f32_e32 v22, v22, v36
	v_add_f32_e32 v28, v16, v37
	v_add_f32_e32 v30, v18, v40
	v_mul_f32_e32 v16, v21, v21
	v_mul_f32_e32 v17, v23, v23
	v_mul_f32_e32 v18, v29, v29
	v_mul_f32_e32 v19, v31, v31
	v_fmac_f32_e32 v16, v20, v20
	v_fmac_f32_e32 v17, v22, v22
	v_fmac_f32_e32 v18, v28, v28
	v_fmac_f32_e32 v19, v30, v30
	v_add_f32_e32 v16, v16, v17
	v_add_f32_e32 v17, v18, v19
	v_add_f32_e32 v16, v16, v17
	v_add_f32_e32 v16, v34, v16
	ds_bpermute_b32 v17, v120, v16
	v_cvt_pk_bf16_f32 v18, v20, v21
	v_cvt_pk_bf16_f32 v19, v22, v23
	v_cvt_pk_bf16_f32 v20, v28, v29
	v_cvt_pk_bf16_f32 v21, v30, v31
	s_waitcnt lgkmcnt(0)
	v_add_f32_e32 v16, v16, v17
	ds_bpermute_b32 v17, v114, v16
	global_store_dwordx4 v[38:39], v[18:21], off offset:256
	s_and_saveexec_b64 s[38:39], s[4:5]
	s_cbranch_execz .LBB0_2018
	v_lshlrev_b64 v[18:19], 6, v[32:33]
	v_lshl_add_u64 v[18:19], s[18:19], 0, v[18:19]
	v_lshl_add_u64 v[18:19], s[36:37], 2, v[18:19]
	s_lshl_b32 s0, s50, 2
	v_lshl_add_u64 v[18:19], v[18:19], 0, s[0:1]
	s_waitcnt lgkmcnt(0)
	v_add_f32_e32 v16, v16, v17
	global_store_dword v[18:19], v16, off
.LBB0_2018:
	s_or_b64 exec, exec, s[38:39]
	v_add_u32_e32 v16, 0xb0, v148
	s_waitcnt lgkmcnt(0)
	v_ashrrev_i32_e32 v17, 31, v16
	v_lshlrev_b64 v[18:19], 11, v[16:17]
	v_lshl_add_u64 v[18:19], s[14:15], 0, v[18:19]
	v_lshl_add_u64 v[22:23], v[146:147], 1, v[18:19]
	s_waitcnt vmcnt(7)
	v_lshlrev_b32_e32 v24, 16, v212
	v_and_b32_e32 v18, 0xffff0000, v212
	v_lshlrev_b32_e32 v25, 16, v213
	v_and_b32_e32 v19, 0xffff0000, v213
	v_lshlrev_b32_e32 v26, 16, v214
	v_and_b32_e32 v20, 0xffff0000, v214
	v_lshlrev_b32_e32 v27, 16, v215
	v_and_b32_e32 v21, 0xffff0000, v215
	v_add_f32_e32 v24, v12, v24
	v_add_f32_e32 v18, v13, v18
	v_add_f32_e32 v25, v14, v25
	v_add_f32_e32 v19, v15, v19
	v_add_f32_e32 v26, v8, v26
	v_add_f32_e32 v20, v9, v20
	v_add_f32_e32 v27, v10, v27
	v_add_f32_e32 v21, v11, v21
	v_cvt_pk_bf16_f32 v8, v24, v18
	v_cvt_pk_bf16_f32 v9, v25, v19
	v_cvt_pk_bf16_f32 v10, v26, v20
	v_cvt_pk_bf16_f32 v11, v27, v21
	v_mul_f32_e32 v18, v18, v18
	v_mul_f32_e32 v19, v19, v19
	v_mul_f32_e32 v20, v20, v20
	v_mul_f32_e32 v21, v21, v21
	v_fmac_f32_e32 v18, v24, v24
	v_fmac_f32_e32 v19, v25, v25
	v_fmac_f32_e32 v20, v26, v26
	v_fmac_f32_e32 v21, v27, v27
	v_add_f32_e32 v18, v18, v19
	v_add_f32_e32 v19, v20, v21
	v_add_f32_e32 v18, v18, v19
	global_store_dwordx4 v[22:23], v[8:11], off
	s_waitcnt vmcnt(7)
	v_lshlrev_b32_e32 v19, 16, v216
	v_and_b32_e32 v12, 0xffff0000, v216
	v_lshlrev_b32_e32 v20, 16, v217
	v_and_b32_e32 v13, 0xffff0000, v217
	v_lshlrev_b32_e32 v21, 16, v218
	v_and_b32_e32 v14, 0xffff0000, v218
	v_lshlrev_b32_e32 v24, 16, v219
	v_and_b32_e32 v15, 0xffff0000, v219
	v_add_f32_e32 v5, v5, v12
	v_add_f32_e32 v7, v7, v13
	v_add_f32_e32 v13, v1, v14
	v_add_f32_e32 v15, v3, v15
	v_add_f32_e32 v4, v4, v19
	v_add_f32_e32 v6, v6, v20
	v_add_f32_e32 v12, v0, v21
	v_add_f32_e32 v14, v2, v24
	v_mul_f32_e32 v0, v5, v5
	v_mul_f32_e32 v1, v7, v7
	v_mul_f32_e32 v2, v13, v13
	v_mul_f32_e32 v3, v15, v15
	v_fmac_f32_e32 v0, v4, v4
	v_fmac_f32_e32 v1, v6, v6
	v_fmac_f32_e32 v2, v12, v12
	v_fmac_f32_e32 v3, v14, v14
	v_add_f32_e32 v0, v0, v1
	v_add_f32_e32 v1, v2, v3
	v_add_f32_e32 v0, v0, v1
	v_add_f32_e32 v0, v18, v0
	ds_bpermute_b32 v1, v120, v0
	v_cvt_pk_bf16_f32 v2, v4, v5
	v_cvt_pk_bf16_f32 v3, v6, v7
	v_cvt_pk_bf16_f32 v4, v12, v13
	v_cvt_pk_bf16_f32 v5, v14, v15
	s_waitcnt lgkmcnt(0)
	v_add_f32_e32 v0, v0, v1
	ds_bpermute_b32 v1, v114, v0
	global_store_dwordx4 v[22:23], v[2:5], off offset:256
	s_and_saveexec_b64 s[38:39], s[4:5]
	s_cbranch_execz .LBB0_2020
	v_lshlrev_b64 v[2:3], 6, v[16:17]
	v_lshl_add_u64 v[2:3], s[18:19], 0, v[2:3]
	v_lshl_add_u64 v[2:3], s[36:37], 2, v[2:3]
	s_lshl_b32 s0, s50, 2
	v_lshl_add_u64 v[2:3], v[2:3], 0, s[0:1]
	s_waitcnt lgkmcnt(0)
	v_add_f32_e32 v0, v0, v1
	global_store_dword v[2:3], v0, off
